# P1 conv-epilogue weights via LDS; SSD prefetch as buffer loads moved after G; delayed vmcnt wait
# speedup vs baseline: 1.0200x; 1.0200x over previous
; #define LAS __attribute__((address_space(3)))
; __device__ __forceinline__ unsigned pk2e(float lo, float hi) { typedef __bf16 b2 __attribute__((ext_vector_type(2))); b2 v; v.x = (__bf16)lo; v.y = (__bf16)hi; return __builtin_bit_cast(unsigned, v); }
;     __device__ __forceinline__ void operator()(const f32x4 (&acc)[2][2][4][2], const Unit& u, int wr, int wc, int fr, int fq, LAS unsigned char* hb) const {
;     ...
;         if (fr >= 16 - H) {
; #pragma unroll
;             for (int ai = 0; ai < 2; ++ai)
; #pragma unroll
;                 for (int m = 0; m < 4; ++m) { const int q = 8 * ai + 4 * wr + m; asm volatile("" ::: "memory");
; #pragma unroll
;                     for (int bj = 0; bj < 2; ++bj) { const f32x4 v0 = acc[ai][bj][m][0], v1 = acc[ai][bj][m][1];
;                         u32x4 w; w.x = pk2e(v0[0], v0[1]); w.y = pk2e(v0[2], v0[3]); w.z = pk2e(v1[0], v1[1]); w.w = pk2e(v1[2], v1[3]);
;                         *(LAS u32x4*)(hb + ((q * H + fr - (16 - H)) * NCH + bj * HALF + chl) * 2) = w; } }
;         }
;         asm volatile("s_waitcnt lgkmcnt(0)" ::: "memory"); __builtin_amdgcn_s_barrier(); asm volatile("" ::: "memory");
;     ...
;                     const f32x4 w0 = *(const f32x4*)((const char*)cw + woff), w1 = *(const f32x4*)((const char*)cw + woff + XBCW * 4), w2 = *(const f32x4*)((const char*)cw + woff + 2 * XBCW * 4), w3 = *(const f32x4*)((const char*)cw + woff + 3 * XBCW * 4), bs = *(const f32x4*)((const char*)cb + woff);
.LBB0_180:
	s_and_b64 vcc, exec, s[4:5]
	s_cbranch_vccz .LBB0_179
	v_readfirstlane_b32 s72, v181
	v_and_b32_e32 v200, 63, v181
	v_lshlrev_b32_e32 v238, 2, v148
	s_lshr_b32 s72, s72, 6
	v_lshlrev_b32_e32 v201, 4, v200
	v_add_u32_e32 v238, 0x26000, v238
	s_cmp_gt_u32 s72, 4
	s_cbranch_scc1 .Lp1w_skipload
	v_readlane_b32 s74, v237, 22
	v_readlane_b32 s75, v237, 23
	v_readlane_b32 s76, v237, 24
	v_readlane_b32 s77, v237, 25
	s_mul_i32 s73, s72, 0x1800
	s_add_u32 s74, s74, s73
	s_addc_u32 s75, s75, 0
	s_cmp_eq_u32 s72, 4
	s_cselect_b32 s74, s76, s74
	s_cselect_b32 s75, s77, s75
	s_add_i32 s73, s2, -4
	s_lshl_b32 s73, s73, 10
	s_add_u32 s74, s74, s73
	s_addc_u32 s75, s75, 0
	s_nop 4
	global_load_dwordx4 v[196:199], v201, s[74:75]
.Lp1w_skipload:
	v_cmp_gt_i32_e32 vcc, 13, v149
	s_and_saveexec_b64 s[4:5], vcc
	s_xor_b64 s[4:5], exec, s[4:5]
	s_andn2_saveexec_b64 s[4:5], s[4:5]
	s_cbranch_execz .LBB0_183
	v_add_lshl_u32 v136, v149, s35, 9
	v_lshlrev_b32_e32 v146, 1, v148
	v_add_u32_e32 v147, s53, v136
	v_cvt_pk_bf16_f32 v162, v124, v125
	v_cvt_pk_bf16_f32 v163, v126, v127
	v_cvt_pk_bf16_f32 v164, v120, v121
	v_cvt_pk_bf16_f32 v165, v122, v123
	v_add3_u32 v147, v147, v146, s54
	ds_write_b128 v147, v[162:165]
	v_add_u32_e32 v147, s55, v136
	v_cvt_pk_bf16_f32 v162, v116, v117
	v_cvt_pk_bf16_f32 v163, v118, v119
	v_cvt_pk_bf16_f32 v164, v112, v113
	v_cvt_pk_bf16_f32 v165, v114, v115
	v_add3_u32 v147, v147, v146, s54
	ds_write_b128 v147, v[162:165]
	v_add_lshl_u32 v147, s36, v149, 9
	v_add_u32_e32 v150, s53, v147
	v_cvt_pk_bf16_f32 v162, v108, v109
	v_cvt_pk_bf16_f32 v163, v110, v111
	v_cvt_pk_bf16_f32 v164, v104, v105
	v_cvt_pk_bf16_f32 v165, v106, v107
	v_add3_u32 v150, v150, v146, s54
	v_add_u32_e32 v147, s55, v147
	ds_write_b128 v150, v[162:165]
	v_cvt_pk_bf16_f32 v162, v100, v101
	v_cvt_pk_bf16_f32 v163, v102, v103
	v_cvt_pk_bf16_f32 v164, v96, v97
	v_cvt_pk_bf16_f32 v165, v98, v99
	v_add3_u32 v147, v147, v146, s54
	ds_write_b128 v147, v[162:165]
	v_add_u32_e32 v147, 0xc00, v136
	v_add_u32_e32 v150, s53, v147
	v_cvt_pk_bf16_f32 v162, v92, v93
	v_cvt_pk_bf16_f32 v163, v94, v95
	v_cvt_pk_bf16_f32 v164, v88, v89
	v_cvt_pk_bf16_f32 v165, v90, v91
	v_add3_u32 v150, v150, v146, s54
	v_add_u32_e32 v147, s55, v147
	ds_write_b128 v150, v[162:165]
	v_cvt_pk_bf16_f32 v162, v84, v85
	v_cvt_pk_bf16_f32 v163, v86, v87
	v_cvt_pk_bf16_f32 v164, v80, v81
	v_cvt_pk_bf16_f32 v165, v82, v83
	v_add3_u32 v147, v147, v146, s54
	ds_write_b128 v147, v[162:165]
	v_add_u32_e32 v147, 0x1200, v136
	v_add_u32_e32 v150, s53, v147
	v_cvt_pk_bf16_f32 v162, v76, v77
	v_cvt_pk_bf16_f32 v163, v78, v79
	v_cvt_pk_bf16_f32 v164, v72, v73
	v_cvt_pk_bf16_f32 v165, v74, v75
	v_add3_u32 v150, v150, v146, s54
	v_add_u32_e32 v147, s55, v147
	ds_write_b128 v150, v[162:165]
	v_cvt_pk_bf16_f32 v162, v68, v69
	v_cvt_pk_bf16_f32 v163, v70, v71
	v_cvt_pk_bf16_f32 v164, v64, v65
	v_cvt_pk_bf16_f32 v165, v66, v67
	v_add3_u32 v147, v147, v146, s54
	ds_write_b128 v147, v[162:165]
	v_add_u32_e32 v147, 0x3000, v136
	v_add_u32_e32 v150, s53, v147
	v_cvt_pk_bf16_f32 v162, v60, v61
	v_cvt_pk_bf16_f32 v163, v62, v63
	v_cvt_pk_bf16_f32 v164, v56, v57
	v_cvt_pk_bf16_f32 v165, v58, v59
	v_add3_u32 v150, v150, v146, s54
	v_add_u32_e32 v147, s55, v147
	ds_write_b128 v150, v[162:165]
	v_cvt_pk_bf16_f32 v162, v52, v53
	v_cvt_pk_bf16_f32 v163, v54, v55
	v_cvt_pk_bf16_f32 v164, v48, v49
	v_cvt_pk_bf16_f32 v165, v50, v51
	v_add3_u32 v147, v147, v146, s54
	ds_write_b128 v147, v[162:165]
	v_add_u32_e32 v147, 0x3600, v136
	v_add_u32_e32 v150, s53, v147
	v_cvt_pk_bf16_f32 v162, v44, v45
	v_cvt_pk_bf16_f32 v163, v46, v47
	v_cvt_pk_bf16_f32 v164, v40, v41
	v_cvt_pk_bf16_f32 v165, v42, v43
	v_add3_u32 v150, v150, v146, s54
	v_add_u32_e32 v147, s55, v147
	ds_write_b128 v150, v[162:165]
	v_cvt_pk_bf16_f32 v162, v36, v37
	v_cvt_pk_bf16_f32 v163, v38, v39
	v_cvt_pk_bf16_f32 v164, v32, v33
	v_cvt_pk_bf16_f32 v165, v34, v35
	v_add3_u32 v147, v147, v146, s54
	ds_write_b128 v147, v[162:165]
	v_add_u32_e32 v147, 0x3c00, v136
	v_add_u32_e32 v150, s53, v147
	v_cvt_pk_bf16_f32 v162, v28, v29
	v_cvt_pk_bf16_f32 v163, v30, v31
	v_cvt_pk_bf16_f32 v164, v24, v25
	v_cvt_pk_bf16_f32 v165, v26, v27
	v_add3_u32 v150, v150, v146, s54
	v_add_u32_e32 v147, s55, v147
	ds_write_b128 v150, v[162:165]
	v_cvt_pk_bf16_f32 v162, v20, v21
	v_cvt_pk_bf16_f32 v163, v22, v23
	v_cvt_pk_bf16_f32 v164, v16, v17
	v_cvt_pk_bf16_f32 v165, v18, v19
	v_add3_u32 v147, v147, v146, s54
	ds_write_b128 v147, v[162:165]
	v_add_u32_e32 v136, 0x4200, v136
	v_add_u32_e32 v147, s53, v136
	v_cvt_pk_bf16_f32 v162, v12, v13
	v_cvt_pk_bf16_f32 v163, v14, v15
	v_cvt_pk_bf16_f32 v164, v8, v9
	v_cvt_pk_bf16_f32 v165, v10, v11
	v_add3_u32 v147, v147, v146, s54
	v_add_u32_e32 v136, s55, v136
	ds_write_b128 v147, v[162:165]
	v_cvt_pk_bf16_f32 v162, v4, v5
	v_cvt_pk_bf16_f32 v163, v6, v7
	v_cvt_pk_bf16_f32 v164, v0, v1
	v_cvt_pk_bf16_f32 v165, v2, v3
	v_add3_u32 v136, v136, v146, s54
	ds_write_b128 v136, v[162:165]
.LBB0_183:
	s_or_b64 exec, exec, s[4:5]
	s_cmp_gt_u32 s72, 4
	s_cbranch_scc1 .Lp1w_skipstore
	v_lshl_add_u32 v200, s72, 10, v201
	v_add_u32_e32 v200, 0x26000, v200
	s_waitcnt vmcnt(0)
	ds_write_b128 v200, v[196:199]
; #define LAS __attribute__((address_space(3)))
;     __device__ __forceinline__ void operator()(const f32x4 (&acc)[2][2][4][2], const Unit& u, int wr, int wc, int fr, int fq, LAS unsigned char* hb) const {
;     ...
;         asm volatile("s_waitcnt lgkmcnt(0)" ::: "memory"); __builtin_amdgcn_s_barrier(); asm volatile("" ::: "memory");
;         const int hr1 = H - 1, hr2 = (H - 2 + fr) < (H - 1) ? (H - 2 + fr) : (H - 1), hr3 = (H - 3 + fr) < (H - 1) ? (H - 3 + fr) : (H - 1);
;         const int ch0 = (u.pn - 4) * BM + chl;
; #pragma unroll
;         for (int ai = 0; ai < 2; ++ai)
; #pragma unroll
;             for (int m = 0; m < 4; ++m) { asm volatile("" ::: "memory"); __builtin_amdgcn_sched_barrier(0);
;                 const int q = 8 * ai + 4 * wr + m, prev = q > 0 ? q - 1 : 0; const int lr = ai * HALF + wr * 64 + m * 16 + fr, R = R0 + lr;
;                 const int Rc = R < 0 ? 0 : R; const int b = Rc / LL, p = Rc - b * LL;
;                 const bool ok = (lr >= H && R < TT);
;                 const unsigned ooff = ((unsigned)Rc * (unsigned)LDP + (unsigned)(OFF_XBC + ch0)) * 2u;
; #pragma unroll
;                 for (int bn = 0; bn < 4; ++bn) { const int bj = bn >> 1, n = bn & 1; const int co = bj * HALF + 4 * n;
;                     const unsigned woff = (unsigned)(ch0 + co) * 4u;
;                     const f32x4 w0 = *(const f32x4*)((const char*)cw + woff), w1 = *(const f32x4*)((const char*)cw + woff + XBCW * 4), w2 = *(const f32x4*)((const char*)cw + woff + 2 * XBCW * 4), w3 = *(const f32x4*)((const char*)cw + woff + 3 * XBCW * 4), bs = *(const f32x4*)((const char*)cb + woff);
;                     const LAS unsigned char* hp = hb + (prev * H * NCH + chl + co) * 2;
;                     const u32x2 q1 = *(const LAS u32x2*)(hp + hr1 * NCH * 2), q2 = *(const LAS u32x2*)(hp + hr2 * NCH * 2), q3 = *(const LAS u32x2*)(hp + hr3 * NCH * 2);
;                     const float h1[4] = {__builtin_bit_cast(float, q1.x << 16), __builtin_bit_cast(float, q1.x & 0xffff0000u), __builtin_bit_cast(float, q1.y << 16), __builtin_bit_cast(float, q1.y & 0xffff0000u)};
;                     const float h2[4] = {__builtin_bit_cast(float, q2.x << 16), __builtin_bit_cast(float, q2.x & 0xffff0000u), __builtin_bit_cast(float, q2.y << 16), __builtin_bit_cast(float, q2.y & 0xffff0000u)};
.Lp1w_skipstore:
	s_waitcnt lgkmcnt(0)
	s_barrier
	v_min_i32_e32 v136, 1, v149
	v_min_i32_e32 v146, 2, v149
	s_lshl_b32 s2, s2, 8
	s_add_i32 s22, s2, 0x3ffffc00
	v_add_u32_e32 v164, s2, v148
	v_add_u32_e32 v165, 0xfffffd00, v148
	v_lshlrev_b32_e32 v163, 9, v136
	v_lshlrev_b32_e32 v162, 9, v146
	v_add_u32_e32 v136, s17, v161
	v_max_i32_e32 v146, 0, v136
	v_mul_hi_u32 v147, v146, s56
	v_lshrrev_b32_e32 v147, 11, v147
	v_mul_u32_u24_e32 v147, 0x1010, v147
	v_sub_u32_e32 v147, v146, v147
	v_cmp_gt_i32_e64 s[4:5], s50, v136
	v_mul_lo_u32 v136, v146, s51
	v_add_u32_e32 v146, s37, v165
	v_lshl_add_u32 v166, v146, 1, s53
	v_cmp_lt_i32_e32 vcc, 2, v161
	v_add_u32_e32 v167, v166, v163
	s_and_b64 s[2:3], vcc, s[4:5]
	v_add_lshl_u32 v150, v136, v164, 1
	v_cmp_eq_u32_e64 s[8:9], 0, v147
	v_cmp_lt_u32_e64 s[6:7], 1, v147
	v_cmp_lt_u32_e64 s[4:5], 2, v147
	v_add_lshl_u32 v136, s22, v148, 2
	ds_read_b64 v[146:147], v166 offset:1024
	v_add_u32_e32 v168, v166, v162
	ds_read_b64 v[148:149], v167 offset:512
	ds_read_b64 v[184:185], v168
	v_readlane_b32 s22, v237, 58
	v_mov_b32_e32 v151, v137
	s_waitcnt lgkmcnt(0)
	v_lshlrev_b32_e32 v179, 16, v146
	v_and_b32_e32 v182, 0xffff0000, v146
	v_lshlrev_b32_e32 v173, 16, v147
	v_and_b32_e32 v174, 0xffff0000, v147
	v_lshlrev_b32_e32 v177, 16, v148
	v_and_b32_e32 v178, 0xffff0000, v148
	v_lshlrev_b32_e32 v171, 16, v149
	v_and_b32_e32 v172, 0xffff0000, v149
	v_lshlrev_b32_e32 v175, 16, v184
	v_and_b32_e32 v176, 0xffff0000, v184
	v_lshlrev_b32_e32 v169, 16, v185
	v_and_b32_e32 v170, 0xffff0000, v185
	v_readlane_b32 s23, v237, 59
	v_mov_b32_dpp v179, v124 row_shr:1 row_mask:0xf bank_mask:0xf
	v_mov_b32_dpp v177, v124 row_shr:2 row_mask:0xf bank_mask:0xf
	v_mov_b32_dpp v175, v124 row_shr:3 row_mask:0xf bank_mask:0xf
	v_mov_b32_dpp v182, v125 row_shr:1 row_mask:0xf bank_mask:0xf
	v_mov_b32_dpp v178, v125 row_shr:2 row_mask:0xf bank_mask:0xf
	v_mov_b32_dpp v176, v125 row_shr:3 row_mask:0xf bank_mask:0xf
	v_mov_b32_dpp v173, v126 row_shr:1 row_mask:0xf bank_mask:0xf
	v_mov_b32_dpp v171, v126 row_shr:2 row_mask:0xf bank_mask:0xf
	v_mov_b32_dpp v169, v126 row_shr:3 row_mask:0xf bank_mask:0xf
	v_mov_b32_dpp v174, v127 row_shr:1 row_mask:0xf bank_mask:0xf
	v_mov_b32_dpp v172, v127 row_shr:2 row_mask:0xf bank_mask:0xf
	v_mov_b32_dpp v170, v127 row_shr:3 row_mask:0xf bank_mask:0xf
	v_lshl_add_u64 v[150:151], s[22:23], 0, v[150:151]
	s_and_saveexec_b64 s[22:23], s[2:3]
	s_cbranch_execz .LBB0_185
	ds_read_b128 v[184:187], v238 offset:4096
	ds_read_b128 v[188:191], v238 offset:3072
	ds_read_b128 v[192:195], v238 offset:2048
	v_cndmask_b32_e64 v183, v182, 0, s[8:9]
	ds_read_b128 v[196:199], v238 offset:1024
	s_nop 0
	ds_read_b128 v[200:203], v238
	v_cndmask_b32_e64 v182, v179, 0, s[8:9]
	v_cndmask_b32_e64 v179, 0, v178, s[6:7]
	v_cndmask_b32_e64 v178, 0, v177, s[6:7]
	v_cndmask_b32_e64 v177, 0, v176, s[4:5]
	v_cndmask_b32_e64 v176, 0, v175, s[4:5]
	s_waitcnt lgkmcnt(0)
	v_pk_fma_f32 v[124:125], v[124:125], v[188:189], v[184:185]
	v_pk_fma_f32 v[126:127], v[126:127], v[190:191], v[186:187]
	v_pk_fma_f32 v[124:125], v[182:183], v[192:193], v[124:125]
	s_nop 0
	v_pk_fma_f32 v[124:125], v[178:179], v[196:197], v[124:125]
	s_nop 0
	v_pk_fma_f32 v[124:125], v[176:177], v[200:201], v[124:125]
	s_nop 0
	v_mul_f32_e32 v175, 0xbfb8aa3b, v125
	v_exp_f32_e32 v175, v175
	s_nop 0
	v_add_f32_e32 v175, 1.0, v175
	v_rcp_f32_e32 v177, v175
	v_mul_f32_e32 v175, 0xbfb8aa3b, v124
	v_exp_f32_e32 v175, v175
	s_nop 0
	v_add_f32_e32 v175, 1.0, v175
	v_rcp_f32_e32 v176, v175
	v_cndmask_b32_e64 v175, v174, 0, s[8:9]
	v_cndmask_b32_e64 v174, v173, 0, s[8:9]
	v_pk_fma_f32 v[126:127], v[174:175], v[194:195], v[126:127]
	v_cndmask_b32_e64 v173, 0, v172, s[6:7]
	v_cndmask_b32_e64 v172, 0, v171, s[6:7]
	v_pk_fma_f32 v[126:127], v[172:173], v[198:199], v[126:127]
	v_cndmask_b32_e64 v171, 0, v170, s[4:5]
	v_cndmask_b32_e64 v170, 0, v169, s[4:5]
	v_pk_mul_f32 v[124:125], v[124:125], v[176:177]
	v_pk_fma_f32 v[126:127], v[170:171], v[202:203], v[126:127]
	v_cvt_pk_bf16_f32 v124, v124, v125
	v_mul_f32_e32 v125, 0xbfb8aa3b, v127
	v_exp_f32_e32 v125, v125
	s_nop 0
	v_add_f32_e32 v125, 1.0, v125
	v_rcp_f32_e32 v171, v125
	v_mul_f32_e32 v125, 0xbfb8aa3b, v126
	v_exp_f32_e32 v125, v125
	s_nop 0
	v_add_f32_e32 v125, 1.0, v125
	v_rcp_f32_e32 v170, v125
	s_nop 0
	v_pk_mul_f32 v[126:127], v[126:127], v[170:171]
	s_nop 0
	v_cvt_pk_bf16_f32 v125, v126, v127
	global_store_dwordx2 v[150:151], v[124:125], off
;     __device__ __forceinline__ void operator()(const f32x4 (&acc)[2][2][4][2], const Unit& u, int wr, int wc, int fr, int fq, LAS unsigned char* hb) const {
;     ...
;             for (int m = 0; m < 4; ++m) { asm volatile("" ::: "memory"); __builtin_amdgcn_sched_barrier(0);
;                 const int q = 8 * ai + 4 * wr + m, prev = q > 0 ? q - 1 : 0; const int lr = ai * HALF + wr * 64 + m * 16 + fr, R = R0 + lr;
;                 const int Rc = R < 0 ? 0 : R; const int b = Rc / LL, p = Rc - b * LL;
;                 const bool ok = (lr >= H && R < TT);
;                 const unsigned ooff = ((unsigned)Rc * (unsigned)LDP + (unsigned)(OFF_XBC + ch0)) * 2u;
; #pragma unroll
;                 for (int bn = 0; bn < 4; ++bn) { const int bj = bn >> 1, n = bn & 1; const int co = bj * HALF + 4 * n;
;                     const unsigned woff = (unsigned)(ch0 + co) * 4u;
;                     const f32x4 w0 = *(const f32x4*)((const char*)cw + woff), w1 = *(const f32x4*)((const char*)cw + woff + XBCW * 4), w2 = *(const f32x4*)((const char*)cw + woff + 2 * XBCW * 4), w3 = *(const f32x4*)((const char*)cw + woff + 3 * XBCW * 4), bs = *(const f32x4*)((const char*)cb + woff);
;                     const LAS unsigned char* hp = hb + (prev * H * NCH + chl + co) * 2;
;                     const u32x2 q1 = *(const LAS u32x2*)(hp + hr1 * NCH * 2), q2 = *(const LAS u32x2*)(hp + hr2 * NCH * 2), q3 = *(const LAS u32x2*)(hp + hr3 * NCH * 2);
;                     const float h1[4] = {__builtin_bit_cast(float, q1.x << 16), __builtin_bit_cast(float, q1.x & 0xffff0000u), __builtin_bit_cast(float, q1.y << 16), __builtin_bit_cast(float, q1.y & 0xffff0000u)};
;                     const float h2[4] = {__builtin_bit_cast(float, q2.x << 16), __builtin_bit_cast(float, q2.x & 0xffff0000u), __builtin_bit_cast(float, q2.y << 16), __builtin_bit_cast(float, q2.y & 0xffff0000u)};
;                     const float h3[4] = {__builtin_bit_cast(float, q3.x << 16), __builtin_bit_cast(float, q3.x & 0xffff0000u), __builtin_bit_cast(float, q3.y << 16), __builtin_bit_cast(float, q3.y & 0xffff0000u)};
;                     const f32x4 gv = acc[ai][bj][m][n];
;                     float o[4];
; #pragma unroll
;                     for (int j = 0; j < 4; ++j) { const float g = gv[j];
;                         float g1 = dpp_row_shr<1>(h1[j], g), g2 = dpp_row_shr<2>(h2[j], g), g3 = dpp_row_shr<3>(h3[j], g);
.LBB0_185:
	s_or_b64 exec, exec, s[22:23]
	ds_read_b64 v[124:125], v166 offset:1032
	ds_read_b64 v[126:127], v167 offset:520
	ds_read_b64 v[186:187], v168 offset:8
	v_add_u32_e32 v184, 16, v136
	v_mov_b32_e32 v185, v137
	s_waitcnt lgkmcnt(0)
	v_lshlrev_b32_e32 v179, 16, v124
	v_and_b32_e32 v182, 0xffff0000, v124
	v_lshlrev_b32_e32 v173, 16, v125
	v_and_b32_e32 v174, 0xffff0000, v125
	v_lshlrev_b32_e32 v177, 16, v126
	v_and_b32_e32 v178, 0xffff0000, v126
	v_lshlrev_b32_e32 v171, 16, v127
	v_and_b32_e32 v172, 0xffff0000, v127
	v_lshlrev_b32_e32 v175, 16, v186
	v_and_b32_e32 v176, 0xffff0000, v186
	v_lshlrev_b32_e32 v169, 16, v187
	v_and_b32_e32 v170, 0xffff0000, v187
	v_mov_b32_dpp v179, v120 row_shr:1 row_mask:0xf bank_mask:0xf
	v_mov_b32_dpp v177, v120 row_shr:2 row_mask:0xf bank_mask:0xf
	v_mov_b32_dpp v175, v120 row_shr:3 row_mask:0xf bank_mask:0xf
	v_mov_b32_dpp v182, v121 row_shr:1 row_mask:0xf bank_mask:0xf
	v_mov_b32_dpp v178, v121 row_shr:2 row_mask:0xf bank_mask:0xf
	v_mov_b32_dpp v176, v121 row_shr:3 row_mask:0xf bank_mask:0xf
	v_mov_b32_dpp v173, v122 row_shr:1 row_mask:0xf bank_mask:0xf
	v_mov_b32_dpp v171, v122 row_shr:2 row_mask:0xf bank_mask:0xf
	v_mov_b32_dpp v169, v122 row_shr:3 row_mask:0xf bank_mask:0xf
	v_mov_b32_dpp v174, v123 row_shr:1 row_mask:0xf bank_mask:0xf
	v_mov_b32_dpp v172, v123 row_shr:2 row_mask:0xf bank_mask:0xf
	v_mov_b32_dpp v170, v123 row_shr:3 row_mask:0xf bank_mask:0xf
	s_and_saveexec_b64 s[22:23], s[2:3]
	s_cbranch_execz .LBB0_187
	ds_read_b128 v[184:187], v238 offset:4112
	ds_read_b128 v[188:191], v238 offset:3088
	ds_read_b128 v[192:195], v238 offset:2064
	v_cndmask_b32_e64 v183, v182, 0, s[8:9]
	ds_read_b128 v[196:199], v238 offset:1040
	s_nop 0
	ds_read_b128 v[200:203], v238 offset:16
	v_cndmask_b32_e64 v182, v179, 0, s[8:9]
	v_cndmask_b32_e64 v179, 0, v178, s[6:7]
	v_cndmask_b32_e64 v178, 0, v177, s[6:7]
	v_cndmask_b32_e64 v177, 0, v176, s[4:5]
	v_cndmask_b32_e64 v176, 0, v175, s[4:5]
	s_waitcnt lgkmcnt(0)
	v_pk_fma_f32 v[120:121], v[120:121], v[188:189], v[184:185]
	v_pk_fma_f32 v[122:123], v[122:123], v[190:191], v[186:187]
	v_pk_fma_f32 v[120:121], v[182:183], v[192:193], v[120:121]
	s_nop 0
	v_pk_fma_f32 v[120:121], v[178:179], v[196:197], v[120:121]
	s_nop 0
	v_pk_fma_f32 v[120:121], v[176:177], v[200:201], v[120:121]
	s_nop 0
	v_mul_f32_e32 v175, 0xbfb8aa3b, v121
	v_exp_f32_e32 v175, v175
	s_nop 0
	v_add_f32_e32 v175, 1.0, v175
	v_rcp_f32_e32 v177, v175
	v_mul_f32_e32 v175, 0xbfb8aa3b, v120
	v_exp_f32_e32 v175, v175
	s_nop 0
	v_add_f32_e32 v175, 1.0, v175
	v_rcp_f32_e32 v176, v175
	v_cndmask_b32_e64 v175, v174, 0, s[8:9]
	v_cndmask_b32_e64 v174, v173, 0, s[8:9]
	v_pk_fma_f32 v[122:123], v[174:175], v[194:195], v[122:123]
	v_cndmask_b32_e64 v173, 0, v172, s[6:7]
	v_cndmask_b32_e64 v172, 0, v171, s[6:7]
	v_pk_fma_f32 v[122:123], v[172:173], v[198:199], v[122:123]
	v_cndmask_b32_e64 v171, 0, v170, s[4:5]
	v_cndmask_b32_e64 v170, 0, v169, s[4:5]
	v_pk_mul_f32 v[120:121], v[120:121], v[176:177]
	v_pk_fma_f32 v[122:123], v[170:171], v[202:203], v[122:123]
	v_cvt_pk_bf16_f32 v120, v120, v121
	v_mul_f32_e32 v121, 0xbfb8aa3b, v123
	v_exp_f32_e32 v121, v121
	s_nop 0
	v_add_f32_e32 v121, 1.0, v121
	v_rcp_f32_e32 v171, v121
	v_mul_f32_e32 v121, 0xbfb8aa3b, v122
	v_exp_f32_e32 v121, v121
	s_nop 0
	v_add_f32_e32 v121, 1.0, v121
	v_rcp_f32_e32 v170, v121
	s_nop 0
	v_pk_mul_f32 v[122:123], v[122:123], v[170:171]
	s_nop 0
	v_cvt_pk_bf16_f32 v121, v122, v123
	global_store_dwordx2 v[150:151], v[120:121], off offset:8
.LBB0_187:
	s_or_b64 exec, exec, s[22:23]
	ds_read_b64 v[120:121], v166 offset:1280
	ds_read_b64 v[122:123], v167 offset:768
	ds_read_b64 v[186:187], v168 offset:256
	v_add_u32_e32 v184, 0x200, v136
	v_mov_b32_e32 v185, v137
	s_waitcnt lgkmcnt(0)
	v_lshlrev_b32_e32 v179, 16, v120
	v_and_b32_e32 v182, 0xffff0000, v120
	v_lshlrev_b32_e32 v173, 16, v121
	v_and_b32_e32 v174, 0xffff0000, v121
	v_lshlrev_b32_e32 v177, 16, v122
	v_and_b32_e32 v178, 0xffff0000, v122
	v_lshlrev_b32_e32 v171, 16, v123
	v_and_b32_e32 v172, 0xffff0000, v123
	v_lshlrev_b32_e32 v175, 16, v186
	v_and_b32_e32 v176, 0xffff0000, v186
	v_lshlrev_b32_e32 v169, 16, v187
	v_and_b32_e32 v170, 0xffff0000, v187
	v_mov_b32_dpp v179, v116 row_shr:1 row_mask:0xf bank_mask:0xf
	v_mov_b32_dpp v177, v116 row_shr:2 row_mask:0xf bank_mask:0xf
	v_mov_b32_dpp v175, v116 row_shr:3 row_mask:0xf bank_mask:0xf
	v_mov_b32_dpp v182, v117 row_shr:1 row_mask:0xf bank_mask:0xf
	v_mov_b32_dpp v178, v117 row_shr:2 row_mask:0xf bank_mask:0xf
	v_mov_b32_dpp v176, v117 row_shr:3 row_mask:0xf bank_mask:0xf
	v_mov_b32_dpp v173, v118 row_shr:1 row_mask:0xf bank_mask:0xf
	v_mov_b32_dpp v171, v118 row_shr:2 row_mask:0xf bank_mask:0xf
	v_mov_b32_dpp v169, v118 row_shr:3 row_mask:0xf bank_mask:0xf
	v_mov_b32_dpp v174, v119 row_shr:1 row_mask:0xf bank_mask:0xf
	v_mov_b32_dpp v172, v119 row_shr:2 row_mask:0xf bank_mask:0xf
	v_mov_b32_dpp v170, v119 row_shr:3 row_mask:0xf bank_mask:0xf
	s_and_saveexec_b64 s[22:23], s[2:3]
	s_cbranch_execz .LBB0_189
	ds_read_b128 v[184:187], v238 offset:4608
	ds_read_b128 v[188:191], v238 offset:3584
	ds_read_b128 v[192:195], v238 offset:2560
	v_cndmask_b32_e64 v183, v182, 0, s[8:9]
	ds_read_b128 v[196:199], v238 offset:1536
	s_nop 0
	ds_read_b128 v[200:203], v238 offset:512
	v_cndmask_b32_e64 v182, v179, 0, s[8:9]
	v_cndmask_b32_e64 v179, 0, v178, s[6:7]
	v_cndmask_b32_e64 v178, 0, v177, s[6:7]
	v_cndmask_b32_e64 v177, 0, v176, s[4:5]
	v_cndmask_b32_e64 v176, 0, v175, s[4:5]
	s_waitcnt lgkmcnt(0)
	v_pk_fma_f32 v[116:117], v[116:117], v[188:189], v[184:185]
	v_pk_fma_f32 v[118:119], v[118:119], v[190:191], v[186:187]
	v_pk_fma_f32 v[116:117], v[182:183], v[192:193], v[116:117]
	s_nop 0
	v_pk_fma_f32 v[116:117], v[178:179], v[196:197], v[116:117]
	s_nop 0
	v_pk_fma_f32 v[116:117], v[176:177], v[200:201], v[116:117]
	s_nop 0
	v_mul_f32_e32 v175, 0xbfb8aa3b, v117
	v_exp_f32_e32 v175, v175
	s_nop 0
	v_add_f32_e32 v175, 1.0, v175
	v_rcp_f32_e32 v177, v175
	v_mul_f32_e32 v175, 0xbfb8aa3b, v116
	v_exp_f32_e32 v175, v175
	s_nop 0
	v_add_f32_e32 v175, 1.0, v175
	v_rcp_f32_e32 v176, v175
	v_cndmask_b32_e64 v175, v174, 0, s[8:9]
	v_cndmask_b32_e64 v174, v173, 0, s[8:9]
	v_pk_fma_f32 v[118:119], v[174:175], v[194:195], v[118:119]
	v_cndmask_b32_e64 v173, 0, v172, s[6:7]
	v_cndmask_b32_e64 v172, 0, v171, s[6:7]
	v_pk_fma_f32 v[118:119], v[172:173], v[198:199], v[118:119]
	v_cndmask_b32_e64 v171, 0, v170, s[4:5]
	v_cndmask_b32_e64 v170, 0, v169, s[4:5]
	v_pk_mul_f32 v[116:117], v[116:117], v[176:177]
	v_pk_fma_f32 v[118:119], v[170:171], v[202:203], v[118:119]
	v_cvt_pk_bf16_f32 v116, v116, v117
	v_mul_f32_e32 v117, 0xbfb8aa3b, v119
	v_exp_f32_e32 v117, v117
	s_nop 0
	v_add_f32_e32 v117, 1.0, v117
	v_rcp_f32_e32 v171, v117
	v_mul_f32_e32 v117, 0xbfb8aa3b, v118
	v_exp_f32_e32 v117, v117
	s_nop 0
	v_add_f32_e32 v117, 1.0, v117
	v_rcp_f32_e32 v170, v117
	s_nop 0
	v_pk_mul_f32 v[118:119], v[118:119], v[170:171]
	s_nop 0
	v_cvt_pk_bf16_f32 v117, v118, v119
	global_store_dwordx2 v[150:151], v[116:117], off offset:256
;     __device__ __forceinline__ void operator()(const f32x4 (&acc)[2][2][4][2], const Unit& u, int wr, int wc, int fr, int fq, LAS unsigned char* hb) const {
;     ...
;             for (int m = 0; m < 4; ++m) { asm volatile("" ::: "memory"); __builtin_amdgcn_sched_barrier(0);
;                 const int q = 8 * ai + 4 * wr + m, prev = q > 0 ? q - 1 : 0; const int lr = ai * HALF + wr * 64 + m * 16 + fr, R = R0 + lr;
;                 const int Rc = R < 0 ? 0 : R; const int b = Rc / LL, p = Rc - b * LL;
;                 const bool ok = (lr >= H && R < TT);
;                 const unsigned ooff = ((unsigned)Rc * (unsigned)LDP + (unsigned)(OFF_XBC + ch0)) * 2u;
; #pragma unroll
;                 for (int bn = 0; bn < 4; ++bn) { const int bj = bn >> 1, n = bn & 1; const int co = bj * HALF + 4 * n;
;                     const unsigned woff = (unsigned)(ch0 + co) * 4u;
;                     const f32x4 w0 = *(const f32x4*)((const char*)cw + woff), w1 = *(const f32x4*)((const char*)cw + woff + XBCW * 4), w2 = *(const f32x4*)((const char*)cw + woff + 2 * XBCW * 4), w3 = *(const f32x4*)((const char*)cw + woff + 3 * XBCW * 4), bs = *(const f32x4*)((const char*)cb + woff);
;                     const LAS unsigned char* hp = hb + (prev * H * NCH + chl + co) * 2;
;                     const u32x2 q1 = *(const LAS u32x2*)(hp + hr1 * NCH * 2), q2 = *(const LAS u32x2*)(hp + hr2 * NCH * 2), q3 = *(const LAS u32x2*)(hp + hr3 * NCH * 2);
;                     const float h1[4] = {__builtin_bit_cast(float, q1.x << 16), __builtin_bit_cast(float, q1.x & 0xffff0000u), __builtin_bit_cast(float, q1.y << 16), __builtin_bit_cast(float, q1.y & 0xffff0000u)};
;                     const float h2[4] = {__builtin_bit_cast(float, q2.x << 16), __builtin_bit_cast(float, q2.x & 0xffff0000u), __builtin_bit_cast(float, q2.y << 16), __builtin_bit_cast(float, q2.y & 0xffff0000u)};
;                     const float h3[4] = {__builtin_bit_cast(float, q3.x << 16), __builtin_bit_cast(float, q3.x & 0xffff0000u), __builtin_bit_cast(float, q3.y << 16), __builtin_bit_cast(float, q3.y & 0xffff0000u)};
;                     const f32x4 gv = acc[ai][bj][m][n];
;                     float o[4];
; #pragma unroll
;                     for (int j = 0; j < 4; ++j) { const float g = gv[j];
;                         float g1 = dpp_row_shr<1>(h1[j], g), g2 = dpp_row_shr<2>(h2[j], g), g3 = dpp_row_shr<3>(h3[j], g);
.LBB0_189:
	s_or_b64 exec, exec, s[22:23]
	ds_read_b64 v[116:117], v166 offset:1288
	ds_read_b64 v[118:119], v167 offset:776
	ds_read_b64 v[166:167], v168 offset:264
	v_add_u32_e32 v136, 0x210, v136
	s_waitcnt lgkmcnt(0)
	v_lshlrev_b32_e32 v176, 16, v116
	v_and_b32_e32 v177, 0xffff0000, v116
	v_lshlrev_b32_e32 v170, 16, v117
	v_and_b32_e32 v171, 0xffff0000, v117
	v_lshlrev_b32_e32 v174, 16, v118
	v_and_b32_e32 v175, 0xffff0000, v118
	v_lshlrev_b32_e32 v168, 16, v119
	v_and_b32_e32 v169, 0xffff0000, v119
	v_lshlrev_b32_e32 v172, 16, v166
	v_and_b32_e32 v173, 0xffff0000, v166
	v_lshlrev_b32_e32 v166, 16, v167
	v_and_b32_e32 v167, 0xffff0000, v167
	v_mov_b32_dpp v176, v112 row_shr:1 row_mask:0xf bank_mask:0xf
	v_mov_b32_dpp v174, v112 row_shr:2 row_mask:0xf bank_mask:0xf
	v_mov_b32_dpp v172, v112 row_shr:3 row_mask:0xf bank_mask:0xf
	v_mov_b32_dpp v177, v113 row_shr:1 row_mask:0xf bank_mask:0xf
	v_mov_b32_dpp v175, v113 row_shr:2 row_mask:0xf bank_mask:0xf
	v_mov_b32_dpp v173, v113 row_shr:3 row_mask:0xf bank_mask:0xf
	v_mov_b32_dpp v170, v114 row_shr:1 row_mask:0xf bank_mask:0xf
	v_mov_b32_dpp v168, v114 row_shr:2 row_mask:0xf bank_mask:0xf
	v_mov_b32_dpp v166, v114 row_shr:3 row_mask:0xf bank_mask:0xf
	v_mov_b32_dpp v171, v115 row_shr:1 row_mask:0xf bank_mask:0xf
	v_mov_b32_dpp v169, v115 row_shr:2 row_mask:0xf bank_mask:0xf
	v_mov_b32_dpp v167, v115 row_shr:3 row_mask:0xf bank_mask:0xf
	s_and_saveexec_b64 s[22:23], s[2:3]
	s_cbranch_execz .LBB0_191
	ds_read_b128 v[182:185], v238 offset:4624
	ds_read_b128 v[186:189], v238 offset:3600
	v_cndmask_b32_e64 v177, v177, 0, s[8:9]
	ds_read_b128 v[190:193], v238 offset:2576
	v_cndmask_b32_e64 v176, v176, 0, s[8:9]
	ds_read_b128 v[194:197], v238 offset:1552
	ds_read_b128 v[198:201], v238 offset:528
	v_cndmask_b32_e64 v175, 0, v175, s[6:7]
	v_cndmask_b32_e64 v174, 0, v174, s[6:7]
	v_cndmask_b32_e64 v173, 0, v173, s[4:5]
	v_cndmask_b32_e64 v172, 0, v172, s[4:5]
	v_cndmask_b32_e64 v171, v171, 0, s[8:9]
	v_cndmask_b32_e64 v170, v170, 0, s[8:9]
	v_cndmask_b32_e64 v169, 0, v169, s[6:7]
	v_cndmask_b32_e64 v168, 0, v168, s[6:7]
	v_cndmask_b32_e64 v167, 0, v167, s[4:5]
	v_cndmask_b32_e64 v166, 0, v166, s[4:5]
	s_waitcnt lgkmcnt(0)
	v_pk_fma_f32 v[112:113], v[112:113], v[186:187], v[182:183]
	v_pk_fma_f32 v[114:115], v[114:115], v[188:189], v[184:185]
	v_pk_fma_f32 v[112:113], v[176:177], v[190:191], v[112:113]
	v_pk_fma_f32 v[114:115], v[170:171], v[192:193], v[114:115]
	v_pk_fma_f32 v[112:113], v[174:175], v[194:195], v[112:113]
	s_nop 0
	v_pk_fma_f32 v[112:113], v[172:173], v[198:199], v[112:113]
	v_pk_fma_f32 v[114:115], v[168:169], v[196:197], v[114:115]
	v_mul_f32_e32 v136, 0xbfb8aa3b, v113
	v_exp_f32_e32 v136, v136
	v_pk_fma_f32 v[114:115], v[166:167], v[200:201], v[114:115]
	v_add_f32_e32 v136, 1.0, v136
	v_rcp_f32_e32 v173, v136
	v_mul_f32_e32 v136, 0xbfb8aa3b, v112
	v_exp_f32_e32 v136, v136
	s_nop 0
	v_add_f32_e32 v136, 1.0, v136
	v_rcp_f32_e32 v172, v136
	s_nop 0
	v_pk_mul_f32 v[112:113], v[112:113], v[172:173]
	s_nop 0
	v_cvt_pk_bf16_f32 v112, v112, v113
	v_mul_f32_e32 v113, 0xbfb8aa3b, v115
	v_exp_f32_e32 v113, v113
	s_nop 0
	v_add_f32_e32 v113, 1.0, v113
	v_rcp_f32_e32 v167, v113
	v_mul_f32_e32 v113, 0xbfb8aa3b, v114
	v_exp_f32_e32 v113, v113
	s_nop 0
	v_add_f32_e32 v113, 1.0, v113
	v_rcp_f32_e32 v166, v113
	s_nop 0
	v_pk_mul_f32 v[114:115], v[114:115], v[166:167]
	s_nop 0
	v_cvt_pk_bf16_f32 v113, v114, v115
	global_store_dwordx2 v[150:151], v[112:113], off offset:264
.LBB0_191:
	s_or_b64 exec, exec, s[22:23]
	v_add_u32_e32 v112, 16, v161
	v_add_u32_e32 v113, s17, v112
	v_max_i32_e32 v114, 0, v113
	v_mul_hi_u32 v115, v114, s56
	v_lshrrev_b32_e32 v115, 11, v115
	v_cmp_lt_i32_e32 vcc, 2, v112
	v_mul_lo_u32 v112, v114, s51
	v_mul_u32_u24_e32 v115, 0x1010, v115
	v_add_lshl_u32 v136, v112, v164, 1
	v_add_u32_e32 v112, s38, v165
	v_sub_u32_e32 v115, v114, v115
	v_cmp_gt_i32_e64 s[4:5], s50, v113
	v_lshl_add_u32 v114, v112, 1, s53
	s_and_b64 s[2:3], vcc, s[4:5]
	v_cmp_eq_u32_e64 s[8:9], 0, v115
	v_cmp_lt_u32_e64 s[6:7], 1, v115
	v_cmp_lt_u32_e64 s[4:5], 2, v115
	v_add_u32_e32 v115, v114, v163
	ds_read_b64 v[112:113], v114 offset:1024
	v_add_u32_e32 v150, v114, v162
	ds_read_b64 v[178:179], v115 offset:512
	ds_read_b64 v[182:183], v150
	v_readlane_b32 s22, v237, 58
	v_readlane_b32 s23, v237, 59
	s_waitcnt lgkmcnt(0)
	v_lshlrev_b32_e32 v175, 16, v112
	v_and_b32_e32 v176, 0xffff0000, v112
	v_lshlrev_b32_e32 v169, 16, v113
	v_and_b32_e32 v170, 0xffff0000, v113
	v_lshlrev_b32_e32 v173, 16, v178
	v_and_b32_e32 v174, 0xffff0000, v178
	v_lshlrev_b32_e32 v167, 16, v179
	v_and_b32_e32 v168, 0xffff0000, v179
	v_lshlrev_b32_e32 v171, 16, v182
	v_and_b32_e32 v172, 0xffff0000, v182
	v_lshlrev_b32_e32 v151, 16, v183
	v_and_b32_e32 v166, 0xffff0000, v183
	v_mov_b32_dpp v175, v108 row_shr:1 row_mask:0xf bank_mask:0xf
	v_mov_b32_dpp v173, v108 row_shr:2 row_mask:0xf bank_mask:0xf
	v_mov_b32_dpp v171, v108 row_shr:3 row_mask:0xf bank_mask:0xf
	v_mov_b32_dpp v176, v109 row_shr:1 row_mask:0xf bank_mask:0xf
	v_mov_b32_dpp v174, v109 row_shr:2 row_mask:0xf bank_mask:0xf
	v_mov_b32_dpp v172, v109 row_shr:3 row_mask:0xf bank_mask:0xf
	v_mov_b32_dpp v169, v110 row_shr:1 row_mask:0xf bank_mask:0xf
	v_mov_b32_dpp v167, v110 row_shr:2 row_mask:0xf bank_mask:0xf
	v_mov_b32_dpp v151, v110 row_shr:3 row_mask:0xf bank_mask:0xf
	v_mov_b32_dpp v170, v111 row_shr:1 row_mask:0xf bank_mask:0xf
	v_mov_b32_dpp v168, v111 row_shr:2 row_mask:0xf bank_mask:0xf
	v_mov_b32_dpp v166, v111 row_shr:3 row_mask:0xf bank_mask:0xf
	v_lshl_add_u64 v[112:113], s[22:23], 0, v[136:137]
	s_and_saveexec_b64 s[22:23], s[2:3]
	s_cbranch_execz .LBB0_193
;     __device__ __forceinline__ void operator()(const f32x4 (&acc)[2][2][4][2], const Unit& u, int wr, int wc, int fr, int fq, LAS unsigned char* hb) const {
;     ...
;             for (int m = 0; m < 4; ++m) { asm volatile("" ::: "memory"); __builtin_amdgcn_sched_barrier(0);
;                 const int q = 8 * ai + 4 * wr + m, prev = q > 0 ? q - 1 : 0; const int lr = ai * HALF + wr * 64 + m * 16 + fr, R = R0 + lr;
;                 const int Rc = R < 0 ? 0 : R; const int b = Rc / LL, p = Rc - b * LL;
;                 const bool ok = (lr >= H && R < TT);
;                 const unsigned ooff = ((unsigned)Rc * (unsigned)LDP + (unsigned)(OFF_XBC + ch0)) * 2u;
; #pragma unroll
;                 for (int bn = 0; bn < 4; ++bn) { const int bj = bn >> 1, n = bn & 1; const int co = bj * HALF + 4 * n;
;                     const unsigned woff = (unsigned)(ch0 + co) * 4u;
;                     const f32x4 w0 = *(const f32x4*)((const char*)cw + woff), w1 = *(const f32x4*)((const char*)cw + woff + XBCW * 4), w2 = *(const f32x4*)((const char*)cw + woff + 2 * XBCW * 4), w3 = *(const f32x4*)((const char*)cw + woff + 3 * XBCW * 4), bs = *(const f32x4*)((const char*)cb + woff);
;                     const LAS unsigned char* hp = hb + (prev * H * NCH + chl + co) * 2;
;                     const u32x2 q1 = *(const LAS u32x2*)(hp + hr1 * NCH * 2), q2 = *(const LAS u32x2*)(hp + hr2 * NCH * 2), q3 = *(const LAS u32x2*)(hp + hr3 * NCH * 2);
;                     const float h1[4] = {__builtin_bit_cast(float, q1.x << 16), __builtin_bit_cast(float, q1.x & 0xffff0000u), __builtin_bit_cast(float, q1.y << 16), __builtin_bit_cast(float, q1.y & 0xffff0000u)};
;                     const float h2[4] = {__builtin_bit_cast(float, q2.x << 16), __builtin_bit_cast(float, q2.x & 0xffff0000u), __builtin_bit_cast(float, q2.y << 16), __builtin_bit_cast(float, q2.y & 0xffff0000u)};
;                     const float h3[4] = {__builtin_bit_cast(float, q3.x << 16), __builtin_bit_cast(float, q3.x & 0xffff0000u), __builtin_bit_cast(float, q3.y << 16), __builtin_bit_cast(float, q3.y & 0xffff0000u)};
;                     const f32x4 gv = acc[ai][bj][m][n];
;                     float o[4];
; #pragma unroll
;                     for (int j = 0; j < 4; ++j) { const float g = gv[j];
;                         float g1 = dpp_row_shr<1>(h1[j], g), g2 = dpp_row_shr<2>(h2[j], g), g3 = dpp_row_shr<3>(h3[j], g);
	ds_read_b128 v[182:185], v238 offset:4096
	ds_read_b128 v[186:189], v238 offset:3072
	v_cndmask_b32_e64 v177, v176, 0, s[8:9]
	ds_read_b128 v[190:193], v238 offset:2048
	v_cndmask_b32_e64 v176, v175, 0, s[8:9]
	ds_read_b128 v[194:197], v238 offset:1024
	ds_read_b128 v[198:201], v238
	v_cndmask_b32_e64 v175, 0, v174, s[6:7]
	v_cndmask_b32_e64 v174, 0, v173, s[6:7]
	v_cndmask_b32_e64 v173, 0, v172, s[4:5]
	v_cndmask_b32_e64 v172, 0, v171, s[4:5]
	v_cndmask_b32_e64 v171, v170, 0, s[8:9]
	v_cndmask_b32_e64 v170, v169, 0, s[8:9]
	v_cndmask_b32_e64 v169, 0, v168, s[6:7]
	v_cndmask_b32_e64 v168, 0, v167, s[6:7]
	v_cndmask_b32_e64 v167, 0, v166, s[4:5]
	v_cndmask_b32_e64 v166, 0, v151, s[4:5]
	s_waitcnt lgkmcnt(0)
	v_pk_fma_f32 v[108:109], v[108:109], v[186:187], v[182:183]
	v_pk_fma_f32 v[110:111], v[110:111], v[188:189], v[184:185]
	v_pk_fma_f32 v[108:109], v[176:177], v[190:191], v[108:109]
	v_pk_fma_f32 v[110:111], v[170:171], v[192:193], v[110:111]
	v_pk_fma_f32 v[108:109], v[174:175], v[194:195], v[108:109]
	s_nop 0
	v_pk_fma_f32 v[108:109], v[172:173], v[198:199], v[108:109]
	v_pk_fma_f32 v[110:111], v[168:169], v[196:197], v[110:111]
	v_mul_f32_e32 v136, 0xbfb8aa3b, v109
	v_exp_f32_e32 v136, v136
	v_pk_fma_f32 v[110:111], v[166:167], v[200:201], v[110:111]
	v_add_f32_e32 v136, 1.0, v136
	v_rcp_f32_e32 v173, v136
	v_mul_f32_e32 v136, 0xbfb8aa3b, v108
	v_exp_f32_e32 v136, v136
	s_nop 0
	v_add_f32_e32 v136, 1.0, v136
	v_rcp_f32_e32 v172, v136
	s_nop 0
	v_pk_mul_f32 v[108:109], v[108:109], v[172:173]
	s_nop 0
	v_cvt_pk_bf16_f32 v108, v108, v109
	v_mul_f32_e32 v109, 0xbfb8aa3b, v111
	v_exp_f32_e32 v109, v109
	s_nop 0
	v_add_f32_e32 v109, 1.0, v109
	v_rcp_f32_e32 v167, v109
	v_mul_f32_e32 v109, 0xbfb8aa3b, v110
	v_exp_f32_e32 v109, v109
	s_nop 0
	v_add_f32_e32 v109, 1.0, v109
	v_rcp_f32_e32 v166, v109
	s_nop 0
	v_pk_mul_f32 v[110:111], v[110:111], v[166:167]
	s_nop 0
	v_cvt_pk_bf16_f32 v109, v110, v111
	global_store_dwordx2 v[112:113], v[108:109], off
.LBB0_193:
	s_or_b64 exec, exec, s[22:23]
	ds_read_b64 v[108:109], v114 offset:1032
	ds_read_b64 v[110:111], v115 offset:520
	ds_read_b64 v[172:173], v150 offset:8
	s_waitcnt lgkmcnt(0)
	v_lshlrev_b32_e32 v170, 16, v108
	v_and_b32_e32 v171, 0xffff0000, v108
	v_lshlrev_b32_e32 v136, 16, v109
	v_and_b32_e32 v151, 0xffff0000, v109
	v_lshlrev_b32_e32 v168, 16, v110
	v_and_b32_e32 v169, 0xffff0000, v110
	v_lshlrev_b32_e32 v110, 16, v111
	v_and_b32_e32 v111, 0xffff0000, v111
	v_lshlrev_b32_e32 v166, 16, v172
	v_and_b32_e32 v167, 0xffff0000, v172
	v_lshlrev_b32_e32 v108, 16, v173
	v_and_b32_e32 v109, 0xffff0000, v173
	v_mov_b32_dpp v170, v104 row_shr:1 row_mask:0xf bank_mask:0xf
	v_mov_b32_dpp v168, v104 row_shr:2 row_mask:0xf bank_mask:0xf
	v_mov_b32_dpp v166, v104 row_shr:3 row_mask:0xf bank_mask:0xf
	v_mov_b32_dpp v171, v105 row_shr:1 row_mask:0xf bank_mask:0xf
	v_mov_b32_dpp v169, v105 row_shr:2 row_mask:0xf bank_mask:0xf
	v_mov_b32_dpp v167, v105 row_shr:3 row_mask:0xf bank_mask:0xf
	v_mov_b32_dpp v136, v106 row_shr:1 row_mask:0xf bank_mask:0xf
	v_mov_b32_dpp v110, v106 row_shr:2 row_mask:0xf bank_mask:0xf
	v_mov_b32_dpp v108, v106 row_shr:3 row_mask:0xf bank_mask:0xf
	v_mov_b32_dpp v151, v107 row_shr:1 row_mask:0xf bank_mask:0xf
	v_mov_b32_dpp v111, v107 row_shr:2 row_mask:0xf bank_mask:0xf
	v_mov_b32_dpp v109, v107 row_shr:3 row_mask:0xf bank_mask:0xf
	s_and_saveexec_b64 s[22:23], s[2:3]
	s_cbranch_execz .LBB0_195
	ds_read_b128 v[172:175], v238 offset:4112
	ds_read_b128 v[176:179], v238 offset:3088
	ds_read_b128 v[182:185], v238 offset:2064
	v_cndmask_b32_e64 v171, v171, 0, s[8:9]
	ds_read_b128 v[186:189], v238 offset:1040
	s_nop 0
	ds_read_b128 v[190:193], v238 offset:16
	v_cndmask_b32_e64 v170, v170, 0, s[8:9]
	v_cndmask_b32_e64 v169, 0, v169, s[6:7]
	v_cndmask_b32_e64 v168, 0, v168, s[6:7]
	v_cndmask_b32_e64 v167, 0, v167, s[4:5]
	v_cndmask_b32_e64 v166, 0, v166, s[4:5]
	v_cndmask_b32_e64 v111, 0, v111, s[6:7]
	v_cndmask_b32_e64 v110, 0, v110, s[6:7]
	v_cndmask_b32_e64 v109, 0, v109, s[4:5]
	v_cndmask_b32_e64 v108, 0, v108, s[4:5]
	s_waitcnt lgkmcnt(0)
	v_pk_fma_f32 v[104:105], v[104:105], v[176:177], v[172:173]
	v_pk_fma_f32 v[106:107], v[106:107], v[178:179], v[174:175]
	v_pk_fma_f32 v[104:105], v[170:171], v[182:183], v[104:105]
	s_nop 0
	v_pk_fma_f32 v[104:105], v[168:169], v[186:187], v[104:105]
	s_nop 0
	v_pk_fma_f32 v[104:105], v[166:167], v[190:191], v[104:105]
	s_nop 0
	v_mul_f32_e32 v166, 0xbfb8aa3b, v105
	v_exp_f32_e32 v166, v166
	s_nop 0
	v_add_f32_e32 v166, 1.0, v166
	v_rcp_f32_e32 v167, v166
	v_mul_f32_e32 v166, 0xbfb8aa3b, v104
	v_exp_f32_e32 v166, v166
	s_nop 0
	v_add_f32_e32 v166, 1.0, v166
	v_rcp_f32_e32 v166, v166
	s_nop 0
	v_pk_mul_f32 v[104:105], v[104:105], v[166:167]
	v_cndmask_b32_e64 v167, v151, 0, s[8:9]
	v_cndmask_b32_e64 v166, v136, 0, s[8:9]
	v_pk_fma_f32 v[106:107], v[166:167], v[184:185], v[106:107]
	v_cvt_pk_bf16_f32 v104, v104, v105
	v_pk_fma_f32 v[106:107], v[110:111], v[188:189], v[106:107]
	s_nop 0
	v_pk_fma_f32 v[106:107], v[108:109], v[192:193], v[106:107]
	s_nop 0
	v_mul_f32_e32 v105, 0xbfb8aa3b, v107
	v_exp_f32_e32 v105, v105
	s_nop 0
	v_add_f32_e32 v105, 1.0, v105
	v_rcp_f32_e32 v109, v105
	v_mul_f32_e32 v105, 0xbfb8aa3b, v106
	v_exp_f32_e32 v105, v105
	s_nop 0
	v_add_f32_e32 v105, 1.0, v105
	v_rcp_f32_e32 v108, v105
	s_nop 0
	v_pk_mul_f32 v[106:107], v[106:107], v[108:109]
	s_nop 0
	v_cvt_pk_bf16_f32 v105, v106, v107
	global_store_dwordx2 v[112:113], v[104:105], off offset:8
;     __device__ __forceinline__ void operator()(const f32x4 (&acc)[2][2][4][2], const Unit& u, int wr, int wc, int fr, int fq, LAS unsigned char* hb) const {
;     ...
;             for (int m = 0; m < 4; ++m) { asm volatile("" ::: "memory"); __builtin_amdgcn_sched_barrier(0);
;                 const int q = 8 * ai + 4 * wr + m, prev = q > 0 ? q - 1 : 0; const int lr = ai * HALF + wr * 64 + m * 16 + fr, R = R0 + lr;
;                 const int Rc = R < 0 ? 0 : R; const int b = Rc / LL, p = Rc - b * LL;
;                 const bool ok = (lr >= H && R < TT);
;                 const unsigned ooff = ((unsigned)Rc * (unsigned)LDP + (unsigned)(OFF_XBC + ch0)) * 2u;
; #pragma unroll
;                 for (int bn = 0; bn < 4; ++bn) { const int bj = bn >> 1, n = bn & 1; const int co = bj * HALF + 4 * n;
;                     const unsigned woff = (unsigned)(ch0 + co) * 4u;
;                     const f32x4 w0 = *(const f32x4*)((const char*)cw + woff), w1 = *(const f32x4*)((const char*)cw + woff + XBCW * 4), w2 = *(const f32x4*)((const char*)cw + woff + 2 * XBCW * 4), w3 = *(const f32x4*)((const char*)cw + woff + 3 * XBCW * 4), bs = *(const f32x4*)((const char*)cb + woff);
;                     const LAS unsigned char* hp = hb + (prev * H * NCH + chl + co) * 2;
;                     const u32x2 q1 = *(const LAS u32x2*)(hp + hr1 * NCH * 2), q2 = *(const LAS u32x2*)(hp + hr2 * NCH * 2), q3 = *(const LAS u32x2*)(hp + hr3 * NCH * 2);
;                     const float h1[4] = {__builtin_bit_cast(float, q1.x << 16), __builtin_bit_cast(float, q1.x & 0xffff0000u), __builtin_bit_cast(float, q1.y << 16), __builtin_bit_cast(float, q1.y & 0xffff0000u)};
;                     const float h2[4] = {__builtin_bit_cast(float, q2.x << 16), __builtin_bit_cast(float, q2.x & 0xffff0000u), __builtin_bit_cast(float, q2.y << 16), __builtin_bit_cast(float, q2.y & 0xffff0000u)};
;                     const float h3[4] = {__builtin_bit_cast(float, q3.x << 16), __builtin_bit_cast(float, q3.x & 0xffff0000u), __builtin_bit_cast(float, q3.y << 16), __builtin_bit_cast(float, q3.y & 0xffff0000u)};
;                     const f32x4 gv = acc[ai][bj][m][n];
;                     float o[4];
; #pragma unroll
;                     for (int j = 0; j < 4; ++j) { const float g = gv[j];
;                         float g1 = dpp_row_shr<1>(h1[j], g), g2 = dpp_row_shr<2>(h2[j], g), g3 = dpp_row_shr<3>(h3[j], g);
.LBB0_195:
	s_or_b64 exec, exec, s[22:23]
	ds_read_b64 v[104:105], v114 offset:1280
	ds_read_b64 v[106:107], v115 offset:768
	ds_read_b64 v[168:169], v150 offset:256
	s_waitcnt lgkmcnt(0)
	v_lshlrev_b32_e32 v166, 16, v104
	v_and_b32_e32 v167, 0xffff0000, v104
	v_lshlrev_b32_e32 v108, 16, v105
	v_and_b32_e32 v109, 0xffff0000, v105
	v_lshlrev_b32_e32 v136, 16, v106
	v_and_b32_e32 v151, 0xffff0000, v106
	v_lshlrev_b32_e32 v106, 16, v107
	v_and_b32_e32 v107, 0xffff0000, v107
	v_lshlrev_b32_e32 v110, 16, v168
	v_and_b32_e32 v111, 0xffff0000, v168
	v_lshlrev_b32_e32 v104, 16, v169
	v_and_b32_e32 v105, 0xffff0000, v169
	v_mov_b32_dpp v166, v100 row_shr:1 row_mask:0xf bank_mask:0xf
	v_mov_b32_dpp v136, v100 row_shr:2 row_mask:0xf bank_mask:0xf
	v_mov_b32_dpp v110, v100 row_shr:3 row_mask:0xf bank_mask:0xf
	v_mov_b32_dpp v167, v101 row_shr:1 row_mask:0xf bank_mask:0xf
	v_mov_b32_dpp v151, v101 row_shr:2 row_mask:0xf bank_mask:0xf
	v_mov_b32_dpp v111, v101 row_shr:3 row_mask:0xf bank_mask:0xf
	v_mov_b32_dpp v108, v102 row_shr:1 row_mask:0xf bank_mask:0xf
	v_mov_b32_dpp v106, v102 row_shr:2 row_mask:0xf bank_mask:0xf
	v_mov_b32_dpp v104, v102 row_shr:3 row_mask:0xf bank_mask:0xf
	v_mov_b32_dpp v109, v103 row_shr:1 row_mask:0xf bank_mask:0xf
	v_mov_b32_dpp v107, v103 row_shr:2 row_mask:0xf bank_mask:0xf
	v_mov_b32_dpp v105, v103 row_shr:3 row_mask:0xf bank_mask:0xf
	s_and_saveexec_b64 s[22:23], s[2:3]
	s_cbranch_execz .LBB0_197
	ds_read_b128 v[168:171], v238 offset:4608
	ds_read_b128 v[172:175], v238 offset:3584
	ds_read_b128 v[176:179], v238 offset:2560
	v_cndmask_b32_e64 v167, v167, 0, s[8:9]
	ds_read_b128 v[182:185], v238 offset:1536
	s_nop 0
	ds_read_b128 v[186:189], v238 offset:512
	v_cndmask_b32_e64 v166, v166, 0, s[8:9]
	v_cndmask_b32_e64 v111, 0, v111, s[4:5]
	v_cndmask_b32_e64 v110, 0, v110, s[4:5]
	v_cndmask_b32_e64 v109, v109, 0, s[8:9]
	v_cndmask_b32_e64 v108, v108, 0, s[8:9]
	v_cndmask_b32_e64 v107, 0, v107, s[6:7]
	v_cndmask_b32_e64 v106, 0, v106, s[6:7]
	v_cndmask_b32_e64 v105, 0, v105, s[4:5]
	v_cndmask_b32_e64 v104, 0, v104, s[4:5]
	s_waitcnt lgkmcnt(0)
	v_pk_fma_f32 v[100:101], v[100:101], v[172:173], v[168:169]
	v_pk_fma_f32 v[102:103], v[102:103], v[174:175], v[170:171]
	v_pk_fma_f32 v[100:101], v[166:167], v[176:177], v[100:101]
	v_cndmask_b32_e64 v167, 0, v151, s[6:7]
	v_cndmask_b32_e64 v166, 0, v136, s[6:7]
	v_pk_fma_f32 v[102:103], v[108:109], v[178:179], v[102:103]
	v_pk_fma_f32 v[100:101], v[166:167], v[182:183], v[100:101]
	s_nop 0
	v_pk_fma_f32 v[100:101], v[110:111], v[186:187], v[100:101]
	v_pk_fma_f32 v[102:103], v[106:107], v[184:185], v[102:103]
	v_mul_f32_e32 v110, 0xbfb8aa3b, v101
	v_exp_f32_e32 v110, v110
	v_pk_fma_f32 v[102:103], v[104:105], v[188:189], v[102:103]
	v_add_f32_e32 v110, 1.0, v110
	v_rcp_f32_e32 v111, v110
	v_mul_f32_e32 v110, 0xbfb8aa3b, v100
	v_exp_f32_e32 v110, v110
	s_nop 0
	v_add_f32_e32 v110, 1.0, v110
	v_rcp_f32_e32 v110, v110
	s_nop 0
	v_pk_mul_f32 v[100:101], v[100:101], v[110:111]
	s_nop 0
	v_cvt_pk_bf16_f32 v100, v100, v101
	v_mul_f32_e32 v101, 0xbfb8aa3b, v103
	v_exp_f32_e32 v101, v101
	s_nop 0
	v_add_f32_e32 v101, 1.0, v101
	v_rcp_f32_e32 v105, v101
	v_mul_f32_e32 v101, 0xbfb8aa3b, v102
	v_exp_f32_e32 v101, v101
	s_nop 0
	v_add_f32_e32 v101, 1.0, v101
	v_rcp_f32_e32 v104, v101
	s_nop 0
	v_pk_mul_f32 v[102:103], v[102:103], v[104:105]
	s_nop 0
	v_cvt_pk_bf16_f32 v101, v102, v103
	global_store_dwordx2 v[112:113], v[100:101], off offset:256
.LBB0_197:
	s_or_b64 exec, exec, s[22:23]
	ds_read_b64 v[100:101], v114 offset:1288
	ds_read_b64 v[102:103], v115 offset:776
	ds_read_b64 v[114:115], v150 offset:264
	s_waitcnt lgkmcnt(0)
	v_lshlrev_b32_e32 v110, 16, v100
	v_and_b32_e32 v111, 0xffff0000, v100
	v_lshlrev_b32_e32 v104, 16, v101
	v_and_b32_e32 v105, 0xffff0000, v101
	v_lshlrev_b32_e32 v108, 16, v102
	v_and_b32_e32 v109, 0xffff0000, v102
	v_lshlrev_b32_e32 v102, 16, v103
	v_and_b32_e32 v103, 0xffff0000, v103
	v_lshlrev_b32_e32 v106, 16, v114
	v_and_b32_e32 v107, 0xffff0000, v114
	v_lshlrev_b32_e32 v100, 16, v115
	v_and_b32_e32 v101, 0xffff0000, v115
	v_mov_b32_dpp v110, v96 row_shr:1 row_mask:0xf bank_mask:0xf
	v_mov_b32_dpp v108, v96 row_shr:2 row_mask:0xf bank_mask:0xf
	v_mov_b32_dpp v106, v96 row_shr:3 row_mask:0xf bank_mask:0xf
	v_mov_b32_dpp v111, v97 row_shr:1 row_mask:0xf bank_mask:0xf
	v_mov_b32_dpp v109, v97 row_shr:2 row_mask:0xf bank_mask:0xf
	v_mov_b32_dpp v107, v97 row_shr:3 row_mask:0xf bank_mask:0xf
	v_mov_b32_dpp v104, v98 row_shr:1 row_mask:0xf bank_mask:0xf
	v_mov_b32_dpp v102, v98 row_shr:2 row_mask:0xf bank_mask:0xf
	v_mov_b32_dpp v100, v98 row_shr:3 row_mask:0xf bank_mask:0xf
	v_mov_b32_dpp v105, v99 row_shr:1 row_mask:0xf bank_mask:0xf
	v_mov_b32_dpp v103, v99 row_shr:2 row_mask:0xf bank_mask:0xf
	v_mov_b32_dpp v101, v99 row_shr:3 row_mask:0xf bank_mask:0xf
	s_and_saveexec_b64 s[22:23], s[2:3]
	s_cbranch_execz .LBB0_199
	ds_read_b128 v[166:169], v238 offset:4624
	ds_read_b128 v[170:173], v238 offset:3600
	v_cndmask_b32_e64 v111, v111, 0, s[8:9]
	ds_read_b128 v[174:177], v238 offset:2576
	v_cndmask_b32_e64 v110, v110, 0, s[8:9]
	ds_read_b128 v[182:185], v238 offset:1552
	ds_read_b128 v[186:189], v238 offset:528
	v_cndmask_b32_e64 v109, 0, v109, s[6:7]
	v_cndmask_b32_e64 v108, 0, v108, s[6:7]
	v_cndmask_b32_e64 v107, 0, v107, s[4:5]
	v_cndmask_b32_e64 v106, 0, v106, s[4:5]
	v_cndmask_b32_e64 v105, v105, 0, s[8:9]
	v_cndmask_b32_e64 v104, v104, 0, s[8:9]
	v_cndmask_b32_e64 v103, 0, v103, s[6:7]
	v_cndmask_b32_e64 v102, 0, v102, s[6:7]
	v_cndmask_b32_e64 v101, 0, v101, s[4:5]
	v_cndmask_b32_e64 v100, 0, v100, s[4:5]
	s_waitcnt lgkmcnt(0)
	v_pk_fma_f32 v[96:97], v[96:97], v[170:171], v[166:167]
	v_pk_fma_f32 v[98:99], v[98:99], v[172:173], v[168:169]
	v_pk_fma_f32 v[96:97], v[110:111], v[174:175], v[96:97]
	v_pk_fma_f32 v[98:99], v[104:105], v[176:177], v[98:99]
	v_pk_fma_f32 v[96:97], v[108:109], v[182:183], v[96:97]
	s_nop 0
	v_pk_fma_f32 v[96:97], v[106:107], v[186:187], v[96:97]
	v_pk_fma_f32 v[98:99], v[102:103], v[184:185], v[98:99]
	v_mul_f32_e32 v106, 0xbfb8aa3b, v97
	v_exp_f32_e32 v106, v106
	v_pk_fma_f32 v[98:99], v[100:101], v[188:189], v[98:99]
	v_add_f32_e32 v106, 1.0, v106
	v_rcp_f32_e32 v107, v106
	v_mul_f32_e32 v106, 0xbfb8aa3b, v96
	v_exp_f32_e32 v106, v106
	s_nop 0
	v_add_f32_e32 v106, 1.0, v106
	v_rcp_f32_e32 v106, v106
	s_nop 0
	v_pk_mul_f32 v[96:97], v[96:97], v[106:107]
	s_nop 0
	v_cvt_pk_bf16_f32 v96, v96, v97
	v_mul_f32_e32 v97, 0xbfb8aa3b, v99
	v_exp_f32_e32 v97, v97
	s_nop 0
	v_add_f32_e32 v97, 1.0, v97
	v_rcp_f32_e32 v101, v97
	v_mul_f32_e32 v97, 0xbfb8aa3b, v98
	v_exp_f32_e32 v97, v97
	s_nop 0
	v_add_f32_e32 v97, 1.0, v97
	v_rcp_f32_e32 v100, v97
	s_nop 0
	v_pk_mul_f32 v[98:99], v[98:99], v[100:101]
	s_nop 0
	v_cvt_pk_bf16_f32 v97, v98, v99
	global_store_dwordx2 v[112:113], v[96:97], off offset:264
;     __device__ __forceinline__ void operator()(const f32x4 (&acc)[2][2][4][2], const Unit& u, int wr, int wc, int fr, int fq, LAS unsigned char* hb) const {
;     ...
;             for (int m = 0; m < 4; ++m) { asm volatile("" ::: "memory"); __builtin_amdgcn_sched_barrier(0);
;                 const int q = 8 * ai + 4 * wr + m, prev = q > 0 ? q - 1 : 0; const int lr = ai * HALF + wr * 64 + m * 16 + fr, R = R0 + lr;
;                 const int Rc = R < 0 ? 0 : R; const int b = Rc / LL, p = Rc - b * LL;
;                 const bool ok = (lr >= H && R < TT);
;                 const unsigned ooff = ((unsigned)Rc * (unsigned)LDP + (unsigned)(OFF_XBC + ch0)) * 2u;
; #pragma unroll
;                 for (int bn = 0; bn < 4; ++bn) { const int bj = bn >> 1, n = bn & 1; const int co = bj * HALF + 4 * n;
;                     const unsigned woff = (unsigned)(ch0 + co) * 4u;
;                     const f32x4 w0 = *(const f32x4*)((const char*)cw + woff), w1 = *(const f32x4*)((const char*)cw + woff + XBCW * 4), w2 = *(const f32x4*)((const char*)cw + woff + 2 * XBCW * 4), w3 = *(const f32x4*)((const char*)cw + woff + 3 * XBCW * 4), bs = *(const f32x4*)((const char*)cb + woff);
;                     const LAS unsigned char* hp = hb + (prev * H * NCH + chl + co) * 2;
;                     const u32x2 q1 = *(const LAS u32x2*)(hp + hr1 * NCH * 2), q2 = *(const LAS u32x2*)(hp + hr2 * NCH * 2), q3 = *(const LAS u32x2*)(hp + hr3 * NCH * 2);
;                     const float h1[4] = {__builtin_bit_cast(float, q1.x << 16), __builtin_bit_cast(float, q1.x & 0xffff0000u), __builtin_bit_cast(float, q1.y << 16), __builtin_bit_cast(float, q1.y & 0xffff0000u)};
;                     const float h2[4] = {__builtin_bit_cast(float, q2.x << 16), __builtin_bit_cast(float, q2.x & 0xffff0000u), __builtin_bit_cast(float, q2.y << 16), __builtin_bit_cast(float, q2.y & 0xffff0000u)};
;                     const float h3[4] = {__builtin_bit_cast(float, q3.x << 16), __builtin_bit_cast(float, q3.x & 0xffff0000u), __builtin_bit_cast(float, q3.y << 16), __builtin_bit_cast(float, q3.y & 0xffff0000u)};
;                     const f32x4 gv = acc[ai][bj][m][n];
;                     float o[4];
; #pragma unroll
;                     for (int j = 0; j < 4; ++j) { const float g = gv[j];
;                         float g1 = dpp_row_shr<1>(h1[j], g), g2 = dpp_row_shr<2>(h2[j], g), g3 = dpp_row_shr<3>(h3[j], g);
.LBB0_199:
	s_or_b64 exec, exec, s[22:23]
	v_add_u32_e32 v96, 32, v161
	v_add_u32_e32 v97, s17, v96
	v_max_i32_e32 v98, 0, v97
	v_mul_hi_u32 v99, v98, s56
	v_lshrrev_b32_e32 v99, 11, v99
	v_cmp_lt_i32_e32 vcc, 2, v96
	v_mul_lo_u32 v96, v98, s51
	v_mul_u32_u24_e32 v99, 0x1010, v99
	v_add_lshl_u32 v136, v96, v164, 1
	v_add_u32_e32 v96, s39, v165
	v_sub_u32_e32 v99, v98, v99
	v_cmp_gt_i32_e64 s[4:5], s50, v97
	v_lshl_add_u32 v98, v96, 1, s53
	s_and_b64 s[2:3], vcc, s[4:5]
	v_cmp_eq_u32_e64 s[8:9], 0, v99
	v_cmp_lt_u32_e64 s[6:7], 1, v99
	v_cmp_lt_u32_e64 s[4:5], 2, v99
	v_add_u32_e32 v99, v98, v163
	ds_read_b64 v[96:97], v98 offset:1024
	v_add_u32_e32 v100, v98, v162
	ds_read_b64 v[114:115], v99 offset:512
	ds_read_b64 v[150:151], v100
	v_readlane_b32 s22, v237, 58
	v_readlane_b32 s23, v237, 59
	s_waitcnt lgkmcnt(0)
	v_lshlrev_b32_e32 v111, 16, v96
	v_and_b32_e32 v112, 0xffff0000, v96
	v_lshlrev_b32_e32 v105, 16, v97
	v_and_b32_e32 v106, 0xffff0000, v97
	v_lshlrev_b32_e32 v109, 16, v114
	v_and_b32_e32 v110, 0xffff0000, v114
	v_lshlrev_b32_e32 v103, 16, v115
	v_and_b32_e32 v104, 0xffff0000, v115
	v_lshlrev_b32_e32 v107, 16, v150
	v_and_b32_e32 v108, 0xffff0000, v150
	v_lshlrev_b32_e32 v101, 16, v151
	v_and_b32_e32 v102, 0xffff0000, v151
	v_mov_b32_dpp v111, v92 row_shr:1 row_mask:0xf bank_mask:0xf
	v_mov_b32_dpp v109, v92 row_shr:2 row_mask:0xf bank_mask:0xf
	v_mov_b32_dpp v107, v92 row_shr:3 row_mask:0xf bank_mask:0xf
	v_mov_b32_dpp v112, v93 row_shr:1 row_mask:0xf bank_mask:0xf
	v_mov_b32_dpp v110, v93 row_shr:2 row_mask:0xf bank_mask:0xf
	v_mov_b32_dpp v108, v93 row_shr:3 row_mask:0xf bank_mask:0xf
	v_mov_b32_dpp v105, v94 row_shr:1 row_mask:0xf bank_mask:0xf
	v_mov_b32_dpp v103, v94 row_shr:2 row_mask:0xf bank_mask:0xf
	v_mov_b32_dpp v101, v94 row_shr:3 row_mask:0xf bank_mask:0xf
	v_mov_b32_dpp v106, v95 row_shr:1 row_mask:0xf bank_mask:0xf
	v_mov_b32_dpp v104, v95 row_shr:2 row_mask:0xf bank_mask:0xf
	v_mov_b32_dpp v102, v95 row_shr:3 row_mask:0xf bank_mask:0xf
	v_lshl_add_u64 v[96:97], s[22:23], 0, v[136:137]
	s_and_saveexec_b64 s[22:23], s[2:3]
	s_cbranch_execz .LBB0_201
	ds_read_b128 v[166:169], v238 offset:4096
	ds_read_b128 v[170:173], v238 offset:3072
	v_cndmask_b32_e64 v113, v112, 0, s[8:9]
	ds_read_b128 v[174:177], v238 offset:2048
	v_cndmask_b32_e64 v112, v111, 0, s[8:9]
	ds_read_b128 v[182:185], v238 offset:1024
	ds_read_b128 v[186:189], v238
	v_cndmask_b32_e64 v111, 0, v110, s[6:7]
	v_cndmask_b32_e64 v110, 0, v109, s[6:7]
	v_cndmask_b32_e64 v109, 0, v108, s[4:5]
	v_cndmask_b32_e64 v108, 0, v107, s[4:5]
	s_waitcnt lgkmcnt(0)
	v_pk_fma_f32 v[92:93], v[92:93], v[170:171], v[166:167]
	v_pk_fma_f32 v[94:95], v[94:95], v[172:173], v[168:169]
	v_pk_fma_f32 v[92:93], v[112:113], v[174:175], v[92:93]
	s_nop 0
	v_pk_fma_f32 v[92:93], v[110:111], v[182:183], v[92:93]
	s_nop 0
	v_pk_fma_f32 v[92:93], v[108:109], v[186:187], v[92:93]
	s_nop 0
	v_mul_f32_e32 v107, 0xbfb8aa3b, v93
	v_exp_f32_e32 v107, v107
	s_nop 0
	v_add_f32_e32 v107, 1.0, v107
	v_rcp_f32_e32 v109, v107
	v_mul_f32_e32 v107, 0xbfb8aa3b, v92
	v_exp_f32_e32 v107, v107
	s_nop 0
	v_add_f32_e32 v107, 1.0, v107
	v_rcp_f32_e32 v108, v107
	v_cndmask_b32_e64 v107, v106, 0, s[8:9]
	v_cndmask_b32_e64 v106, v105, 0, s[8:9]
	v_pk_fma_f32 v[94:95], v[106:107], v[176:177], v[94:95]
	v_cndmask_b32_e64 v105, 0, v104, s[6:7]
	v_cndmask_b32_e64 v104, 0, v103, s[6:7]
	v_pk_fma_f32 v[94:95], v[104:105], v[184:185], v[94:95]
	v_cndmask_b32_e64 v103, 0, v102, s[4:5]
	v_cndmask_b32_e64 v102, 0, v101, s[4:5]
	v_pk_mul_f32 v[92:93], v[92:93], v[108:109]
	v_pk_fma_f32 v[94:95], v[102:103], v[188:189], v[94:95]
	v_cvt_pk_bf16_f32 v92, v92, v93
	v_mul_f32_e32 v93, 0xbfb8aa3b, v95
	v_exp_f32_e32 v93, v93
	s_nop 0
	v_add_f32_e32 v93, 1.0, v93
	v_rcp_f32_e32 v103, v93
	v_mul_f32_e32 v93, 0xbfb8aa3b, v94
	v_exp_f32_e32 v93, v93
	s_nop 0
	v_add_f32_e32 v93, 1.0, v93
	v_rcp_f32_e32 v102, v93
	s_nop 0
	v_pk_mul_f32 v[94:95], v[94:95], v[102:103]
	s_nop 0
	v_cvt_pk_bf16_f32 v93, v94, v95
	global_store_dwordx2 v[96:97], v[92:93], off
.LBB0_201:
	s_or_b64 exec, exec, s[22:23]
	ds_read_b64 v[92:93], v98 offset:1032
	ds_read_b64 v[94:95], v99 offset:520
	ds_read_b64 v[110:111], v100 offset:8
	s_waitcnt lgkmcnt(0)
	v_lshlrev_b32_e32 v107, 16, v92
	v_and_b32_e32 v108, 0xffff0000, v92
	v_lshlrev_b32_e32 v101, 16, v93
	v_and_b32_e32 v102, 0xffff0000, v93
	v_lshlrev_b32_e32 v105, 16, v94
	v_and_b32_e32 v106, 0xffff0000, v94
	v_lshlrev_b32_e32 v94, 16, v95
	v_and_b32_e32 v95, 0xffff0000, v95
	v_lshlrev_b32_e32 v103, 16, v110
	v_and_b32_e32 v104, 0xffff0000, v110
	v_lshlrev_b32_e32 v92, 16, v111
	v_and_b32_e32 v93, 0xffff0000, v111
	v_mov_b32_dpp v107, v88 row_shr:1 row_mask:0xf bank_mask:0xf
	v_mov_b32_dpp v105, v88 row_shr:2 row_mask:0xf bank_mask:0xf
	v_mov_b32_dpp v103, v88 row_shr:3 row_mask:0xf bank_mask:0xf
	v_mov_b32_dpp v108, v89 row_shr:1 row_mask:0xf bank_mask:0xf
	v_mov_b32_dpp v106, v89 row_shr:2 row_mask:0xf bank_mask:0xf
	v_mov_b32_dpp v104, v89 row_shr:3 row_mask:0xf bank_mask:0xf
	v_mov_b32_dpp v101, v90 row_shr:1 row_mask:0xf bank_mask:0xf
	v_mov_b32_dpp v94, v90 row_shr:2 row_mask:0xf bank_mask:0xf
	v_mov_b32_dpp v92, v90 row_shr:3 row_mask:0xf bank_mask:0xf
	v_mov_b32_dpp v102, v91 row_shr:1 row_mask:0xf bank_mask:0xf
	v_mov_b32_dpp v95, v91 row_shr:2 row_mask:0xf bank_mask:0xf
	v_mov_b32_dpp v93, v91 row_shr:3 row_mask:0xf bank_mask:0xf
	s_and_saveexec_b64 s[22:23], s[2:3]
	s_cbranch_execz .LBB0_203
;     __device__ __forceinline__ void operator()(const f32x4 (&acc)[2][2][4][2], const Unit& u, int wr, int wc, int fr, int fq, LAS unsigned char* hb) const {
;     ...
;             for (int m = 0; m < 4; ++m) { asm volatile("" ::: "memory"); __builtin_amdgcn_sched_barrier(0);
;                 const int q = 8 * ai + 4 * wr + m, prev = q > 0 ? q - 1 : 0; const int lr = ai * HALF + wr * 64 + m * 16 + fr, R = R0 + lr;
;                 const int Rc = R < 0 ? 0 : R; const int b = Rc / LL, p = Rc - b * LL;
;                 const bool ok = (lr >= H && R < TT);
;                 const unsigned ooff = ((unsigned)Rc * (unsigned)LDP + (unsigned)(OFF_XBC + ch0)) * 2u;
; #pragma unroll
;                 for (int bn = 0; bn < 4; ++bn) { const int bj = bn >> 1, n = bn & 1; const int co = bj * HALF + 4 * n;
;                     const unsigned woff = (unsigned)(ch0 + co) * 4u;
;                     const f32x4 w0 = *(const f32x4*)((const char*)cw + woff), w1 = *(const f32x4*)((const char*)cw + woff + XBCW * 4), w2 = *(const f32x4*)((const char*)cw + woff + 2 * XBCW * 4), w3 = *(const f32x4*)((const char*)cw + woff + 3 * XBCW * 4), bs = *(const f32x4*)((const char*)cb + woff);
;                     const LAS unsigned char* hp = hb + (prev * H * NCH + chl + co) * 2;
;                     const u32x2 q1 = *(const LAS u32x2*)(hp + hr1 * NCH * 2), q2 = *(const LAS u32x2*)(hp + hr2 * NCH * 2), q3 = *(const LAS u32x2*)(hp + hr3 * NCH * 2);
;                     const float h1[4] = {__builtin_bit_cast(float, q1.x << 16), __builtin_bit_cast(float, q1.x & 0xffff0000u), __builtin_bit_cast(float, q1.y << 16), __builtin_bit_cast(float, q1.y & 0xffff0000u)};
;                     const float h2[4] = {__builtin_bit_cast(float, q2.x << 16), __builtin_bit_cast(float, q2.x & 0xffff0000u), __builtin_bit_cast(float, q2.y << 16), __builtin_bit_cast(float, q2.y & 0xffff0000u)};
;                     const float h3[4] = {__builtin_bit_cast(float, q3.x << 16), __builtin_bit_cast(float, q3.x & 0xffff0000u), __builtin_bit_cast(float, q3.y << 16), __builtin_bit_cast(float, q3.y & 0xffff0000u)};
;                     const f32x4 gv = acc[ai][bj][m][n];
;                     float o[4];
; #pragma unroll
;                     for (int j = 0; j < 4; ++j) { const float g = gv[j];
;                         float g1 = dpp_row_shr<1>(h1[j], g), g2 = dpp_row_shr<2>(h2[j], g), g3 = dpp_row_shr<3>(h3[j], g);
	ds_read_b128 v[110:113], v238 offset:4112
	ds_read_b128 v[166:169], v238 offset:3088
	v_cndmask_b32_e64 v109, v108, 0, s[8:9]
	ds_read_b128 v[170:173], v238 offset:2064
	v_cndmask_b32_e64 v108, v107, 0, s[8:9]
	ds_read_b128 v[174:177], v238 offset:1040
	ds_read_b128 v[182:185], v238 offset:16
	v_cndmask_b32_e64 v107, 0, v106, s[6:7]
	v_cndmask_b32_e64 v106, 0, v105, s[6:7]
	v_cndmask_b32_e64 v105, 0, v104, s[4:5]
	v_cndmask_b32_e64 v104, 0, v103, s[4:5]
	v_cndmask_b32_e64 v95, 0, v95, s[6:7]
	v_cndmask_b32_e64 v94, 0, v94, s[6:7]
	v_cndmask_b32_e64 v93, 0, v93, s[4:5]
	v_cndmask_b32_e64 v92, 0, v92, s[4:5]
	s_waitcnt lgkmcnt(0)
	v_pk_fma_f32 v[88:89], v[88:89], v[166:167], v[110:111]
	v_pk_fma_f32 v[90:91], v[90:91], v[168:169], v[112:113]
	v_pk_fma_f32 v[88:89], v[108:109], v[170:171], v[88:89]
	s_nop 0
	v_pk_fma_f32 v[88:89], v[106:107], v[174:175], v[88:89]
	s_nop 0
	v_pk_fma_f32 v[88:89], v[104:105], v[182:183], v[88:89]
	s_nop 0
	v_mul_f32_e32 v103, 0xbfb8aa3b, v89
	v_exp_f32_e32 v103, v103
	s_nop 0
	v_add_f32_e32 v103, 1.0, v103
	v_rcp_f32_e32 v105, v103
	v_mul_f32_e32 v103, 0xbfb8aa3b, v88
	v_exp_f32_e32 v103, v103
	s_nop 0
	v_add_f32_e32 v103, 1.0, v103
	v_rcp_f32_e32 v104, v103
	v_cndmask_b32_e64 v103, v102, 0, s[8:9]
	v_cndmask_b32_e64 v102, v101, 0, s[8:9]
	v_pk_fma_f32 v[90:91], v[102:103], v[172:173], v[90:91]
	v_pk_mul_f32 v[88:89], v[88:89], v[104:105]
	v_pk_fma_f32 v[90:91], v[94:95], v[176:177], v[90:91]
	v_cvt_pk_bf16_f32 v88, v88, v89
	v_pk_fma_f32 v[90:91], v[92:93], v[184:185], v[90:91]
	s_nop 0
	v_mul_f32_e32 v89, 0xbfb8aa3b, v91
	v_exp_f32_e32 v89, v89
	s_nop 0
	v_add_f32_e32 v89, 1.0, v89
	v_rcp_f32_e32 v93, v89
	v_mul_f32_e32 v89, 0xbfb8aa3b, v90
	v_exp_f32_e32 v89, v89
	s_nop 0
	v_add_f32_e32 v89, 1.0, v89
	v_rcp_f32_e32 v92, v89
	s_nop 0
	v_pk_mul_f32 v[90:91], v[90:91], v[92:93]
	s_nop 0
	v_cvt_pk_bf16_f32 v89, v90, v91
	global_store_dwordx2 v[96:97], v[88:89], off offset:8
.LBB0_203:
	s_or_b64 exec, exec, s[22:23]
	ds_read_b64 v[88:89], v98 offset:1280
	ds_read_b64 v[90:91], v99 offset:768
	ds_read_b64 v[106:107], v100 offset:256
	s_waitcnt lgkmcnt(0)
	v_lshlrev_b32_e32 v103, 16, v88
	v_and_b32_e32 v104, 0xffff0000, v88
	v_lshlrev_b32_e32 v92, 16, v89
	v_and_b32_e32 v93, 0xffff0000, v89
	v_lshlrev_b32_e32 v101, 16, v90
	v_and_b32_e32 v102, 0xffff0000, v90
	v_lshlrev_b32_e32 v90, 16, v91
	v_and_b32_e32 v91, 0xffff0000, v91
	v_lshlrev_b32_e32 v94, 16, v106
	v_and_b32_e32 v95, 0xffff0000, v106
	v_lshlrev_b32_e32 v88, 16, v107
	v_and_b32_e32 v89, 0xffff0000, v107
	v_mov_b32_dpp v103, v84 row_shr:1 row_mask:0xf bank_mask:0xf
	v_mov_b32_dpp v101, v84 row_shr:2 row_mask:0xf bank_mask:0xf
	v_mov_b32_dpp v94, v84 row_shr:3 row_mask:0xf bank_mask:0xf
	v_mov_b32_dpp v104, v85 row_shr:1 row_mask:0xf bank_mask:0xf
	v_mov_b32_dpp v102, v85 row_shr:2 row_mask:0xf bank_mask:0xf
	v_mov_b32_dpp v95, v85 row_shr:3 row_mask:0xf bank_mask:0xf
	v_mov_b32_dpp v92, v86 row_shr:1 row_mask:0xf bank_mask:0xf
	v_mov_b32_dpp v90, v86 row_shr:2 row_mask:0xf bank_mask:0xf
	v_mov_b32_dpp v88, v86 row_shr:3 row_mask:0xf bank_mask:0xf
	v_mov_b32_dpp v93, v87 row_shr:1 row_mask:0xf bank_mask:0xf
	v_mov_b32_dpp v91, v87 row_shr:2 row_mask:0xf bank_mask:0xf
	v_mov_b32_dpp v89, v87 row_shr:3 row_mask:0xf bank_mask:0xf
	s_and_saveexec_b64 s[22:23], s[2:3]
	s_cbranch_execz .LBB0_205
	ds_read_b128 v[106:109], v238 offset:4608
	ds_read_b128 v[110:113], v238 offset:3584
	ds_read_b128 v[166:169], v238 offset:2560
	v_cndmask_b32_e64 v105, v104, 0, s[8:9]
	ds_read_b128 v[170:173], v238 offset:1536
	ds_read_b128 v[174:177], v238 offset:512
	v_cndmask_b32_e64 v104, v103, 0, s[8:9]
	v_cndmask_b32_e64 v103, 0, v102, s[6:7]
	v_cndmask_b32_e64 v102, 0, v101, s[6:7]
	v_cndmask_b32_e64 v95, 0, v95, s[4:5]
	v_cndmask_b32_e64 v94, 0, v94, s[4:5]
	v_cndmask_b32_e64 v93, v93, 0, s[8:9]
	v_cndmask_b32_e64 v92, v92, 0, s[8:9]
	v_cndmask_b32_e64 v91, 0, v91, s[6:7]
	v_cndmask_b32_e64 v90, 0, v90, s[6:7]
	v_cndmask_b32_e64 v89, 0, v89, s[4:5]
	v_cndmask_b32_e64 v88, 0, v88, s[4:5]
	s_waitcnt lgkmcnt(0)
	v_pk_fma_f32 v[84:85], v[84:85], v[110:111], v[106:107]
	v_pk_fma_f32 v[86:87], v[86:87], v[112:113], v[108:109]
	v_pk_fma_f32 v[84:85], v[104:105], v[166:167], v[84:85]
	v_pk_fma_f32 v[86:87], v[92:93], v[168:169], v[86:87]
	v_pk_fma_f32 v[84:85], v[102:103], v[170:171], v[84:85]
	s_nop 0
	v_pk_fma_f32 v[84:85], v[94:95], v[174:175], v[84:85]
	v_pk_fma_f32 v[86:87], v[90:91], v[172:173], v[86:87]
	v_mul_f32_e32 v94, 0xbfb8aa3b, v85
	v_exp_f32_e32 v94, v94
	v_pk_fma_f32 v[86:87], v[88:89], v[176:177], v[86:87]
	v_add_f32_e32 v94, 1.0, v94
	v_rcp_f32_e32 v95, v94
	v_mul_f32_e32 v94, 0xbfb8aa3b, v84
	v_exp_f32_e32 v94, v94
	s_nop 0
	v_add_f32_e32 v94, 1.0, v94
	v_rcp_f32_e32 v94, v94
	s_nop 0
	v_pk_mul_f32 v[84:85], v[84:85], v[94:95]
	s_nop 0
	v_cvt_pk_bf16_f32 v84, v84, v85
	v_mul_f32_e32 v85, 0xbfb8aa3b, v87
	v_exp_f32_e32 v85, v85
	s_nop 0
	v_add_f32_e32 v85, 1.0, v85
	v_rcp_f32_e32 v89, v85
	v_mul_f32_e32 v85, 0xbfb8aa3b, v86
	v_exp_f32_e32 v85, v85
	s_nop 0
	v_add_f32_e32 v85, 1.0, v85
	v_rcp_f32_e32 v88, v85
	s_nop 0
	v_pk_mul_f32 v[86:87], v[86:87], v[88:89]
	s_nop 0
	v_cvt_pk_bf16_f32 v85, v86, v87
	global_store_dwordx2 v[96:97], v[84:85], off offset:256
;     __device__ __forceinline__ void operator()(const f32x4 (&acc)[2][2][4][2], const Unit& u, int wr, int wc, int fr, int fq, LAS unsigned char* hb) const {
;     ...
;             for (int m = 0; m < 4; ++m) { asm volatile("" ::: "memory"); __builtin_amdgcn_sched_barrier(0);
;                 const int q = 8 * ai + 4 * wr + m, prev = q > 0 ? q - 1 : 0; const int lr = ai * HALF + wr * 64 + m * 16 + fr, R = R0 + lr;
;                 const int Rc = R < 0 ? 0 : R; const int b = Rc / LL, p = Rc - b * LL;
;                 const bool ok = (lr >= H && R < TT);
;                 const unsigned ooff = ((unsigned)Rc * (unsigned)LDP + (unsigned)(OFF_XBC + ch0)) * 2u;
; #pragma unroll
;                 for (int bn = 0; bn < 4; ++bn) { const int bj = bn >> 1, n = bn & 1; const int co = bj * HALF + 4 * n;
;                     const unsigned woff = (unsigned)(ch0 + co) * 4u;
;                     const f32x4 w0 = *(const f32x4*)((const char*)cw + woff), w1 = *(const f32x4*)((const char*)cw + woff + XBCW * 4), w2 = *(const f32x4*)((const char*)cw + woff + 2 * XBCW * 4), w3 = *(const f32x4*)((const char*)cw + woff + 3 * XBCW * 4), bs = *(const f32x4*)((const char*)cb + woff);
;                     const LAS unsigned char* hp = hb + (prev * H * NCH + chl + co) * 2;
;                     const u32x2 q1 = *(const LAS u32x2*)(hp + hr1 * NCH * 2), q2 = *(const LAS u32x2*)(hp + hr2 * NCH * 2), q3 = *(const LAS u32x2*)(hp + hr3 * NCH * 2);
;                     const float h1[4] = {__builtin_bit_cast(float, q1.x << 16), __builtin_bit_cast(float, q1.x & 0xffff0000u), __builtin_bit_cast(float, q1.y << 16), __builtin_bit_cast(float, q1.y & 0xffff0000u)};
;                     const float h2[4] = {__builtin_bit_cast(float, q2.x << 16), __builtin_bit_cast(float, q2.x & 0xffff0000u), __builtin_bit_cast(float, q2.y << 16), __builtin_bit_cast(float, q2.y & 0xffff0000u)};
;                     const float h3[4] = {__builtin_bit_cast(float, q3.x << 16), __builtin_bit_cast(float, q3.x & 0xffff0000u), __builtin_bit_cast(float, q3.y << 16), __builtin_bit_cast(float, q3.y & 0xffff0000u)};
;                     const f32x4 gv = acc[ai][bj][m][n];
;                     float o[4];
; #pragma unroll
;                     for (int j = 0; j < 4; ++j) { const float g = gv[j];
;                         float g1 = dpp_row_shr<1>(h1[j], g), g2 = dpp_row_shr<2>(h2[j], g), g3 = dpp_row_shr<3>(h3[j], g);
.LBB0_205:
	s_or_b64 exec, exec, s[22:23]
	ds_read_b64 v[84:85], v98 offset:1288
	ds_read_b64 v[86:87], v99 offset:776
	ds_read_b64 v[98:99], v100 offset:264
	s_waitcnt lgkmcnt(0)
	v_lshlrev_b32_e32 v94, 16, v84
	v_and_b32_e32 v95, 0xffff0000, v84
	v_lshlrev_b32_e32 v88, 16, v85
	v_and_b32_e32 v89, 0xffff0000, v85
	v_lshlrev_b32_e32 v92, 16, v86
	v_and_b32_e32 v93, 0xffff0000, v86
	v_lshlrev_b32_e32 v86, 16, v87
	v_and_b32_e32 v87, 0xffff0000, v87
	v_lshlrev_b32_e32 v90, 16, v98
	v_and_b32_e32 v91, 0xffff0000, v98
	v_lshlrev_b32_e32 v84, 16, v99
	v_and_b32_e32 v85, 0xffff0000, v99
	v_mov_b32_dpp v94, v80 row_shr:1 row_mask:0xf bank_mask:0xf
	v_mov_b32_dpp v92, v80 row_shr:2 row_mask:0xf bank_mask:0xf
	v_mov_b32_dpp v90, v80 row_shr:3 row_mask:0xf bank_mask:0xf
	v_mov_b32_dpp v95, v81 row_shr:1 row_mask:0xf bank_mask:0xf
	v_mov_b32_dpp v93, v81 row_shr:2 row_mask:0xf bank_mask:0xf
	v_mov_b32_dpp v91, v81 row_shr:3 row_mask:0xf bank_mask:0xf
	v_mov_b32_dpp v88, v82 row_shr:1 row_mask:0xf bank_mask:0xf
	v_mov_b32_dpp v86, v82 row_shr:2 row_mask:0xf bank_mask:0xf
	v_mov_b32_dpp v84, v82 row_shr:3 row_mask:0xf bank_mask:0xf
	v_mov_b32_dpp v89, v83 row_shr:1 row_mask:0xf bank_mask:0xf
	v_mov_b32_dpp v87, v83 row_shr:2 row_mask:0xf bank_mask:0xf
	v_mov_b32_dpp v85, v83 row_shr:3 row_mask:0xf bank_mask:0xf
	s_and_saveexec_b64 s[22:23], s[2:3]
	s_cbranch_execz .LBB0_207
	ds_read_b128 v[98:101], v238 offset:4624
	ds_read_b128 v[102:105], v238 offset:3600
	ds_read_b128 v[106:109], v238 offset:2576
	v_cndmask_b32_e64 v95, v95, 0, s[8:9]
	ds_read_b128 v[110:113], v238 offset:1552
	s_nop 0
	ds_read_b128 v[166:169], v238 offset:528
	v_cndmask_b32_e64 v94, v94, 0, s[8:9]
	v_cndmask_b32_e64 v93, 0, v93, s[6:7]
	v_cndmask_b32_e64 v92, 0, v92, s[6:7]
	v_cndmask_b32_e64 v91, 0, v91, s[4:5]
	v_cndmask_b32_e64 v90, 0, v90, s[4:5]
	v_cndmask_b32_e64 v89, v89, 0, s[8:9]
	v_cndmask_b32_e64 v88, v88, 0, s[8:9]
	v_cndmask_b32_e64 v87, 0, v87, s[6:7]
	v_cndmask_b32_e64 v86, 0, v86, s[6:7]
	v_cndmask_b32_e64 v85, 0, v85, s[4:5]
	v_cndmask_b32_e64 v84, 0, v84, s[4:5]
	s_waitcnt lgkmcnt(0)
	v_pk_fma_f32 v[80:81], v[80:81], v[102:103], v[98:99]
	v_pk_fma_f32 v[82:83], v[82:83], v[104:105], v[100:101]
	v_pk_fma_f32 v[80:81], v[94:95], v[106:107], v[80:81]
	v_pk_fma_f32 v[82:83], v[88:89], v[108:109], v[82:83]
	v_pk_fma_f32 v[80:81], v[92:93], v[110:111], v[80:81]
	s_nop 0
	v_pk_fma_f32 v[80:81], v[90:91], v[166:167], v[80:81]
	v_pk_fma_f32 v[82:83], v[86:87], v[112:113], v[82:83]
	v_mul_f32_e32 v90, 0xbfb8aa3b, v81
	v_exp_f32_e32 v90, v90
	v_pk_fma_f32 v[82:83], v[84:85], v[168:169], v[82:83]
	v_add_f32_e32 v90, 1.0, v90
	v_rcp_f32_e32 v91, v90
	v_mul_f32_e32 v90, 0xbfb8aa3b, v80
	v_exp_f32_e32 v90, v90
	s_nop 0
	v_add_f32_e32 v90, 1.0, v90
	v_rcp_f32_e32 v90, v90
	s_nop 0
	v_pk_mul_f32 v[80:81], v[80:81], v[90:91]
	s_nop 0
	v_cvt_pk_bf16_f32 v80, v80, v81
	v_mul_f32_e32 v81, 0xbfb8aa3b, v83
	v_exp_f32_e32 v81, v81
	s_nop 0
	v_add_f32_e32 v81, 1.0, v81
	v_rcp_f32_e32 v85, v81
	v_mul_f32_e32 v81, 0xbfb8aa3b, v82
	v_exp_f32_e32 v81, v81
	s_nop 0
	v_add_f32_e32 v81, 1.0, v81
	v_rcp_f32_e32 v84, v81
	s_nop 0
	v_pk_mul_f32 v[82:83], v[82:83], v[84:85]
	s_nop 0
	v_cvt_pk_bf16_f32 v81, v82, v83
	global_store_dwordx2 v[96:97], v[80:81], off offset:264
.LBB0_207:
	s_or_b64 exec, exec, s[22:23]
	v_add_u32_e32 v80, 48, v161
	v_add_u32_e32 v81, s17, v80
	v_max_i32_e32 v82, 0, v81
	v_mul_hi_u32 v83, v82, s56
	v_lshrrev_b32_e32 v83, 11, v83
	v_cmp_lt_i32_e32 vcc, 2, v80
	v_mul_lo_u32 v80, v82, s51
	v_mul_u32_u24_e32 v83, 0x1010, v83
	v_add_lshl_u32 v136, v80, v164, 1
	v_add_u32_e32 v80, s40, v165
	v_sub_u32_e32 v83, v82, v83
	v_cmp_gt_i32_e64 s[4:5], s50, v81
	v_lshl_add_u32 v82, v80, 1, s53
	s_and_b64 s[2:3], vcc, s[4:5]
	v_cmp_eq_u32_e64 s[8:9], 0, v83
	v_cmp_lt_u32_e64 s[6:7], 1, v83
	v_cmp_lt_u32_e64 s[4:5], 2, v83
	v_add_u32_e32 v83, v82, v163
	ds_read_b64 v[80:81], v82 offset:1024
	v_add_u32_e32 v84, v82, v162
	ds_read_b64 v[98:99], v83 offset:512
	ds_read_b64 v[100:101], v84
	v_readlane_b32 s22, v237, 58
	v_readlane_b32 s23, v237, 59
	s_waitcnt lgkmcnt(0)
	v_lshlrev_b32_e32 v95, 16, v80
	v_and_b32_e32 v96, 0xffff0000, v80
	v_lshlrev_b32_e32 v89, 16, v81
	v_and_b32_e32 v90, 0xffff0000, v81
	v_lshlrev_b32_e32 v93, 16, v98
	v_and_b32_e32 v94, 0xffff0000, v98
	v_lshlrev_b32_e32 v87, 16, v99
	v_and_b32_e32 v88, 0xffff0000, v99
	v_lshlrev_b32_e32 v91, 16, v100
	v_and_b32_e32 v92, 0xffff0000, v100
	v_lshlrev_b32_e32 v85, 16, v101
	v_and_b32_e32 v86, 0xffff0000, v101
	v_mov_b32_dpp v95, v76 row_shr:1 row_mask:0xf bank_mask:0xf
	v_mov_b32_dpp v93, v76 row_shr:2 row_mask:0xf bank_mask:0xf
	v_mov_b32_dpp v91, v76 row_shr:3 row_mask:0xf bank_mask:0xf
	v_mov_b32_dpp v96, v77 row_shr:1 row_mask:0xf bank_mask:0xf
	v_mov_b32_dpp v94, v77 row_shr:2 row_mask:0xf bank_mask:0xf
	v_mov_b32_dpp v92, v77 row_shr:3 row_mask:0xf bank_mask:0xf
	v_mov_b32_dpp v89, v78 row_shr:1 row_mask:0xf bank_mask:0xf
	v_mov_b32_dpp v87, v78 row_shr:2 row_mask:0xf bank_mask:0xf
	v_mov_b32_dpp v85, v78 row_shr:3 row_mask:0xf bank_mask:0xf
	v_mov_b32_dpp v90, v79 row_shr:1 row_mask:0xf bank_mask:0xf
	v_mov_b32_dpp v88, v79 row_shr:2 row_mask:0xf bank_mask:0xf
	v_mov_b32_dpp v86, v79 row_shr:3 row_mask:0xf bank_mask:0xf
	v_lshl_add_u64 v[80:81], s[22:23], 0, v[136:137]
	s_and_saveexec_b64 s[22:23], s[2:3]
	s_cbranch_execz .LBB0_209
;     __device__ __forceinline__ void operator()(const f32x4 (&acc)[2][2][4][2], const Unit& u, int wr, int wc, int fr, int fq, LAS unsigned char* hb) const {
;     ...
;             for (int m = 0; m < 4; ++m) { asm volatile("" ::: "memory"); __builtin_amdgcn_sched_barrier(0);
;                 const int q = 8 * ai + 4 * wr + m, prev = q > 0 ? q - 1 : 0; const int lr = ai * HALF + wr * 64 + m * 16 + fr, R = R0 + lr;
;                 const int Rc = R < 0 ? 0 : R; const int b = Rc / LL, p = Rc - b * LL;
;                 const bool ok = (lr >= H && R < TT);
;                 const unsigned ooff = ((unsigned)Rc * (unsigned)LDP + (unsigned)(OFF_XBC + ch0)) * 2u;
; #pragma unroll
;                 for (int bn = 0; bn < 4; ++bn) { const int bj = bn >> 1, n = bn & 1; const int co = bj * HALF + 4 * n;
;                     const unsigned woff = (unsigned)(ch0 + co) * 4u;
;                     const f32x4 w0 = *(const f32x4*)((const char*)cw + woff), w1 = *(const f32x4*)((const char*)cw + woff + XBCW * 4), w2 = *(const f32x4*)((const char*)cw + woff + 2 * XBCW * 4), w3 = *(const f32x4*)((const char*)cw + woff + 3 * XBCW * 4), bs = *(const f32x4*)((const char*)cb + woff);
;                     const LAS unsigned char* hp = hb + (prev * H * NCH + chl + co) * 2;
;                     const u32x2 q1 = *(const LAS u32x2*)(hp + hr1 * NCH * 2), q2 = *(const LAS u32x2*)(hp + hr2 * NCH * 2), q3 = *(const LAS u32x2*)(hp + hr3 * NCH * 2);
;                     const float h1[4] = {__builtin_bit_cast(float, q1.x << 16), __builtin_bit_cast(float, q1.x & 0xffff0000u), __builtin_bit_cast(float, q1.y << 16), __builtin_bit_cast(float, q1.y & 0xffff0000u)};
;                     const float h2[4] = {__builtin_bit_cast(float, q2.x << 16), __builtin_bit_cast(float, q2.x & 0xffff0000u), __builtin_bit_cast(float, q2.y << 16), __builtin_bit_cast(float, q2.y & 0xffff0000u)};
;                     const float h3[4] = {__builtin_bit_cast(float, q3.x << 16), __builtin_bit_cast(float, q3.x & 0xffff0000u), __builtin_bit_cast(float, q3.y << 16), __builtin_bit_cast(float, q3.y & 0xffff0000u)};
;                     const f32x4 gv = acc[ai][bj][m][n];
;                     float o[4];
; #pragma unroll
;                     for (int j = 0; j < 4; ++j) { const float g = gv[j];
;                         float g1 = dpp_row_shr<1>(h1[j], g), g2 = dpp_row_shr<2>(h2[j], g), g3 = dpp_row_shr<3>(h3[j], g);
	ds_read_b128 v[98:101], v238 offset:4096
	ds_read_b128 v[102:105], v238 offset:3072
	ds_read_b128 v[106:109], v238 offset:2048
	v_cndmask_b32_e64 v97, v96, 0, s[8:9]
	ds_read_b128 v[110:113], v238 offset:1024
	s_nop 0
	ds_read_b128 v[166:169], v238
	v_cndmask_b32_e64 v96, v95, 0, s[8:9]
	v_cndmask_b32_e64 v95, 0, v94, s[6:7]
	v_cndmask_b32_e64 v94, 0, v93, s[6:7]
	v_cndmask_b32_e64 v93, 0, v92, s[4:5]
	v_cndmask_b32_e64 v92, 0, v91, s[4:5]
	s_waitcnt lgkmcnt(0)
	v_pk_fma_f32 v[76:77], v[76:77], v[102:103], v[98:99]
	v_pk_fma_f32 v[78:79], v[78:79], v[104:105], v[100:101]
	v_pk_fma_f32 v[76:77], v[96:97], v[106:107], v[76:77]
	s_nop 0
	v_pk_fma_f32 v[76:77], v[94:95], v[110:111], v[76:77]
	s_nop 0
	v_pk_fma_f32 v[76:77], v[92:93], v[166:167], v[76:77]
	s_nop 0
	v_mul_f32_e32 v91, 0xbfb8aa3b, v77
	v_exp_f32_e32 v91, v91
	s_nop 0
	v_add_f32_e32 v91, 1.0, v91
	v_rcp_f32_e32 v93, v91
	v_mul_f32_e32 v91, 0xbfb8aa3b, v76
	v_exp_f32_e32 v91, v91
	s_nop 0
	v_add_f32_e32 v91, 1.0, v91
	v_rcp_f32_e32 v92, v91
	v_cndmask_b32_e64 v91, v90, 0, s[8:9]
	v_cndmask_b32_e64 v90, v89, 0, s[8:9]
	v_pk_fma_f32 v[78:79], v[90:91], v[108:109], v[78:79]
	v_cndmask_b32_e64 v89, 0, v88, s[6:7]
	v_cndmask_b32_e64 v88, 0, v87, s[6:7]
	v_pk_fma_f32 v[78:79], v[88:89], v[112:113], v[78:79]
	v_cndmask_b32_e64 v87, 0, v86, s[4:5]
	v_cndmask_b32_e64 v86, 0, v85, s[4:5]
	v_pk_mul_f32 v[76:77], v[76:77], v[92:93]
	v_pk_fma_f32 v[78:79], v[86:87], v[168:169], v[78:79]
	v_cvt_pk_bf16_f32 v76, v76, v77
	v_mul_f32_e32 v77, 0xbfb8aa3b, v79
	v_exp_f32_e32 v77, v77
	s_nop 0
	v_add_f32_e32 v77, 1.0, v77
	v_rcp_f32_e32 v87, v77
	v_mul_f32_e32 v77, 0xbfb8aa3b, v78
	v_exp_f32_e32 v77, v77
	s_nop 0
	v_add_f32_e32 v77, 1.0, v77
	v_rcp_f32_e32 v86, v77
	s_nop 0
	v_pk_mul_f32 v[78:79], v[78:79], v[86:87]
	s_nop 0
	v_cvt_pk_bf16_f32 v77, v78, v79
	global_store_dwordx2 v[80:81], v[76:77], off
.LBB0_209:
	s_or_b64 exec, exec, s[22:23]
	ds_read_b64 v[76:77], v82 offset:1032
	ds_read_b64 v[78:79], v83 offset:520
	ds_read_b64 v[94:95], v84 offset:8
	s_waitcnt lgkmcnt(0)
	v_lshlrev_b32_e32 v91, 16, v76
	v_and_b32_e32 v92, 0xffff0000, v76
	v_lshlrev_b32_e32 v85, 16, v77
	v_and_b32_e32 v86, 0xffff0000, v77
	v_lshlrev_b32_e32 v89, 16, v78
	v_and_b32_e32 v90, 0xffff0000, v78
	v_lshlrev_b32_e32 v78, 16, v79
	v_and_b32_e32 v79, 0xffff0000, v79
	v_lshlrev_b32_e32 v87, 16, v94
	v_and_b32_e32 v88, 0xffff0000, v94
	v_lshlrev_b32_e32 v76, 16, v95
	v_and_b32_e32 v77, 0xffff0000, v95
	v_mov_b32_dpp v91, v72 row_shr:1 row_mask:0xf bank_mask:0xf
	v_mov_b32_dpp v89, v72 row_shr:2 row_mask:0xf bank_mask:0xf
	v_mov_b32_dpp v87, v72 row_shr:3 row_mask:0xf bank_mask:0xf
	v_mov_b32_dpp v92, v73 row_shr:1 row_mask:0xf bank_mask:0xf
	v_mov_b32_dpp v90, v73 row_shr:2 row_mask:0xf bank_mask:0xf
	v_mov_b32_dpp v88, v73 row_shr:3 row_mask:0xf bank_mask:0xf
	v_mov_b32_dpp v85, v74 row_shr:1 row_mask:0xf bank_mask:0xf
	v_mov_b32_dpp v78, v74 row_shr:2 row_mask:0xf bank_mask:0xf
	v_mov_b32_dpp v76, v74 row_shr:3 row_mask:0xf bank_mask:0xf
	v_mov_b32_dpp v86, v75 row_shr:1 row_mask:0xf bank_mask:0xf
	v_mov_b32_dpp v79, v75 row_shr:2 row_mask:0xf bank_mask:0xf
	v_mov_b32_dpp v77, v75 row_shr:3 row_mask:0xf bank_mask:0xf
	s_and_saveexec_b64 s[22:23], s[2:3]
	s_cbranch_execz .LBB0_211
	ds_read_b128 v[94:97], v238 offset:4112
	ds_read_b128 v[98:101], v238 offset:3088
	ds_read_b128 v[102:105], v238 offset:2064
	v_cndmask_b32_e64 v93, v92, 0, s[8:9]
	ds_read_b128 v[106:109], v238 offset:1040
	s_nop 0
	ds_read_b128 v[110:113], v238 offset:16
	v_cndmask_b32_e64 v92, v91, 0, s[8:9]
	v_cndmask_b32_e64 v91, 0, v90, s[6:7]
	v_cndmask_b32_e64 v90, 0, v89, s[6:7]
	v_cndmask_b32_e64 v89, 0, v88, s[4:5]
	v_cndmask_b32_e64 v88, 0, v87, s[4:5]
	v_cndmask_b32_e64 v79, 0, v79, s[6:7]
	v_cndmask_b32_e64 v78, 0, v78, s[6:7]
	v_cndmask_b32_e64 v77, 0, v77, s[4:5]
	v_cndmask_b32_e64 v76, 0, v76, s[4:5]
	s_waitcnt lgkmcnt(0)
	v_pk_fma_f32 v[72:73], v[72:73], v[98:99], v[94:95]
	v_pk_fma_f32 v[74:75], v[74:75], v[100:101], v[96:97]
	v_pk_fma_f32 v[72:73], v[92:93], v[102:103], v[72:73]
	s_nop 0
	v_pk_fma_f32 v[72:73], v[90:91], v[106:107], v[72:73]
	s_nop 0
	v_pk_fma_f32 v[72:73], v[88:89], v[110:111], v[72:73]
	s_nop 0
	v_mul_f32_e32 v87, 0xbfb8aa3b, v73
	v_exp_f32_e32 v87, v87
	s_nop 0
	v_add_f32_e32 v87, 1.0, v87
	v_rcp_f32_e32 v89, v87
	v_mul_f32_e32 v87, 0xbfb8aa3b, v72
	v_exp_f32_e32 v87, v87
	s_nop 0
	v_add_f32_e32 v87, 1.0, v87
	v_rcp_f32_e32 v88, v87
	v_cndmask_b32_e64 v87, v86, 0, s[8:9]
	v_cndmask_b32_e64 v86, v85, 0, s[8:9]
	v_pk_fma_f32 v[74:75], v[86:87], v[104:105], v[74:75]
	v_pk_mul_f32 v[72:73], v[72:73], v[88:89]
	v_pk_fma_f32 v[74:75], v[78:79], v[108:109], v[74:75]
	v_cvt_pk_bf16_f32 v72, v72, v73
	v_pk_fma_f32 v[74:75], v[76:77], v[112:113], v[74:75]
	s_nop 0
	v_mul_f32_e32 v73, 0xbfb8aa3b, v75
	v_exp_f32_e32 v73, v73
	s_nop 0
	v_add_f32_e32 v73, 1.0, v73
	v_rcp_f32_e32 v77, v73
	v_mul_f32_e32 v73, 0xbfb8aa3b, v74
	v_exp_f32_e32 v73, v73
	s_nop 0
	v_add_f32_e32 v73, 1.0, v73
	v_rcp_f32_e32 v76, v73
	s_nop 0
	v_pk_mul_f32 v[74:75], v[74:75], v[76:77]
	s_nop 0
	v_cvt_pk_bf16_f32 v73, v74, v75
	global_store_dwordx2 v[80:81], v[72:73], off offset:8
;     __device__ __forceinline__ void operator()(const f32x4 (&acc)[2][2][4][2], const Unit& u, int wr, int wc, int fr, int fq, LAS unsigned char* hb) const {
;     ...
;             for (int m = 0; m < 4; ++m) { asm volatile("" ::: "memory"); __builtin_amdgcn_sched_barrier(0);
;                 const int q = 8 * ai + 4 * wr + m, prev = q > 0 ? q - 1 : 0; const int lr = ai * HALF + wr * 64 + m * 16 + fr, R = R0 + lr;
;                 const int Rc = R < 0 ? 0 : R; const int b = Rc / LL, p = Rc - b * LL;
;                 const bool ok = (lr >= H && R < TT);
;                 const unsigned ooff = ((unsigned)Rc * (unsigned)LDP + (unsigned)(OFF_XBC + ch0)) * 2u;
; #pragma unroll
;                 for (int bn = 0; bn < 4; ++bn) { const int bj = bn >> 1, n = bn & 1; const int co = bj * HALF + 4 * n;
;                     const unsigned woff = (unsigned)(ch0 + co) * 4u;
;                     const f32x4 w0 = *(const f32x4*)((const char*)cw + woff), w1 = *(const f32x4*)((const char*)cw + woff + XBCW * 4), w2 = *(const f32x4*)((const char*)cw + woff + 2 * XBCW * 4), w3 = *(const f32x4*)((const char*)cw + woff + 3 * XBCW * 4), bs = *(const f32x4*)((const char*)cb + woff);
;                     const LAS unsigned char* hp = hb + (prev * H * NCH + chl + co) * 2;
;                     const u32x2 q1 = *(const LAS u32x2*)(hp + hr1 * NCH * 2), q2 = *(const LAS u32x2*)(hp + hr2 * NCH * 2), q3 = *(const LAS u32x2*)(hp + hr3 * NCH * 2);
;                     const float h1[4] = {__builtin_bit_cast(float, q1.x << 16), __builtin_bit_cast(float, q1.x & 0xffff0000u), __builtin_bit_cast(float, q1.y << 16), __builtin_bit_cast(float, q1.y & 0xffff0000u)};
;                     const float h2[4] = {__builtin_bit_cast(float, q2.x << 16), __builtin_bit_cast(float, q2.x & 0xffff0000u), __builtin_bit_cast(float, q2.y << 16), __builtin_bit_cast(float, q2.y & 0xffff0000u)};
;                     const float h3[4] = {__builtin_bit_cast(float, q3.x << 16), __builtin_bit_cast(float, q3.x & 0xffff0000u), __builtin_bit_cast(float, q3.y << 16), __builtin_bit_cast(float, q3.y & 0xffff0000u)};
;                     const f32x4 gv = acc[ai][bj][m][n];
;                     float o[4];
; #pragma unroll
;                     for (int j = 0; j < 4; ++j) { const float g = gv[j];
;                         float g1 = dpp_row_shr<1>(h1[j], g), g2 = dpp_row_shr<2>(h2[j], g), g3 = dpp_row_shr<3>(h3[j], g);
.LBB0_211:
	s_or_b64 exec, exec, s[22:23]
	ds_read_b64 v[72:73], v82 offset:1280
	ds_read_b64 v[74:75], v83 offset:768
	ds_read_b64 v[90:91], v84 offset:256
	s_waitcnt lgkmcnt(0)
	v_lshlrev_b32_e32 v87, 16, v72
	v_and_b32_e32 v88, 0xffff0000, v72
	v_lshlrev_b32_e32 v76, 16, v73
	v_and_b32_e32 v77, 0xffff0000, v73
	v_lshlrev_b32_e32 v85, 16, v74
	v_and_b32_e32 v86, 0xffff0000, v74
	v_lshlrev_b32_e32 v74, 16, v75
	v_and_b32_e32 v75, 0xffff0000, v75
	v_lshlrev_b32_e32 v78, 16, v90
	v_and_b32_e32 v79, 0xffff0000, v90
	v_lshlrev_b32_e32 v72, 16, v91
	v_and_b32_e32 v73, 0xffff0000, v91
	v_mov_b32_dpp v87, v68 row_shr:1 row_mask:0xf bank_mask:0xf
	v_mov_b32_dpp v85, v68 row_shr:2 row_mask:0xf bank_mask:0xf
	v_mov_b32_dpp v78, v68 row_shr:3 row_mask:0xf bank_mask:0xf
	v_mov_b32_dpp v88, v69 row_shr:1 row_mask:0xf bank_mask:0xf
	v_mov_b32_dpp v86, v69 row_shr:2 row_mask:0xf bank_mask:0xf
	v_mov_b32_dpp v79, v69 row_shr:3 row_mask:0xf bank_mask:0xf
	v_mov_b32_dpp v76, v70 row_shr:1 row_mask:0xf bank_mask:0xf
	v_mov_b32_dpp v74, v70 row_shr:2 row_mask:0xf bank_mask:0xf
	v_mov_b32_dpp v72, v70 row_shr:3 row_mask:0xf bank_mask:0xf
	v_mov_b32_dpp v77, v71 row_shr:1 row_mask:0xf bank_mask:0xf
	v_mov_b32_dpp v75, v71 row_shr:2 row_mask:0xf bank_mask:0xf
	v_mov_b32_dpp v73, v71 row_shr:3 row_mask:0xf bank_mask:0xf
	s_and_saveexec_b64 s[22:23], s[2:3]
	s_cbranch_execz .LBB0_213
	ds_read_b128 v[90:93], v238 offset:4608
	ds_read_b128 v[94:97], v238 offset:3584
	ds_read_b128 v[98:101], v238 offset:2560
	v_cndmask_b32_e64 v89, v88, 0, s[8:9]
	ds_read_b128 v[102:105], v238 offset:1536
	s_nop 0
	ds_read_b128 v[106:109], v238 offset:512
	v_cndmask_b32_e64 v88, v87, 0, s[8:9]
	v_cndmask_b32_e64 v87, 0, v86, s[6:7]
	v_cndmask_b32_e64 v86, 0, v85, s[6:7]
	v_cndmask_b32_e64 v79, 0, v79, s[4:5]
	v_cndmask_b32_e64 v78, 0, v78, s[4:5]
	v_cndmask_b32_e64 v77, v77, 0, s[8:9]
	v_cndmask_b32_e64 v76, v76, 0, s[8:9]
	v_cndmask_b32_e64 v75, 0, v75, s[6:7]
	v_cndmask_b32_e64 v74, 0, v74, s[6:7]
	v_cndmask_b32_e64 v73, 0, v73, s[4:5]
	v_cndmask_b32_e64 v72, 0, v72, s[4:5]
	s_waitcnt lgkmcnt(0)
	v_pk_fma_f32 v[68:69], v[68:69], v[94:95], v[90:91]
	v_pk_fma_f32 v[70:71], v[70:71], v[96:97], v[92:93]
	v_pk_fma_f32 v[68:69], v[88:89], v[98:99], v[68:69]
	v_pk_fma_f32 v[70:71], v[76:77], v[100:101], v[70:71]
	v_pk_fma_f32 v[68:69], v[86:87], v[102:103], v[68:69]
	s_nop 0
	v_pk_fma_f32 v[68:69], v[78:79], v[106:107], v[68:69]
	v_pk_fma_f32 v[70:71], v[74:75], v[104:105], v[70:71]
	v_mul_f32_e32 v78, 0xbfb8aa3b, v69
	v_exp_f32_e32 v78, v78
	v_pk_fma_f32 v[70:71], v[72:73], v[108:109], v[70:71]
	v_add_f32_e32 v78, 1.0, v78
	v_rcp_f32_e32 v79, v78
	v_mul_f32_e32 v78, 0xbfb8aa3b, v68
	v_exp_f32_e32 v78, v78
	s_nop 0
	v_add_f32_e32 v78, 1.0, v78
	v_rcp_f32_e32 v78, v78
	s_nop 0
	v_pk_mul_f32 v[68:69], v[68:69], v[78:79]
	s_nop 0
	v_cvt_pk_bf16_f32 v68, v68, v69
	v_mul_f32_e32 v69, 0xbfb8aa3b, v71
	v_exp_f32_e32 v69, v69
	s_nop 0
	v_add_f32_e32 v69, 1.0, v69
	v_rcp_f32_e32 v73, v69
	v_mul_f32_e32 v69, 0xbfb8aa3b, v70
	v_exp_f32_e32 v69, v69
	s_nop 0
	v_add_f32_e32 v69, 1.0, v69
	v_rcp_f32_e32 v72, v69
	s_nop 0
	v_pk_mul_f32 v[70:71], v[70:71], v[72:73]
	s_nop 0
	v_cvt_pk_bf16_f32 v69, v70, v71
	global_store_dwordx2 v[80:81], v[68:69], off offset:256
.LBB0_213:
	s_or_b64 exec, exec, s[22:23]
	ds_read_b64 v[68:69], v82 offset:1288
	ds_read_b64 v[70:71], v83 offset:776
	ds_read_b64 v[82:83], v84 offset:264
	s_waitcnt lgkmcnt(0)
	v_lshlrev_b32_e32 v78, 16, v68
	v_and_b32_e32 v79, 0xffff0000, v68
	v_lshlrev_b32_e32 v72, 16, v69
	v_and_b32_e32 v73, 0xffff0000, v69
	v_lshlrev_b32_e32 v76, 16, v70
	v_and_b32_e32 v77, 0xffff0000, v70
	v_lshlrev_b32_e32 v70, 16, v71
	v_and_b32_e32 v71, 0xffff0000, v71
	v_lshlrev_b32_e32 v74, 16, v82
	v_and_b32_e32 v75, 0xffff0000, v82
	v_lshlrev_b32_e32 v68, 16, v83
	v_and_b32_e32 v69, 0xffff0000, v83
	v_mov_b32_dpp v78, v64 row_shr:1 row_mask:0xf bank_mask:0xf
	v_mov_b32_dpp v76, v64 row_shr:2 row_mask:0xf bank_mask:0xf
	v_mov_b32_dpp v74, v64 row_shr:3 row_mask:0xf bank_mask:0xf
	v_mov_b32_dpp v79, v65 row_shr:1 row_mask:0xf bank_mask:0xf
	v_mov_b32_dpp v77, v65 row_shr:2 row_mask:0xf bank_mask:0xf
	v_mov_b32_dpp v75, v65 row_shr:3 row_mask:0xf bank_mask:0xf
	v_mov_b32_dpp v72, v66 row_shr:1 row_mask:0xf bank_mask:0xf
	v_mov_b32_dpp v70, v66 row_shr:2 row_mask:0xf bank_mask:0xf
	v_mov_b32_dpp v68, v66 row_shr:3 row_mask:0xf bank_mask:0xf
	v_mov_b32_dpp v73, v67 row_shr:1 row_mask:0xf bank_mask:0xf
	v_mov_b32_dpp v71, v67 row_shr:2 row_mask:0xf bank_mask:0xf
	v_mov_b32_dpp v69, v67 row_shr:3 row_mask:0xf bank_mask:0xf
	s_and_saveexec_b64 s[22:23], s[2:3]
	s_cbranch_execz .LBB0_215
	ds_read_b128 v[82:85], v238 offset:4624
	ds_read_b128 v[86:89], v238 offset:3600
	ds_read_b128 v[90:93], v238 offset:2576
	v_cndmask_b32_e64 v79, v79, 0, s[8:9]
	ds_read_b128 v[94:97], v238 offset:1552
	s_nop 0
	ds_read_b128 v[98:101], v238 offset:528
	v_cndmask_b32_e64 v78, v78, 0, s[8:9]
	v_cndmask_b32_e64 v77, 0, v77, s[6:7]
	v_cndmask_b32_e64 v76, 0, v76, s[6:7]
	v_cndmask_b32_e64 v75, 0, v75, s[4:5]
	v_cndmask_b32_e64 v74, 0, v74, s[4:5]
	v_cndmask_b32_e64 v73, v73, 0, s[8:9]
	v_cndmask_b32_e64 v72, v72, 0, s[8:9]
	v_cndmask_b32_e64 v71, 0, v71, s[6:7]
	v_cndmask_b32_e64 v70, 0, v70, s[6:7]
	v_cndmask_b32_e64 v69, 0, v69, s[4:5]
	v_cndmask_b32_e64 v68, 0, v68, s[4:5]
	s_waitcnt lgkmcnt(0)
	v_pk_fma_f32 v[64:65], v[64:65], v[86:87], v[82:83]
	v_pk_fma_f32 v[66:67], v[66:67], v[88:89], v[84:85]
	v_pk_fma_f32 v[64:65], v[78:79], v[90:91], v[64:65]
	v_pk_fma_f32 v[66:67], v[72:73], v[92:93], v[66:67]
	v_pk_fma_f32 v[64:65], v[76:77], v[94:95], v[64:65]
	s_nop 0
	v_pk_fma_f32 v[64:65], v[74:75], v[98:99], v[64:65]
	v_pk_fma_f32 v[66:67], v[70:71], v[96:97], v[66:67]
	v_mul_f32_e32 v74, 0xbfb8aa3b, v65
	v_exp_f32_e32 v74, v74
	v_pk_fma_f32 v[66:67], v[68:69], v[100:101], v[66:67]
	v_add_f32_e32 v74, 1.0, v74
	v_rcp_f32_e32 v75, v74
	v_mul_f32_e32 v74, 0xbfb8aa3b, v64
	v_exp_f32_e32 v74, v74
	s_nop 0
	v_add_f32_e32 v74, 1.0, v74
	v_rcp_f32_e32 v74, v74
	s_nop 0
	v_pk_mul_f32 v[64:65], v[64:65], v[74:75]
	s_nop 0
	v_cvt_pk_bf16_f32 v64, v64, v65
	v_mul_f32_e32 v65, 0xbfb8aa3b, v67
	v_exp_f32_e32 v65, v65
	s_nop 0
	v_add_f32_e32 v65, 1.0, v65
	v_rcp_f32_e32 v69, v65
	v_mul_f32_e32 v65, 0xbfb8aa3b, v66
	v_exp_f32_e32 v65, v65
	s_nop 0
	v_add_f32_e32 v65, 1.0, v65
	v_rcp_f32_e32 v68, v65
	s_nop 0
	v_pk_mul_f32 v[66:67], v[66:67], v[68:69]
	s_nop 0
	v_cvt_pk_bf16_f32 v65, v66, v67
	global_store_dwordx2 v[80:81], v[64:65], off offset:264
;     __device__ __forceinline__ void operator()(const f32x4 (&acc)[2][2][4][2], const Unit& u, int wr, int wc, int fr, int fq, LAS unsigned char* hb) const {
;     ...
;             for (int m = 0; m < 4; ++m) { asm volatile("" ::: "memory"); __builtin_amdgcn_sched_barrier(0);
;                 const int q = 8 * ai + 4 * wr + m, prev = q > 0 ? q - 1 : 0; const int lr = ai * HALF + wr * 64 + m * 16 + fr, R = R0 + lr;
;                 const int Rc = R < 0 ? 0 : R; const int b = Rc / LL, p = Rc - b * LL;
;                 const bool ok = (lr >= H && R < TT);
;                 const unsigned ooff = ((unsigned)Rc * (unsigned)LDP + (unsigned)(OFF_XBC + ch0)) * 2u;
; #pragma unroll
;                 for (int bn = 0; bn < 4; ++bn) { const int bj = bn >> 1, n = bn & 1; const int co = bj * HALF + 4 * n;
;                     const unsigned woff = (unsigned)(ch0 + co) * 4u;
;                     const f32x4 w0 = *(const f32x4*)((const char*)cw + woff), w1 = *(const f32x4*)((const char*)cw + woff + XBCW * 4), w2 = *(const f32x4*)((const char*)cw + woff + 2 * XBCW * 4), w3 = *(const f32x4*)((const char*)cw + woff + 3 * XBCW * 4), bs = *(const f32x4*)((const char*)cb + woff);
;                     const LAS unsigned char* hp = hb + (prev * H * NCH + chl + co) * 2;
;                     const u32x2 q1 = *(const LAS u32x2*)(hp + hr1 * NCH * 2), q2 = *(const LAS u32x2*)(hp + hr2 * NCH * 2), q3 = *(const LAS u32x2*)(hp + hr3 * NCH * 2);
;                     const float h1[4] = {__builtin_bit_cast(float, q1.x << 16), __builtin_bit_cast(float, q1.x & 0xffff0000u), __builtin_bit_cast(float, q1.y << 16), __builtin_bit_cast(float, q1.y & 0xffff0000u)};
;                     const float h2[4] = {__builtin_bit_cast(float, q2.x << 16), __builtin_bit_cast(float, q2.x & 0xffff0000u), __builtin_bit_cast(float, q2.y << 16), __builtin_bit_cast(float, q2.y & 0xffff0000u)};
;                     const float h3[4] = {__builtin_bit_cast(float, q3.x << 16), __builtin_bit_cast(float, q3.x & 0xffff0000u), __builtin_bit_cast(float, q3.y << 16), __builtin_bit_cast(float, q3.y & 0xffff0000u)};
;                     const f32x4 gv = acc[ai][bj][m][n];
;                     float o[4];
; #pragma unroll
;                     for (int j = 0; j < 4; ++j) { const float g = gv[j];
;                         float g1 = dpp_row_shr<1>(h1[j], g), g2 = dpp_row_shr<2>(h2[j], g), g3 = dpp_row_shr<3>(h3[j], g);
.LBB0_215:
	s_or_b64 exec, exec, s[22:23]
	v_add_u32_e32 v64, 0x80, v161
	v_add_u32_e32 v65, s17, v64
	v_max_i32_e32 v66, 0, v65
	v_mul_hi_u32 v67, v66, s56
	v_lshrrev_b32_e32 v67, 11, v67
	v_cmp_lt_i32_e32 vcc, 2, v64
	v_mul_lo_u32 v64, v66, s51
	v_mul_u32_u24_e32 v67, 0x1010, v67
	v_add_lshl_u32 v136, v64, v164, 1
	v_add_u32_e32 v64, s41, v165
	v_sub_u32_e32 v67, v66, v67
	v_cmp_gt_i32_e64 s[4:5], s50, v65
	v_lshl_add_u32 v66, v64, 1, s53
	s_and_b64 s[2:3], vcc, s[4:5]
	v_cmp_eq_u32_e64 s[8:9], 0, v67
	v_cmp_lt_u32_e64 s[6:7], 1, v67
	v_cmp_lt_u32_e64 s[4:5], 2, v67
	v_add_u32_e32 v67, v66, v163
	ds_read_b64 v[64:65], v66 offset:1024
	v_add_u32_e32 v68, v66, v162
	ds_read_b64 v[82:83], v67 offset:512
	ds_read_b64 v[84:85], v68
	v_readlane_b32 s22, v237, 58
	v_readlane_b32 s23, v237, 59
	s_waitcnt lgkmcnt(0)
	v_lshlrev_b32_e32 v79, 16, v64
	v_and_b32_e32 v80, 0xffff0000, v64
	v_lshlrev_b32_e32 v73, 16, v65
	v_and_b32_e32 v74, 0xffff0000, v65
	v_lshlrev_b32_e32 v77, 16, v82
	v_and_b32_e32 v78, 0xffff0000, v82
	v_lshlrev_b32_e32 v71, 16, v83
	v_and_b32_e32 v72, 0xffff0000, v83
	v_lshlrev_b32_e32 v75, 16, v84
	v_and_b32_e32 v76, 0xffff0000, v84
	v_lshlrev_b32_e32 v69, 16, v85
	v_and_b32_e32 v70, 0xffff0000, v85
	v_mov_b32_dpp v79, v60 row_shr:1 row_mask:0xf bank_mask:0xf
	v_mov_b32_dpp v77, v60 row_shr:2 row_mask:0xf bank_mask:0xf
	v_mov_b32_dpp v75, v60 row_shr:3 row_mask:0xf bank_mask:0xf
	v_mov_b32_dpp v80, v61 row_shr:1 row_mask:0xf bank_mask:0xf
	v_mov_b32_dpp v78, v61 row_shr:2 row_mask:0xf bank_mask:0xf
	v_mov_b32_dpp v76, v61 row_shr:3 row_mask:0xf bank_mask:0xf
	v_mov_b32_dpp v73, v62 row_shr:1 row_mask:0xf bank_mask:0xf
	v_mov_b32_dpp v71, v62 row_shr:2 row_mask:0xf bank_mask:0xf
	v_mov_b32_dpp v69, v62 row_shr:3 row_mask:0xf bank_mask:0xf
	v_mov_b32_dpp v74, v63 row_shr:1 row_mask:0xf bank_mask:0xf
	v_mov_b32_dpp v72, v63 row_shr:2 row_mask:0xf bank_mask:0xf
	v_mov_b32_dpp v70, v63 row_shr:3 row_mask:0xf bank_mask:0xf
	v_lshl_add_u64 v[64:65], s[22:23], 0, v[136:137]
	s_and_saveexec_b64 s[22:23], s[2:3]
	s_cbranch_execz .LBB0_217
	ds_read_b128 v[82:85], v238 offset:4096
	ds_read_b128 v[86:89], v238 offset:3072
	ds_read_b128 v[90:93], v238 offset:2048
	v_cndmask_b32_e64 v81, v80, 0, s[8:9]
	ds_read_b128 v[94:97], v238 offset:1024
	s_nop 0
	ds_read_b128 v[98:101], v238
	v_cndmask_b32_e64 v80, v79, 0, s[8:9]
	v_cndmask_b32_e64 v79, 0, v78, s[6:7]
	v_cndmask_b32_e64 v78, 0, v77, s[6:7]
	v_cndmask_b32_e64 v77, 0, v76, s[4:5]
	v_cndmask_b32_e64 v76, 0, v75, s[4:5]
	s_waitcnt lgkmcnt(0)
	v_pk_fma_f32 v[60:61], v[60:61], v[86:87], v[82:83]
	v_pk_fma_f32 v[62:63], v[62:63], v[88:89], v[84:85]
	v_pk_fma_f32 v[60:61], v[80:81], v[90:91], v[60:61]
	s_nop 0
	v_pk_fma_f32 v[60:61], v[78:79], v[94:95], v[60:61]
	s_nop 0
	v_pk_fma_f32 v[60:61], v[76:77], v[98:99], v[60:61]
	s_nop 0
	v_mul_f32_e32 v75, 0xbfb8aa3b, v61
	v_exp_f32_e32 v75, v75
	s_nop 0
	v_add_f32_e32 v75, 1.0, v75
	v_rcp_f32_e32 v77, v75
	v_mul_f32_e32 v75, 0xbfb8aa3b, v60
	v_exp_f32_e32 v75, v75
	s_nop 0
	v_add_f32_e32 v75, 1.0, v75
	v_rcp_f32_e32 v76, v75
	v_cndmask_b32_e64 v75, v74, 0, s[8:9]
	v_cndmask_b32_e64 v74, v73, 0, s[8:9]
	v_pk_fma_f32 v[62:63], v[74:75], v[92:93], v[62:63]
	v_cndmask_b32_e64 v73, 0, v72, s[6:7]
	v_cndmask_b32_e64 v72, 0, v71, s[6:7]
	v_pk_fma_f32 v[62:63], v[72:73], v[96:97], v[62:63]
	v_cndmask_b32_e64 v71, 0, v70, s[4:5]
	v_cndmask_b32_e64 v70, 0, v69, s[4:5]
	v_pk_mul_f32 v[60:61], v[60:61], v[76:77]
	v_pk_fma_f32 v[62:63], v[70:71], v[100:101], v[62:63]
	v_cvt_pk_bf16_f32 v60, v60, v61
	v_mul_f32_e32 v61, 0xbfb8aa3b, v63
	v_exp_f32_e32 v61, v61
	s_nop 0
	v_add_f32_e32 v61, 1.0, v61
	v_rcp_f32_e32 v71, v61
	v_mul_f32_e32 v61, 0xbfb8aa3b, v62
	v_exp_f32_e32 v61, v61
	s_nop 0
	v_add_f32_e32 v61, 1.0, v61
	v_rcp_f32_e32 v70, v61
	s_nop 0
	v_pk_mul_f32 v[62:63], v[62:63], v[70:71]
	s_nop 0
	v_cvt_pk_bf16_f32 v61, v62, v63
	global_store_dwordx2 v[64:65], v[60:61], off
.LBB0_217:
	s_or_b64 exec, exec, s[22:23]
	ds_read_b64 v[60:61], v66 offset:1032
	ds_read_b64 v[62:63], v67 offset:520
	ds_read_b64 v[78:79], v68 offset:8
	s_waitcnt lgkmcnt(0)
	v_lshlrev_b32_e32 v75, 16, v60
	v_and_b32_e32 v76, 0xffff0000, v60
	v_lshlrev_b32_e32 v69, 16, v61
	v_and_b32_e32 v70, 0xffff0000, v61
	v_lshlrev_b32_e32 v73, 16, v62
	v_and_b32_e32 v74, 0xffff0000, v62
	v_lshlrev_b32_e32 v62, 16, v63
	v_and_b32_e32 v63, 0xffff0000, v63
	v_lshlrev_b32_e32 v71, 16, v78
	v_and_b32_e32 v72, 0xffff0000, v78
	v_lshlrev_b32_e32 v60, 16, v79
	v_and_b32_e32 v61, 0xffff0000, v79
	v_mov_b32_dpp v75, v56 row_shr:1 row_mask:0xf bank_mask:0xf
	v_mov_b32_dpp v73, v56 row_shr:2 row_mask:0xf bank_mask:0xf
	v_mov_b32_dpp v71, v56 row_shr:3 row_mask:0xf bank_mask:0xf
	v_mov_b32_dpp v76, v57 row_shr:1 row_mask:0xf bank_mask:0xf
	v_mov_b32_dpp v74, v57 row_shr:2 row_mask:0xf bank_mask:0xf
	v_mov_b32_dpp v72, v57 row_shr:3 row_mask:0xf bank_mask:0xf
	v_mov_b32_dpp v69, v58 row_shr:1 row_mask:0xf bank_mask:0xf
	v_mov_b32_dpp v62, v58 row_shr:2 row_mask:0xf bank_mask:0xf
	v_mov_b32_dpp v60, v58 row_shr:3 row_mask:0xf bank_mask:0xf
	v_mov_b32_dpp v70, v59 row_shr:1 row_mask:0xf bank_mask:0xf
	v_mov_b32_dpp v63, v59 row_shr:2 row_mask:0xf bank_mask:0xf
	v_mov_b32_dpp v61, v59 row_shr:3 row_mask:0xf bank_mask:0xf
	s_and_saveexec_b64 s[22:23], s[2:3]
	s_cbranch_execz .LBB0_219
;     __device__ __forceinline__ void operator()(const f32x4 (&acc)[2][2][4][2], const Unit& u, int wr, int wc, int fr, int fq, LAS unsigned char* hb) const {
;     ...
;             for (int m = 0; m < 4; ++m) { asm volatile("" ::: "memory"); __builtin_amdgcn_sched_barrier(0);
;                 const int q = 8 * ai + 4 * wr + m, prev = q > 0 ? q - 1 : 0; const int lr = ai * HALF + wr * 64 + m * 16 + fr, R = R0 + lr;
;                 const int Rc = R < 0 ? 0 : R; const int b = Rc / LL, p = Rc - b * LL;
;                 const bool ok = (lr >= H && R < TT);
;                 const unsigned ooff = ((unsigned)Rc * (unsigned)LDP + (unsigned)(OFF_XBC + ch0)) * 2u;
; #pragma unroll
;                 for (int bn = 0; bn < 4; ++bn) { const int bj = bn >> 1, n = bn & 1; const int co = bj * HALF + 4 * n;
;                     const unsigned woff = (unsigned)(ch0 + co) * 4u;
;                     const f32x4 w0 = *(const f32x4*)((const char*)cw + woff), w1 = *(const f32x4*)((const char*)cw + woff + XBCW * 4), w2 = *(const f32x4*)((const char*)cw + woff + 2 * XBCW * 4), w3 = *(const f32x4*)((const char*)cw + woff + 3 * XBCW * 4), bs = *(const f32x4*)((const char*)cb + woff);
;                     const LAS unsigned char* hp = hb + (prev * H * NCH + chl + co) * 2;
;                     const u32x2 q1 = *(const LAS u32x2*)(hp + hr1 * NCH * 2), q2 = *(const LAS u32x2*)(hp + hr2 * NCH * 2), q3 = *(const LAS u32x2*)(hp + hr3 * NCH * 2);
;                     const float h1[4] = {__builtin_bit_cast(float, q1.x << 16), __builtin_bit_cast(float, q1.x & 0xffff0000u), __builtin_bit_cast(float, q1.y << 16), __builtin_bit_cast(float, q1.y & 0xffff0000u)};
;                     const float h2[4] = {__builtin_bit_cast(float, q2.x << 16), __builtin_bit_cast(float, q2.x & 0xffff0000u), __builtin_bit_cast(float, q2.y << 16), __builtin_bit_cast(float, q2.y & 0xffff0000u)};
;                     const float h3[4] = {__builtin_bit_cast(float, q3.x << 16), __builtin_bit_cast(float, q3.x & 0xffff0000u), __builtin_bit_cast(float, q3.y << 16), __builtin_bit_cast(float, q3.y & 0xffff0000u)};
;                     const f32x4 gv = acc[ai][bj][m][n];
;                     float o[4];
; #pragma unroll
;                     for (int j = 0; j < 4; ++j) { const float g = gv[j];
;                         float g1 = dpp_row_shr<1>(h1[j], g), g2 = dpp_row_shr<2>(h2[j], g), g3 = dpp_row_shr<3>(h3[j], g);
	ds_read_b128 v[78:81], v238 offset:4112
	ds_read_b128 v[82:85], v238 offset:3088
	ds_read_b128 v[86:89], v238 offset:2064
	v_cndmask_b32_e64 v77, v76, 0, s[8:9]
	ds_read_b128 v[90:93], v238 offset:1040
	s_nop 0
	ds_read_b128 v[94:97], v238 offset:16
	v_cndmask_b32_e64 v76, v75, 0, s[8:9]
	v_cndmask_b32_e64 v75, 0, v74, s[6:7]
	v_cndmask_b32_e64 v74, 0, v73, s[6:7]
	v_cndmask_b32_e64 v73, 0, v72, s[4:5]
	v_cndmask_b32_e64 v72, 0, v71, s[4:5]
	v_cndmask_b32_e64 v63, 0, v63, s[6:7]
	v_cndmask_b32_e64 v62, 0, v62, s[6:7]
	v_cndmask_b32_e64 v61, 0, v61, s[4:5]
	v_cndmask_b32_e64 v60, 0, v60, s[4:5]
	s_waitcnt lgkmcnt(0)
	v_pk_fma_f32 v[56:57], v[56:57], v[82:83], v[78:79]
	v_pk_fma_f32 v[58:59], v[58:59], v[84:85], v[80:81]
	v_pk_fma_f32 v[56:57], v[76:77], v[86:87], v[56:57]
	s_nop 0
	v_pk_fma_f32 v[56:57], v[74:75], v[90:91], v[56:57]
	s_nop 0
	v_pk_fma_f32 v[56:57], v[72:73], v[94:95], v[56:57]
	s_nop 0
	v_mul_f32_e32 v71, 0xbfb8aa3b, v57
	v_exp_f32_e32 v71, v71
	s_nop 0
	v_add_f32_e32 v71, 1.0, v71
	v_rcp_f32_e32 v73, v71
	v_mul_f32_e32 v71, 0xbfb8aa3b, v56
	v_exp_f32_e32 v71, v71
	s_nop 0
	v_add_f32_e32 v71, 1.0, v71
	v_rcp_f32_e32 v72, v71
	v_cndmask_b32_e64 v71, v70, 0, s[8:9]
	v_cndmask_b32_e64 v70, v69, 0, s[8:9]
	v_pk_fma_f32 v[58:59], v[70:71], v[88:89], v[58:59]
	v_pk_mul_f32 v[56:57], v[56:57], v[72:73]
	v_pk_fma_f32 v[58:59], v[62:63], v[92:93], v[58:59]
	v_cvt_pk_bf16_f32 v56, v56, v57
	v_pk_fma_f32 v[58:59], v[60:61], v[96:97], v[58:59]
	s_nop 0
	v_mul_f32_e32 v57, 0xbfb8aa3b, v59
	v_exp_f32_e32 v57, v57
	s_nop 0
	v_add_f32_e32 v57, 1.0, v57
	v_rcp_f32_e32 v61, v57
	v_mul_f32_e32 v57, 0xbfb8aa3b, v58
	v_exp_f32_e32 v57, v57
	s_nop 0
	v_add_f32_e32 v57, 1.0, v57
	v_rcp_f32_e32 v60, v57
	s_nop 0
	v_pk_mul_f32 v[58:59], v[58:59], v[60:61]
	s_nop 0
	v_cvt_pk_bf16_f32 v57, v58, v59
	global_store_dwordx2 v[64:65], v[56:57], off offset:8
.LBB0_219:
	s_or_b64 exec, exec, s[22:23]
	ds_read_b64 v[56:57], v66 offset:1280
	ds_read_b64 v[58:59], v67 offset:768
	ds_read_b64 v[74:75], v68 offset:256
	s_waitcnt lgkmcnt(0)
	v_lshlrev_b32_e32 v71, 16, v56
	v_and_b32_e32 v72, 0xffff0000, v56
	v_lshlrev_b32_e32 v60, 16, v57
	v_and_b32_e32 v61, 0xffff0000, v57
	v_lshlrev_b32_e32 v69, 16, v58
	v_and_b32_e32 v70, 0xffff0000, v58
	v_lshlrev_b32_e32 v58, 16, v59
	v_and_b32_e32 v59, 0xffff0000, v59
	v_lshlrev_b32_e32 v62, 16, v74
	v_and_b32_e32 v63, 0xffff0000, v74
	v_lshlrev_b32_e32 v56, 16, v75
	v_and_b32_e32 v57, 0xffff0000, v75
	v_mov_b32_dpp v71, v52 row_shr:1 row_mask:0xf bank_mask:0xf
	v_mov_b32_dpp v69, v52 row_shr:2 row_mask:0xf bank_mask:0xf
	v_mov_b32_dpp v62, v52 row_shr:3 row_mask:0xf bank_mask:0xf
	v_mov_b32_dpp v72, v53 row_shr:1 row_mask:0xf bank_mask:0xf
	v_mov_b32_dpp v70, v53 row_shr:2 row_mask:0xf bank_mask:0xf
	v_mov_b32_dpp v63, v53 row_shr:3 row_mask:0xf bank_mask:0xf
	v_mov_b32_dpp v60, v54 row_shr:1 row_mask:0xf bank_mask:0xf
	v_mov_b32_dpp v58, v54 row_shr:2 row_mask:0xf bank_mask:0xf
	v_mov_b32_dpp v56, v54 row_shr:3 row_mask:0xf bank_mask:0xf
	v_mov_b32_dpp v61, v55 row_shr:1 row_mask:0xf bank_mask:0xf
	v_mov_b32_dpp v59, v55 row_shr:2 row_mask:0xf bank_mask:0xf
	v_mov_b32_dpp v57, v55 row_shr:3 row_mask:0xf bank_mask:0xf
	s_and_saveexec_b64 s[22:23], s[2:3]
	s_cbranch_execz .LBB0_221
	ds_read_b128 v[74:77], v238 offset:4608
	ds_read_b128 v[78:81], v238 offset:3584
	ds_read_b128 v[82:85], v238 offset:2560
	v_cndmask_b32_e64 v73, v72, 0, s[8:9]
	ds_read_b128 v[86:89], v238 offset:1536
	s_nop 0
	ds_read_b128 v[90:93], v238 offset:512
	v_cndmask_b32_e64 v72, v71, 0, s[8:9]
	v_cndmask_b32_e64 v71, 0, v70, s[6:7]
	v_cndmask_b32_e64 v70, 0, v69, s[6:7]
	v_cndmask_b32_e64 v63, 0, v63, s[4:5]
	v_cndmask_b32_e64 v62, 0, v62, s[4:5]
	v_cndmask_b32_e64 v61, v61, 0, s[8:9]
	v_cndmask_b32_e64 v60, v60, 0, s[8:9]
	v_cndmask_b32_e64 v59, 0, v59, s[6:7]
	v_cndmask_b32_e64 v58, 0, v58, s[6:7]
	v_cndmask_b32_e64 v57, 0, v57, s[4:5]
	v_cndmask_b32_e64 v56, 0, v56, s[4:5]
	s_waitcnt lgkmcnt(0)
	v_pk_fma_f32 v[52:53], v[52:53], v[78:79], v[74:75]
	v_pk_fma_f32 v[54:55], v[54:55], v[80:81], v[76:77]
	v_pk_fma_f32 v[52:53], v[72:73], v[82:83], v[52:53]
	v_pk_fma_f32 v[54:55], v[60:61], v[84:85], v[54:55]
	v_pk_fma_f32 v[52:53], v[70:71], v[86:87], v[52:53]
	s_nop 0
	v_pk_fma_f32 v[52:53], v[62:63], v[90:91], v[52:53]
	v_pk_fma_f32 v[54:55], v[58:59], v[88:89], v[54:55]
	v_mul_f32_e32 v62, 0xbfb8aa3b, v53
	v_exp_f32_e32 v62, v62
	v_pk_fma_f32 v[54:55], v[56:57], v[92:93], v[54:55]
	v_add_f32_e32 v62, 1.0, v62
	v_rcp_f32_e32 v63, v62
	v_mul_f32_e32 v62, 0xbfb8aa3b, v52
	v_exp_f32_e32 v62, v62
	s_nop 0
	v_add_f32_e32 v62, 1.0, v62
	v_rcp_f32_e32 v62, v62
	s_nop 0
	v_pk_mul_f32 v[52:53], v[52:53], v[62:63]
	s_nop 0
	v_cvt_pk_bf16_f32 v52, v52, v53
	v_mul_f32_e32 v53, 0xbfb8aa3b, v55
	v_exp_f32_e32 v53, v53
	s_nop 0
	v_add_f32_e32 v53, 1.0, v53
	v_rcp_f32_e32 v57, v53
	v_mul_f32_e32 v53, 0xbfb8aa3b, v54
	v_exp_f32_e32 v53, v53
	s_nop 0
	v_add_f32_e32 v53, 1.0, v53
	v_rcp_f32_e32 v56, v53
	s_nop 0
	v_pk_mul_f32 v[54:55], v[54:55], v[56:57]
	s_nop 0
	v_cvt_pk_bf16_f32 v53, v54, v55
	global_store_dwordx2 v[64:65], v[52:53], off offset:256
;     __device__ __forceinline__ void operator()(const f32x4 (&acc)[2][2][4][2], const Unit& u, int wr, int wc, int fr, int fq, LAS unsigned char* hb) const {
;     ...
;             for (int m = 0; m < 4; ++m) { asm volatile("" ::: "memory"); __builtin_amdgcn_sched_barrier(0);
;                 const int q = 8 * ai + 4 * wr + m, prev = q > 0 ? q - 1 : 0; const int lr = ai * HALF + wr * 64 + m * 16 + fr, R = R0 + lr;
;                 const int Rc = R < 0 ? 0 : R; const int b = Rc / LL, p = Rc - b * LL;
;                 const bool ok = (lr >= H && R < TT);
;                 const unsigned ooff = ((unsigned)Rc * (unsigned)LDP + (unsigned)(OFF_XBC + ch0)) * 2u;
; #pragma unroll
;                 for (int bn = 0; bn < 4; ++bn) { const int bj = bn >> 1, n = bn & 1; const int co = bj * HALF + 4 * n;
;                     const unsigned woff = (unsigned)(ch0 + co) * 4u;
;                     const f32x4 w0 = *(const f32x4*)((const char*)cw + woff), w1 = *(const f32x4*)((const char*)cw + woff + XBCW * 4), w2 = *(const f32x4*)((const char*)cw + woff + 2 * XBCW * 4), w3 = *(const f32x4*)((const char*)cw + woff + 3 * XBCW * 4), bs = *(const f32x4*)((const char*)cb + woff);
;                     const LAS unsigned char* hp = hb + (prev * H * NCH + chl + co) * 2;
;                     const u32x2 q1 = *(const LAS u32x2*)(hp + hr1 * NCH * 2), q2 = *(const LAS u32x2*)(hp + hr2 * NCH * 2), q3 = *(const LAS u32x2*)(hp + hr3 * NCH * 2);
;                     const float h1[4] = {__builtin_bit_cast(float, q1.x << 16), __builtin_bit_cast(float, q1.x & 0xffff0000u), __builtin_bit_cast(float, q1.y << 16), __builtin_bit_cast(float, q1.y & 0xffff0000u)};
;                     const float h2[4] = {__builtin_bit_cast(float, q2.x << 16), __builtin_bit_cast(float, q2.x & 0xffff0000u), __builtin_bit_cast(float, q2.y << 16), __builtin_bit_cast(float, q2.y & 0xffff0000u)};
;                     const float h3[4] = {__builtin_bit_cast(float, q3.x << 16), __builtin_bit_cast(float, q3.x & 0xffff0000u), __builtin_bit_cast(float, q3.y << 16), __builtin_bit_cast(float, q3.y & 0xffff0000u)};
;                     const f32x4 gv = acc[ai][bj][m][n];
;                     float o[4];
; #pragma unroll
;                     for (int j = 0; j < 4; ++j) { const float g = gv[j];
;                         float g1 = dpp_row_shr<1>(h1[j], g), g2 = dpp_row_shr<2>(h2[j], g), g3 = dpp_row_shr<3>(h3[j], g);
.LBB0_221:
	s_or_b64 exec, exec, s[22:23]
	ds_read_b64 v[52:53], v66 offset:1288
	ds_read_b64 v[54:55], v67 offset:776
	ds_read_b64 v[66:67], v68 offset:264
	s_waitcnt lgkmcnt(0)
	v_lshlrev_b32_e32 v62, 16, v52
	v_and_b32_e32 v63, 0xffff0000, v52
	v_lshlrev_b32_e32 v56, 16, v53
	v_and_b32_e32 v57, 0xffff0000, v53
	v_lshlrev_b32_e32 v60, 16, v54
	v_and_b32_e32 v61, 0xffff0000, v54
	v_lshlrev_b32_e32 v54, 16, v55
	v_and_b32_e32 v55, 0xffff0000, v55
	v_lshlrev_b32_e32 v58, 16, v66
	v_and_b32_e32 v59, 0xffff0000, v66
	v_lshlrev_b32_e32 v52, 16, v67
	v_and_b32_e32 v53, 0xffff0000, v67
	v_mov_b32_dpp v62, v48 row_shr:1 row_mask:0xf bank_mask:0xf
	v_mov_b32_dpp v60, v48 row_shr:2 row_mask:0xf bank_mask:0xf
	v_mov_b32_dpp v58, v48 row_shr:3 row_mask:0xf bank_mask:0xf
	v_mov_b32_dpp v63, v49 row_shr:1 row_mask:0xf bank_mask:0xf
	v_mov_b32_dpp v61, v49 row_shr:2 row_mask:0xf bank_mask:0xf
	v_mov_b32_dpp v59, v49 row_shr:3 row_mask:0xf bank_mask:0xf
	v_mov_b32_dpp v56, v50 row_shr:1 row_mask:0xf bank_mask:0xf
	v_mov_b32_dpp v54, v50 row_shr:2 row_mask:0xf bank_mask:0xf
	v_mov_b32_dpp v52, v50 row_shr:3 row_mask:0xf bank_mask:0xf
	v_mov_b32_dpp v57, v51 row_shr:1 row_mask:0xf bank_mask:0xf
	v_mov_b32_dpp v55, v51 row_shr:2 row_mask:0xf bank_mask:0xf
	v_mov_b32_dpp v53, v51 row_shr:3 row_mask:0xf bank_mask:0xf
	s_and_saveexec_b64 s[22:23], s[2:3]
	s_cbranch_execz .LBB0_223
	ds_read_b128 v[66:69], v238 offset:4624
	ds_read_b128 v[70:73], v238 offset:3600
	ds_read_b128 v[74:77], v238 offset:2576
	v_cndmask_b32_e64 v63, v63, 0, s[8:9]
	ds_read_b128 v[78:81], v238 offset:1552
	s_nop 0
	ds_read_b128 v[82:85], v238 offset:528
	v_cndmask_b32_e64 v62, v62, 0, s[8:9]
	v_cndmask_b32_e64 v61, 0, v61, s[6:7]
	v_cndmask_b32_e64 v60, 0, v60, s[6:7]
	v_cndmask_b32_e64 v59, 0, v59, s[4:5]
	v_cndmask_b32_e64 v58, 0, v58, s[4:5]
	v_cndmask_b32_e64 v57, v57, 0, s[8:9]
	v_cndmask_b32_e64 v56, v56, 0, s[8:9]
	v_cndmask_b32_e64 v55, 0, v55, s[6:7]
	v_cndmask_b32_e64 v54, 0, v54, s[6:7]
	v_cndmask_b32_e64 v53, 0, v53, s[4:5]
	v_cndmask_b32_e64 v52, 0, v52, s[4:5]
	s_waitcnt lgkmcnt(0)
	v_pk_fma_f32 v[48:49], v[48:49], v[70:71], v[66:67]
	v_pk_fma_f32 v[50:51], v[50:51], v[72:73], v[68:69]
	v_pk_fma_f32 v[48:49], v[62:63], v[74:75], v[48:49]
	v_pk_fma_f32 v[50:51], v[56:57], v[76:77], v[50:51]
	v_pk_fma_f32 v[48:49], v[60:61], v[78:79], v[48:49]
	s_nop 0
	v_pk_fma_f32 v[48:49], v[58:59], v[82:83], v[48:49]
	v_pk_fma_f32 v[50:51], v[54:55], v[80:81], v[50:51]
	v_mul_f32_e32 v58, 0xbfb8aa3b, v49
	v_exp_f32_e32 v58, v58
	v_pk_fma_f32 v[50:51], v[52:53], v[84:85], v[50:51]
	v_add_f32_e32 v58, 1.0, v58
	v_rcp_f32_e32 v59, v58
	v_mul_f32_e32 v58, 0xbfb8aa3b, v48
	v_exp_f32_e32 v58, v58
	s_nop 0
	v_add_f32_e32 v58, 1.0, v58
	v_rcp_f32_e32 v58, v58
	s_nop 0
	v_pk_mul_f32 v[48:49], v[48:49], v[58:59]
	s_nop 0
	v_cvt_pk_bf16_f32 v48, v48, v49
	v_mul_f32_e32 v49, 0xbfb8aa3b, v51
	v_exp_f32_e32 v49, v49
	s_nop 0
	v_add_f32_e32 v49, 1.0, v49
	v_rcp_f32_e32 v53, v49
	v_mul_f32_e32 v49, 0xbfb8aa3b, v50
	v_exp_f32_e32 v49, v49
	s_nop 0
	v_add_f32_e32 v49, 1.0, v49
	v_rcp_f32_e32 v52, v49
	s_nop 0
	v_pk_mul_f32 v[50:51], v[50:51], v[52:53]
	s_nop 0
	v_cvt_pk_bf16_f32 v49, v50, v51
	global_store_dwordx2 v[64:65], v[48:49], off offset:264
.LBB0_223:
	s_or_b64 exec, exec, s[22:23]
	v_add_u32_e32 v48, 0x90, v161
	v_add_u32_e32 v49, s17, v48
	v_max_i32_e32 v50, 0, v49
	v_mul_hi_u32 v51, v50, s56
	v_lshrrev_b32_e32 v51, 11, v51
	v_cmp_lt_i32_e32 vcc, 2, v48
	v_mul_lo_u32 v48, v50, s51
	v_mul_u32_u24_e32 v51, 0x1010, v51
	v_add_lshl_u32 v136, v48, v164, 1
	v_add_u32_e32 v48, s42, v165
	v_sub_u32_e32 v51, v50, v51
	v_cmp_gt_i32_e64 s[4:5], s50, v49
	v_lshl_add_u32 v50, v48, 1, s53
	s_and_b64 s[2:3], vcc, s[4:5]
	v_cmp_eq_u32_e64 s[8:9], 0, v51
	v_cmp_lt_u32_e64 s[6:7], 1, v51
	v_cmp_lt_u32_e64 s[4:5], 2, v51
	v_add_u32_e32 v51, v50, v163
	ds_read_b64 v[48:49], v50 offset:1024
	v_add_u32_e32 v52, v50, v162
	ds_read_b64 v[66:67], v51 offset:512
	ds_read_b64 v[68:69], v52
	v_readlane_b32 s22, v237, 58
	v_readlane_b32 s23, v237, 59
	s_waitcnt lgkmcnt(0)
	v_lshlrev_b32_e32 v63, 16, v48
	v_and_b32_e32 v64, 0xffff0000, v48
	v_lshlrev_b32_e32 v57, 16, v49
	v_and_b32_e32 v58, 0xffff0000, v49
	v_lshlrev_b32_e32 v61, 16, v66
	v_and_b32_e32 v62, 0xffff0000, v66
	v_lshlrev_b32_e32 v55, 16, v67
	v_and_b32_e32 v56, 0xffff0000, v67
	v_lshlrev_b32_e32 v59, 16, v68
	v_and_b32_e32 v60, 0xffff0000, v68
	v_lshlrev_b32_e32 v53, 16, v69
	v_and_b32_e32 v54, 0xffff0000, v69
	v_mov_b32_dpp v63, v44 row_shr:1 row_mask:0xf bank_mask:0xf
	v_mov_b32_dpp v61, v44 row_shr:2 row_mask:0xf bank_mask:0xf
	v_mov_b32_dpp v59, v44 row_shr:3 row_mask:0xf bank_mask:0xf
	v_mov_b32_dpp v64, v45 row_shr:1 row_mask:0xf bank_mask:0xf
	v_mov_b32_dpp v62, v45 row_shr:2 row_mask:0xf bank_mask:0xf
	v_mov_b32_dpp v60, v45 row_shr:3 row_mask:0xf bank_mask:0xf
	v_mov_b32_dpp v57, v46 row_shr:1 row_mask:0xf bank_mask:0xf
	v_mov_b32_dpp v55, v46 row_shr:2 row_mask:0xf bank_mask:0xf
	v_mov_b32_dpp v53, v46 row_shr:3 row_mask:0xf bank_mask:0xf
	v_mov_b32_dpp v58, v47 row_shr:1 row_mask:0xf bank_mask:0xf
	v_mov_b32_dpp v56, v47 row_shr:2 row_mask:0xf bank_mask:0xf
	v_mov_b32_dpp v54, v47 row_shr:3 row_mask:0xf bank_mask:0xf
	v_lshl_add_u64 v[48:49], s[22:23], 0, v[136:137]
	s_and_saveexec_b64 s[22:23], s[2:3]
	s_cbranch_execz .LBB0_225
;     __device__ __forceinline__ void operator()(const f32x4 (&acc)[2][2][4][2], const Unit& u, int wr, int wc, int fr, int fq, LAS unsigned char* hb) const {
;     ...
;             for (int m = 0; m < 4; ++m) { asm volatile("" ::: "memory"); __builtin_amdgcn_sched_barrier(0);
;                 const int q = 8 * ai + 4 * wr + m, prev = q > 0 ? q - 1 : 0; const int lr = ai * HALF + wr * 64 + m * 16 + fr, R = R0 + lr;
;                 const int Rc = R < 0 ? 0 : R; const int b = Rc / LL, p = Rc - b * LL;
;                 const bool ok = (lr >= H && R < TT);
;                 const unsigned ooff = ((unsigned)Rc * (unsigned)LDP + (unsigned)(OFF_XBC + ch0)) * 2u;
; #pragma unroll
;                 for (int bn = 0; bn < 4; ++bn) { const int bj = bn >> 1, n = bn & 1; const int co = bj * HALF + 4 * n;
;                     const unsigned woff = (unsigned)(ch0 + co) * 4u;
;                     const f32x4 w0 = *(const f32x4*)((const char*)cw + woff), w1 = *(const f32x4*)((const char*)cw + woff + XBCW * 4), w2 = *(const f32x4*)((const char*)cw + woff + 2 * XBCW * 4), w3 = *(const f32x4*)((const char*)cw + woff + 3 * XBCW * 4), bs = *(const f32x4*)((const char*)cb + woff);
;                     const LAS unsigned char* hp = hb + (prev * H * NCH + chl + co) * 2;
;                     const u32x2 q1 = *(const LAS u32x2*)(hp + hr1 * NCH * 2), q2 = *(const LAS u32x2*)(hp + hr2 * NCH * 2), q3 = *(const LAS u32x2*)(hp + hr3 * NCH * 2);
;                     const float h1[4] = {__builtin_bit_cast(float, q1.x << 16), __builtin_bit_cast(float, q1.x & 0xffff0000u), __builtin_bit_cast(float, q1.y << 16), __builtin_bit_cast(float, q1.y & 0xffff0000u)};
;                     const float h2[4] = {__builtin_bit_cast(float, q2.x << 16), __builtin_bit_cast(float, q2.x & 0xffff0000u), __builtin_bit_cast(float, q2.y << 16), __builtin_bit_cast(float, q2.y & 0xffff0000u)};
;                     const float h3[4] = {__builtin_bit_cast(float, q3.x << 16), __builtin_bit_cast(float, q3.x & 0xffff0000u), __builtin_bit_cast(float, q3.y << 16), __builtin_bit_cast(float, q3.y & 0xffff0000u)};
;                     const f32x4 gv = acc[ai][bj][m][n];
;                     float o[4];
; #pragma unroll
;                     for (int j = 0; j < 4; ++j) { const float g = gv[j];
;                         float g1 = dpp_row_shr<1>(h1[j], g), g2 = dpp_row_shr<2>(h2[j], g), g3 = dpp_row_shr<3>(h3[j], g);
	ds_read_b128 v[66:69], v238 offset:4096
	ds_read_b128 v[70:73], v238 offset:3072
	ds_read_b128 v[74:77], v238 offset:2048
	v_cndmask_b32_e64 v65, v64, 0, s[8:9]
	ds_read_b128 v[78:81], v238 offset:1024
	s_nop 0
	ds_read_b128 v[82:85], v238
	v_cndmask_b32_e64 v64, v63, 0, s[8:9]
	v_cndmask_b32_e64 v63, 0, v62, s[6:7]
	v_cndmask_b32_e64 v62, 0, v61, s[6:7]
	v_cndmask_b32_e64 v61, 0, v60, s[4:5]
	v_cndmask_b32_e64 v60, 0, v59, s[4:5]
	s_waitcnt lgkmcnt(0)
	v_pk_fma_f32 v[44:45], v[44:45], v[70:71], v[66:67]
	v_pk_fma_f32 v[46:47], v[46:47], v[72:73], v[68:69]
	v_pk_fma_f32 v[44:45], v[64:65], v[74:75], v[44:45]
	s_nop 0
	v_pk_fma_f32 v[44:45], v[62:63], v[78:79], v[44:45]
	s_nop 0
	v_pk_fma_f32 v[44:45], v[60:61], v[82:83], v[44:45]
	s_nop 0
	v_mul_f32_e32 v59, 0xbfb8aa3b, v45
	v_exp_f32_e32 v59, v59
	s_nop 0
	v_add_f32_e32 v59, 1.0, v59
	v_rcp_f32_e32 v61, v59
	v_mul_f32_e32 v59, 0xbfb8aa3b, v44
	v_exp_f32_e32 v59, v59
	s_nop 0
	v_add_f32_e32 v59, 1.0, v59
	v_rcp_f32_e32 v60, v59
	v_cndmask_b32_e64 v59, v58, 0, s[8:9]
	v_cndmask_b32_e64 v58, v57, 0, s[8:9]
	v_pk_fma_f32 v[46:47], v[58:59], v[76:77], v[46:47]
	v_cndmask_b32_e64 v57, 0, v56, s[6:7]
	v_cndmask_b32_e64 v56, 0, v55, s[6:7]
	v_pk_fma_f32 v[46:47], v[56:57], v[80:81], v[46:47]
	v_cndmask_b32_e64 v55, 0, v54, s[4:5]
	v_cndmask_b32_e64 v54, 0, v53, s[4:5]
	v_pk_mul_f32 v[44:45], v[44:45], v[60:61]
	v_pk_fma_f32 v[46:47], v[54:55], v[84:85], v[46:47]
	v_cvt_pk_bf16_f32 v44, v44, v45
	v_mul_f32_e32 v45, 0xbfb8aa3b, v47
	v_exp_f32_e32 v45, v45
	s_nop 0
	v_add_f32_e32 v45, 1.0, v45
	v_rcp_f32_e32 v55, v45
	v_mul_f32_e32 v45, 0xbfb8aa3b, v46
	v_exp_f32_e32 v45, v45
	s_nop 0
	v_add_f32_e32 v45, 1.0, v45
	v_rcp_f32_e32 v54, v45
	s_nop 0
	v_pk_mul_f32 v[46:47], v[46:47], v[54:55]
	s_nop 0
	v_cvt_pk_bf16_f32 v45, v46, v47
	global_store_dwordx2 v[48:49], v[44:45], off
.LBB0_225:
	s_or_b64 exec, exec, s[22:23]
	ds_read_b64 v[44:45], v50 offset:1032
	ds_read_b64 v[46:47], v51 offset:520
	ds_read_b64 v[62:63], v52 offset:8
	s_waitcnt lgkmcnt(0)
	v_lshlrev_b32_e32 v59, 16, v44
	v_and_b32_e32 v60, 0xffff0000, v44
	v_lshlrev_b32_e32 v53, 16, v45
	v_and_b32_e32 v54, 0xffff0000, v45
	v_lshlrev_b32_e32 v57, 16, v46
	v_and_b32_e32 v58, 0xffff0000, v46
	v_lshlrev_b32_e32 v46, 16, v47
	v_and_b32_e32 v47, 0xffff0000, v47
	v_lshlrev_b32_e32 v55, 16, v62
	v_and_b32_e32 v56, 0xffff0000, v62
	v_lshlrev_b32_e32 v44, 16, v63
	v_and_b32_e32 v45, 0xffff0000, v63
	v_mov_b32_dpp v59, v40 row_shr:1 row_mask:0xf bank_mask:0xf
	v_mov_b32_dpp v57, v40 row_shr:2 row_mask:0xf bank_mask:0xf
	v_mov_b32_dpp v55, v40 row_shr:3 row_mask:0xf bank_mask:0xf
	v_mov_b32_dpp v60, v41 row_shr:1 row_mask:0xf bank_mask:0xf
	v_mov_b32_dpp v58, v41 row_shr:2 row_mask:0xf bank_mask:0xf
	v_mov_b32_dpp v56, v41 row_shr:3 row_mask:0xf bank_mask:0xf
	v_mov_b32_dpp v53, v42 row_shr:1 row_mask:0xf bank_mask:0xf
	v_mov_b32_dpp v46, v42 row_shr:2 row_mask:0xf bank_mask:0xf
	v_mov_b32_dpp v44, v42 row_shr:3 row_mask:0xf bank_mask:0xf
	v_mov_b32_dpp v54, v43 row_shr:1 row_mask:0xf bank_mask:0xf
	v_mov_b32_dpp v47, v43 row_shr:2 row_mask:0xf bank_mask:0xf
	v_mov_b32_dpp v45, v43 row_shr:3 row_mask:0xf bank_mask:0xf
	s_and_saveexec_b64 s[22:23], s[2:3]
	s_cbranch_execz .LBB0_227
	ds_read_b128 v[62:65], v238 offset:4112
	ds_read_b128 v[66:69], v238 offset:3088
	ds_read_b128 v[70:73], v238 offset:2064
	v_cndmask_b32_e64 v61, v60, 0, s[8:9]
	ds_read_b128 v[74:77], v238 offset:1040
	s_nop 0
	ds_read_b128 v[78:81], v238 offset:16
	v_cndmask_b32_e64 v60, v59, 0, s[8:9]
	v_cndmask_b32_e64 v59, 0, v58, s[6:7]
	v_cndmask_b32_e64 v58, 0, v57, s[6:7]
	v_cndmask_b32_e64 v57, 0, v56, s[4:5]
	v_cndmask_b32_e64 v56, 0, v55, s[4:5]
	v_cndmask_b32_e64 v47, 0, v47, s[6:7]
	v_cndmask_b32_e64 v46, 0, v46, s[6:7]
	v_cndmask_b32_e64 v45, 0, v45, s[4:5]
	v_cndmask_b32_e64 v44, 0, v44, s[4:5]
	s_waitcnt lgkmcnt(0)
	v_pk_fma_f32 v[40:41], v[40:41], v[66:67], v[62:63]
	v_pk_fma_f32 v[42:43], v[42:43], v[68:69], v[64:65]
	v_pk_fma_f32 v[40:41], v[60:61], v[70:71], v[40:41]
	s_nop 0
	v_pk_fma_f32 v[40:41], v[58:59], v[74:75], v[40:41]
	s_nop 0
	v_pk_fma_f32 v[40:41], v[56:57], v[78:79], v[40:41]
	s_nop 0
	v_mul_f32_e32 v55, 0xbfb8aa3b, v41
	v_exp_f32_e32 v55, v55
	s_nop 0
	v_add_f32_e32 v55, 1.0, v55
	v_rcp_f32_e32 v57, v55
	v_mul_f32_e32 v55, 0xbfb8aa3b, v40
	v_exp_f32_e32 v55, v55
	s_nop 0
	v_add_f32_e32 v55, 1.0, v55
	v_rcp_f32_e32 v56, v55
	v_cndmask_b32_e64 v55, v54, 0, s[8:9]
	v_cndmask_b32_e64 v54, v53, 0, s[8:9]
	v_pk_fma_f32 v[42:43], v[54:55], v[72:73], v[42:43]
	v_pk_mul_f32 v[40:41], v[40:41], v[56:57]
	v_pk_fma_f32 v[42:43], v[46:47], v[76:77], v[42:43]
	v_cvt_pk_bf16_f32 v40, v40, v41
	v_pk_fma_f32 v[42:43], v[44:45], v[80:81], v[42:43]
	s_nop 0
	v_mul_f32_e32 v41, 0xbfb8aa3b, v43
	v_exp_f32_e32 v41, v41
	s_nop 0
	v_add_f32_e32 v41, 1.0, v41
	v_rcp_f32_e32 v45, v41
	v_mul_f32_e32 v41, 0xbfb8aa3b, v42
	v_exp_f32_e32 v41, v41
	s_nop 0
	v_add_f32_e32 v41, 1.0, v41
	v_rcp_f32_e32 v44, v41
	s_nop 0
	v_pk_mul_f32 v[42:43], v[42:43], v[44:45]
	s_nop 0
	v_cvt_pk_bf16_f32 v41, v42, v43
	global_store_dwordx2 v[48:49], v[40:41], off offset:8
;     __device__ __forceinline__ void operator()(const f32x4 (&acc)[2][2][4][2], const Unit& u, int wr, int wc, int fr, int fq, LAS unsigned char* hb) const {
;     ...
;             for (int m = 0; m < 4; ++m) { asm volatile("" ::: "memory"); __builtin_amdgcn_sched_barrier(0);
;                 const int q = 8 * ai + 4 * wr + m, prev = q > 0 ? q - 1 : 0; const int lr = ai * HALF + wr * 64 + m * 16 + fr, R = R0 + lr;
;                 const int Rc = R < 0 ? 0 : R; const int b = Rc / LL, p = Rc - b * LL;
;                 const bool ok = (lr >= H && R < TT);
;                 const unsigned ooff = ((unsigned)Rc * (unsigned)LDP + (unsigned)(OFF_XBC + ch0)) * 2u;
; #pragma unroll
;                 for (int bn = 0; bn < 4; ++bn) { const int bj = bn >> 1, n = bn & 1; const int co = bj * HALF + 4 * n;
;                     const unsigned woff = (unsigned)(ch0 + co) * 4u;
;                     const f32x4 w0 = *(const f32x4*)((const char*)cw + woff), w1 = *(const f32x4*)((const char*)cw + woff + XBCW * 4), w2 = *(const f32x4*)((const char*)cw + woff + 2 * XBCW * 4), w3 = *(const f32x4*)((const char*)cw + woff + 3 * XBCW * 4), bs = *(const f32x4*)((const char*)cb + woff);
;                     const LAS unsigned char* hp = hb + (prev * H * NCH + chl + co) * 2;
;                     const u32x2 q1 = *(const LAS u32x2*)(hp + hr1 * NCH * 2), q2 = *(const LAS u32x2*)(hp + hr2 * NCH * 2), q3 = *(const LAS u32x2*)(hp + hr3 * NCH * 2);
;                     const float h1[4] = {__builtin_bit_cast(float, q1.x << 16), __builtin_bit_cast(float, q1.x & 0xffff0000u), __builtin_bit_cast(float, q1.y << 16), __builtin_bit_cast(float, q1.y & 0xffff0000u)};
;                     const float h2[4] = {__builtin_bit_cast(float, q2.x << 16), __builtin_bit_cast(float, q2.x & 0xffff0000u), __builtin_bit_cast(float, q2.y << 16), __builtin_bit_cast(float, q2.y & 0xffff0000u)};
;                     const float h3[4] = {__builtin_bit_cast(float, q3.x << 16), __builtin_bit_cast(float, q3.x & 0xffff0000u), __builtin_bit_cast(float, q3.y << 16), __builtin_bit_cast(float, q3.y & 0xffff0000u)};
;                     const f32x4 gv = acc[ai][bj][m][n];
;                     float o[4];
; #pragma unroll
;                     for (int j = 0; j < 4; ++j) { const float g = gv[j];
;                         float g1 = dpp_row_shr<1>(h1[j], g), g2 = dpp_row_shr<2>(h2[j], g), g3 = dpp_row_shr<3>(h3[j], g);
.LBB0_227:
	s_or_b64 exec, exec, s[22:23]
	ds_read_b64 v[40:41], v50 offset:1280
	ds_read_b64 v[42:43], v51 offset:768
	ds_read_b64 v[58:59], v52 offset:256
	s_waitcnt lgkmcnt(0)
	v_lshlrev_b32_e32 v55, 16, v40
	v_and_b32_e32 v56, 0xffff0000, v40
	v_lshlrev_b32_e32 v44, 16, v41
	v_and_b32_e32 v45, 0xffff0000, v41
	v_lshlrev_b32_e32 v53, 16, v42
	v_and_b32_e32 v54, 0xffff0000, v42
	v_lshlrev_b32_e32 v42, 16, v43
	v_and_b32_e32 v43, 0xffff0000, v43
	v_lshlrev_b32_e32 v46, 16, v58
	v_and_b32_e32 v47, 0xffff0000, v58
	v_lshlrev_b32_e32 v40, 16, v59
	v_and_b32_e32 v41, 0xffff0000, v59
	v_mov_b32_dpp v55, v36 row_shr:1 row_mask:0xf bank_mask:0xf
	v_mov_b32_dpp v53, v36 row_shr:2 row_mask:0xf bank_mask:0xf
	v_mov_b32_dpp v46, v36 row_shr:3 row_mask:0xf bank_mask:0xf
	v_mov_b32_dpp v56, v37 row_shr:1 row_mask:0xf bank_mask:0xf
	v_mov_b32_dpp v54, v37 row_shr:2 row_mask:0xf bank_mask:0xf
	v_mov_b32_dpp v47, v37 row_shr:3 row_mask:0xf bank_mask:0xf
	v_mov_b32_dpp v44, v38 row_shr:1 row_mask:0xf bank_mask:0xf
	v_mov_b32_dpp v42, v38 row_shr:2 row_mask:0xf bank_mask:0xf
	v_mov_b32_dpp v40, v38 row_shr:3 row_mask:0xf bank_mask:0xf
	v_mov_b32_dpp v45, v39 row_shr:1 row_mask:0xf bank_mask:0xf
	v_mov_b32_dpp v43, v39 row_shr:2 row_mask:0xf bank_mask:0xf
	v_mov_b32_dpp v41, v39 row_shr:3 row_mask:0xf bank_mask:0xf
	s_and_saveexec_b64 s[22:23], s[2:3]
	s_cbranch_execz .LBB0_229
	ds_read_b128 v[58:61], v238 offset:4608
	ds_read_b128 v[62:65], v238 offset:3584
	ds_read_b128 v[66:69], v238 offset:2560
	v_cndmask_b32_e64 v57, v56, 0, s[8:9]
	ds_read_b128 v[70:73], v238 offset:1536
	s_nop 0
	ds_read_b128 v[74:77], v238 offset:512
	v_cndmask_b32_e64 v56, v55, 0, s[8:9]
	v_cndmask_b32_e64 v55, 0, v54, s[6:7]
	v_cndmask_b32_e64 v54, 0, v53, s[6:7]
	v_cndmask_b32_e64 v47, 0, v47, s[4:5]
	v_cndmask_b32_e64 v46, 0, v46, s[4:5]
	v_cndmask_b32_e64 v45, v45, 0, s[8:9]
	v_cndmask_b32_e64 v44, v44, 0, s[8:9]
	v_cndmask_b32_e64 v43, 0, v43, s[6:7]
	v_cndmask_b32_e64 v42, 0, v42, s[6:7]
	v_cndmask_b32_e64 v41, 0, v41, s[4:5]
	v_cndmask_b32_e64 v40, 0, v40, s[4:5]
	s_waitcnt lgkmcnt(0)
	v_pk_fma_f32 v[36:37], v[36:37], v[62:63], v[58:59]
	v_pk_fma_f32 v[38:39], v[38:39], v[64:65], v[60:61]
	v_pk_fma_f32 v[36:37], v[56:57], v[66:67], v[36:37]
	v_pk_fma_f32 v[38:39], v[44:45], v[68:69], v[38:39]
	v_pk_fma_f32 v[36:37], v[54:55], v[70:71], v[36:37]
	s_nop 0
	v_pk_fma_f32 v[36:37], v[46:47], v[74:75], v[36:37]
	v_pk_fma_f32 v[38:39], v[42:43], v[72:73], v[38:39]
	v_mul_f32_e32 v46, 0xbfb8aa3b, v37
	v_exp_f32_e32 v46, v46
	v_pk_fma_f32 v[38:39], v[40:41], v[76:77], v[38:39]
	v_add_f32_e32 v46, 1.0, v46
	v_rcp_f32_e32 v47, v46
	v_mul_f32_e32 v46, 0xbfb8aa3b, v36
	v_exp_f32_e32 v46, v46
	s_nop 0
	v_add_f32_e32 v46, 1.0, v46
	v_rcp_f32_e32 v46, v46
	s_nop 0
	v_pk_mul_f32 v[36:37], v[36:37], v[46:47]
	s_nop 0
	v_cvt_pk_bf16_f32 v36, v36, v37
	v_mul_f32_e32 v37, 0xbfb8aa3b, v39
	v_exp_f32_e32 v37, v37
	s_nop 0
	v_add_f32_e32 v37, 1.0, v37
	v_rcp_f32_e32 v41, v37
	v_mul_f32_e32 v37, 0xbfb8aa3b, v38
	v_exp_f32_e32 v37, v37
	s_nop 0
	v_add_f32_e32 v37, 1.0, v37
	v_rcp_f32_e32 v40, v37
	s_nop 0
	v_pk_mul_f32 v[38:39], v[38:39], v[40:41]
	s_nop 0
	v_cvt_pk_bf16_f32 v37, v38, v39
	global_store_dwordx2 v[48:49], v[36:37], off offset:256
.LBB0_229:
	s_or_b64 exec, exec, s[22:23]
	ds_read_b64 v[36:37], v50 offset:1288
	ds_read_b64 v[38:39], v51 offset:776
	ds_read_b64 v[50:51], v52 offset:264
	s_waitcnt lgkmcnt(0)
	v_lshlrev_b32_e32 v46, 16, v36
	v_and_b32_e32 v47, 0xffff0000, v36
	v_lshlrev_b32_e32 v40, 16, v37
	v_and_b32_e32 v41, 0xffff0000, v37
	v_lshlrev_b32_e32 v44, 16, v38
	v_and_b32_e32 v45, 0xffff0000, v38
	v_lshlrev_b32_e32 v38, 16, v39
	v_and_b32_e32 v39, 0xffff0000, v39
	v_lshlrev_b32_e32 v42, 16, v50
	v_and_b32_e32 v43, 0xffff0000, v50
	v_lshlrev_b32_e32 v36, 16, v51
	v_and_b32_e32 v37, 0xffff0000, v51
	v_mov_b32_dpp v46, v32 row_shr:1 row_mask:0xf bank_mask:0xf
	v_mov_b32_dpp v44, v32 row_shr:2 row_mask:0xf bank_mask:0xf
	v_mov_b32_dpp v42, v32 row_shr:3 row_mask:0xf bank_mask:0xf
	v_mov_b32_dpp v47, v33 row_shr:1 row_mask:0xf bank_mask:0xf
	v_mov_b32_dpp v45, v33 row_shr:2 row_mask:0xf bank_mask:0xf
	v_mov_b32_dpp v43, v33 row_shr:3 row_mask:0xf bank_mask:0xf
	v_mov_b32_dpp v40, v34 row_shr:1 row_mask:0xf bank_mask:0xf
	v_mov_b32_dpp v38, v34 row_shr:2 row_mask:0xf bank_mask:0xf
	v_mov_b32_dpp v36, v34 row_shr:3 row_mask:0xf bank_mask:0xf
	v_mov_b32_dpp v41, v35 row_shr:1 row_mask:0xf bank_mask:0xf
	v_mov_b32_dpp v39, v35 row_shr:2 row_mask:0xf bank_mask:0xf
	v_mov_b32_dpp v37, v35 row_shr:3 row_mask:0xf bank_mask:0xf
	s_and_saveexec_b64 s[22:23], s[2:3]
	s_cbranch_execz .LBB0_231
	ds_read_b128 v[50:53], v238 offset:4624
	ds_read_b128 v[54:57], v238 offset:3600
	ds_read_b128 v[58:61], v238 offset:2576
	v_cndmask_b32_e64 v47, v47, 0, s[8:9]
	ds_read_b128 v[62:65], v238 offset:1552
	s_nop 0
	ds_read_b128 v[66:69], v238 offset:528
	v_cndmask_b32_e64 v46, v46, 0, s[8:9]
	v_cndmask_b32_e64 v45, 0, v45, s[6:7]
	v_cndmask_b32_e64 v44, 0, v44, s[6:7]
	v_cndmask_b32_e64 v43, 0, v43, s[4:5]
	v_cndmask_b32_e64 v42, 0, v42, s[4:5]
	v_cndmask_b32_e64 v41, v41, 0, s[8:9]
	v_cndmask_b32_e64 v40, v40, 0, s[8:9]
	v_cndmask_b32_e64 v39, 0, v39, s[6:7]
	v_cndmask_b32_e64 v38, 0, v38, s[6:7]
	v_cndmask_b32_e64 v37, 0, v37, s[4:5]
	v_cndmask_b32_e64 v36, 0, v36, s[4:5]
	s_waitcnt lgkmcnt(0)
	v_pk_fma_f32 v[32:33], v[32:33], v[54:55], v[50:51]
	v_pk_fma_f32 v[34:35], v[34:35], v[56:57], v[52:53]
	v_pk_fma_f32 v[32:33], v[46:47], v[58:59], v[32:33]
	v_pk_fma_f32 v[34:35], v[40:41], v[60:61], v[34:35]
	v_pk_fma_f32 v[32:33], v[44:45], v[62:63], v[32:33]
	s_nop 0
	v_pk_fma_f32 v[32:33], v[42:43], v[66:67], v[32:33]
	v_pk_fma_f32 v[34:35], v[38:39], v[64:65], v[34:35]
	v_mul_f32_e32 v42, 0xbfb8aa3b, v33
	v_exp_f32_e32 v42, v42
	v_pk_fma_f32 v[34:35], v[36:37], v[68:69], v[34:35]
	v_add_f32_e32 v42, 1.0, v42
	v_rcp_f32_e32 v43, v42
	v_mul_f32_e32 v42, 0xbfb8aa3b, v32
	v_exp_f32_e32 v42, v42
	s_nop 0
	v_add_f32_e32 v42, 1.0, v42
	v_rcp_f32_e32 v42, v42
	s_nop 0
	v_pk_mul_f32 v[32:33], v[32:33], v[42:43]
	s_nop 0
	v_cvt_pk_bf16_f32 v32, v32, v33
	v_mul_f32_e32 v33, 0xbfb8aa3b, v35
	v_exp_f32_e32 v33, v33
	s_nop 0
	v_add_f32_e32 v33, 1.0, v33
	v_rcp_f32_e32 v37, v33
	v_mul_f32_e32 v33, 0xbfb8aa3b, v34
	v_exp_f32_e32 v33, v33
	s_nop 0
	v_add_f32_e32 v33, 1.0, v33
	v_rcp_f32_e32 v36, v33
	s_nop 0
	v_pk_mul_f32 v[34:35], v[34:35], v[36:37]
	s_nop 0
	v_cvt_pk_bf16_f32 v33, v34, v35
	global_store_dwordx2 v[48:49], v[32:33], off offset:264
;     __device__ __forceinline__ void operator()(const f32x4 (&acc)[2][2][4][2], const Unit& u, int wr, int wc, int fr, int fq, LAS unsigned char* hb) const {
;     ...
;             for (int m = 0; m < 4; ++m) { asm volatile("" ::: "memory"); __builtin_amdgcn_sched_barrier(0);
;                 const int q = 8 * ai + 4 * wr + m, prev = q > 0 ? q - 1 : 0; const int lr = ai * HALF + wr * 64 + m * 16 + fr, R = R0 + lr;
;                 const int Rc = R < 0 ? 0 : R; const int b = Rc / LL, p = Rc - b * LL;
;                 const bool ok = (lr >= H && R < TT);
;                 const unsigned ooff = ((unsigned)Rc * (unsigned)LDP + (unsigned)(OFF_XBC + ch0)) * 2u;
; #pragma unroll
;                 for (int bn = 0; bn < 4; ++bn) { const int bj = bn >> 1, n = bn & 1; const int co = bj * HALF + 4 * n;
;                     const unsigned woff = (unsigned)(ch0 + co) * 4u;
;                     const f32x4 w0 = *(const f32x4*)((const char*)cw + woff), w1 = *(const f32x4*)((const char*)cw + woff + XBCW * 4), w2 = *(const f32x4*)((const char*)cw + woff + 2 * XBCW * 4), w3 = *(const f32x4*)((const char*)cw + woff + 3 * XBCW * 4), bs = *(const f32x4*)((const char*)cb + woff);
;                     const LAS unsigned char* hp = hb + (prev * H * NCH + chl + co) * 2;
;                     const u32x2 q1 = *(const LAS u32x2*)(hp + hr1 * NCH * 2), q2 = *(const LAS u32x2*)(hp + hr2 * NCH * 2), q3 = *(const LAS u32x2*)(hp + hr3 * NCH * 2);
;                     const float h1[4] = {__builtin_bit_cast(float, q1.x << 16), __builtin_bit_cast(float, q1.x & 0xffff0000u), __builtin_bit_cast(float, q1.y << 16), __builtin_bit_cast(float, q1.y & 0xffff0000u)};
;                     const float h2[4] = {__builtin_bit_cast(float, q2.x << 16), __builtin_bit_cast(float, q2.x & 0xffff0000u), __builtin_bit_cast(float, q2.y << 16), __builtin_bit_cast(float, q2.y & 0xffff0000u)};
;                     const float h3[4] = {__builtin_bit_cast(float, q3.x << 16), __builtin_bit_cast(float, q3.x & 0xffff0000u), __builtin_bit_cast(float, q3.y << 16), __builtin_bit_cast(float, q3.y & 0xffff0000u)};
;                     const f32x4 gv = acc[ai][bj][m][n];
;                     float o[4];
; #pragma unroll
;                     for (int j = 0; j < 4; ++j) { const float g = gv[j];
;                         float g1 = dpp_row_shr<1>(h1[j], g), g2 = dpp_row_shr<2>(h2[j], g), g3 = dpp_row_shr<3>(h3[j], g);
.LBB0_231:
	s_or_b64 exec, exec, s[22:23]
	v_add_u32_e32 v32, 0xa0, v161
	v_add_u32_e32 v33, s17, v32
	v_max_i32_e32 v34, 0, v33
	v_mul_hi_u32 v35, v34, s56
	v_lshrrev_b32_e32 v35, 11, v35
	v_cmp_lt_i32_e32 vcc, 2, v32
	v_mul_lo_u32 v32, v34, s51
	v_mul_u32_u24_e32 v35, 0x1010, v35
	v_add_lshl_u32 v136, v32, v164, 1
	v_add_u32_e32 v32, s43, v165
	v_sub_u32_e32 v35, v34, v35
	v_cmp_gt_i32_e64 s[4:5], s50, v33
	v_lshl_add_u32 v34, v32, 1, s53
	s_and_b64 s[2:3], vcc, s[4:5]
	v_cmp_eq_u32_e64 s[8:9], 0, v35
	v_cmp_lt_u32_e64 s[6:7], 1, v35
	v_cmp_lt_u32_e64 s[4:5], 2, v35
	v_add_u32_e32 v35, v34, v163
	ds_read_b64 v[32:33], v34 offset:1024
	v_add_u32_e32 v36, v34, v162
	ds_read_b64 v[50:51], v35 offset:512
	ds_read_b64 v[52:53], v36
	v_readlane_b32 s22, v237, 58
	v_readlane_b32 s23, v237, 59
	s_waitcnt lgkmcnt(0)
	v_lshlrev_b32_e32 v47, 16, v32
	v_and_b32_e32 v48, 0xffff0000, v32
	v_lshlrev_b32_e32 v41, 16, v33
	v_and_b32_e32 v42, 0xffff0000, v33
	v_lshlrev_b32_e32 v45, 16, v50
	v_and_b32_e32 v46, 0xffff0000, v50
	v_lshlrev_b32_e32 v39, 16, v51
	v_and_b32_e32 v40, 0xffff0000, v51
	v_lshlrev_b32_e32 v43, 16, v52
	v_and_b32_e32 v44, 0xffff0000, v52
	v_lshlrev_b32_e32 v37, 16, v53
	v_and_b32_e32 v38, 0xffff0000, v53
	v_mov_b32_dpp v47, v28 row_shr:1 row_mask:0xf bank_mask:0xf
	v_mov_b32_dpp v45, v28 row_shr:2 row_mask:0xf bank_mask:0xf
	v_mov_b32_dpp v43, v28 row_shr:3 row_mask:0xf bank_mask:0xf
	v_mov_b32_dpp v48, v29 row_shr:1 row_mask:0xf bank_mask:0xf
	v_mov_b32_dpp v46, v29 row_shr:2 row_mask:0xf bank_mask:0xf
	v_mov_b32_dpp v44, v29 row_shr:3 row_mask:0xf bank_mask:0xf
	v_mov_b32_dpp v41, v30 row_shr:1 row_mask:0xf bank_mask:0xf
	v_mov_b32_dpp v39, v30 row_shr:2 row_mask:0xf bank_mask:0xf
	v_mov_b32_dpp v37, v30 row_shr:3 row_mask:0xf bank_mask:0xf
	v_mov_b32_dpp v42, v31 row_shr:1 row_mask:0xf bank_mask:0xf
	v_mov_b32_dpp v40, v31 row_shr:2 row_mask:0xf bank_mask:0xf
	v_mov_b32_dpp v38, v31 row_shr:3 row_mask:0xf bank_mask:0xf
	v_lshl_add_u64 v[32:33], s[22:23], 0, v[136:137]
	s_and_saveexec_b64 s[22:23], s[2:3]
	s_cbranch_execz .LBB0_233
	ds_read_b128 v[50:53], v238 offset:4096
	ds_read_b128 v[54:57], v238 offset:3072
	ds_read_b128 v[58:61], v238 offset:2048
	v_cndmask_b32_e64 v49, v48, 0, s[8:9]
	ds_read_b128 v[62:65], v238 offset:1024
	s_nop 0
	ds_read_b128 v[66:69], v238
	v_cndmask_b32_e64 v48, v47, 0, s[8:9]
	v_cndmask_b32_e64 v47, 0, v46, s[6:7]
	v_cndmask_b32_e64 v46, 0, v45, s[6:7]
	v_cndmask_b32_e64 v45, 0, v44, s[4:5]
	v_cndmask_b32_e64 v44, 0, v43, s[4:5]
	s_waitcnt lgkmcnt(0)
	v_pk_fma_f32 v[28:29], v[28:29], v[54:55], v[50:51]
	v_pk_fma_f32 v[30:31], v[30:31], v[56:57], v[52:53]
	v_pk_fma_f32 v[28:29], v[48:49], v[58:59], v[28:29]
	s_nop 0
	v_pk_fma_f32 v[28:29], v[46:47], v[62:63], v[28:29]
	s_nop 0
	v_pk_fma_f32 v[28:29], v[44:45], v[66:67], v[28:29]
	s_nop 0
	v_mul_f32_e32 v43, 0xbfb8aa3b, v29
	v_exp_f32_e32 v43, v43
	s_nop 0
	v_add_f32_e32 v43, 1.0, v43
	v_rcp_f32_e32 v45, v43
	v_mul_f32_e32 v43, 0xbfb8aa3b, v28
	v_exp_f32_e32 v43, v43
	s_nop 0
	v_add_f32_e32 v43, 1.0, v43
	v_rcp_f32_e32 v44, v43
	v_cndmask_b32_e64 v43, v42, 0, s[8:9]
	v_cndmask_b32_e64 v42, v41, 0, s[8:9]
	v_pk_fma_f32 v[30:31], v[42:43], v[60:61], v[30:31]
	v_cndmask_b32_e64 v41, 0, v40, s[6:7]
	v_cndmask_b32_e64 v40, 0, v39, s[6:7]
	v_pk_fma_f32 v[30:31], v[40:41], v[64:65], v[30:31]
	v_cndmask_b32_e64 v39, 0, v38, s[4:5]
	v_cndmask_b32_e64 v38, 0, v37, s[4:5]
	v_pk_mul_f32 v[28:29], v[28:29], v[44:45]
	v_pk_fma_f32 v[30:31], v[38:39], v[68:69], v[30:31]
	v_cvt_pk_bf16_f32 v28, v28, v29
	v_mul_f32_e32 v29, 0xbfb8aa3b, v31
	v_exp_f32_e32 v29, v29
	s_nop 0
	v_add_f32_e32 v29, 1.0, v29
	v_rcp_f32_e32 v39, v29
	v_mul_f32_e32 v29, 0xbfb8aa3b, v30
	v_exp_f32_e32 v29, v29
	s_nop 0
	v_add_f32_e32 v29, 1.0, v29
	v_rcp_f32_e32 v38, v29
	s_nop 0
	v_pk_mul_f32 v[30:31], v[30:31], v[38:39]
	s_nop 0
	v_cvt_pk_bf16_f32 v29, v30, v31
	global_store_dwordx2 v[32:33], v[28:29], off
.LBB0_233:
	s_or_b64 exec, exec, s[22:23]
	ds_read_b64 v[28:29], v34 offset:1032
	ds_read_b64 v[30:31], v35 offset:520
	ds_read_b64 v[46:47], v36 offset:8
	s_waitcnt lgkmcnt(0)
	v_lshlrev_b32_e32 v43, 16, v28
	v_and_b32_e32 v44, 0xffff0000, v28
	v_lshlrev_b32_e32 v37, 16, v29
	v_and_b32_e32 v38, 0xffff0000, v29
	v_lshlrev_b32_e32 v41, 16, v30
	v_and_b32_e32 v42, 0xffff0000, v30
	v_lshlrev_b32_e32 v30, 16, v31
	v_and_b32_e32 v31, 0xffff0000, v31
	v_lshlrev_b32_e32 v39, 16, v46
	v_and_b32_e32 v40, 0xffff0000, v46
	v_lshlrev_b32_e32 v28, 16, v47
	v_and_b32_e32 v29, 0xffff0000, v47
	v_mov_b32_dpp v43, v24 row_shr:1 row_mask:0xf bank_mask:0xf
	v_mov_b32_dpp v41, v24 row_shr:2 row_mask:0xf bank_mask:0xf
	v_mov_b32_dpp v39, v24 row_shr:3 row_mask:0xf bank_mask:0xf
	v_mov_b32_dpp v44, v25 row_shr:1 row_mask:0xf bank_mask:0xf
	v_mov_b32_dpp v42, v25 row_shr:2 row_mask:0xf bank_mask:0xf
	v_mov_b32_dpp v40, v25 row_shr:3 row_mask:0xf bank_mask:0xf
	v_mov_b32_dpp v37, v26 row_shr:1 row_mask:0xf bank_mask:0xf
	v_mov_b32_dpp v30, v26 row_shr:2 row_mask:0xf bank_mask:0xf
	v_mov_b32_dpp v28, v26 row_shr:3 row_mask:0xf bank_mask:0xf
	v_mov_b32_dpp v38, v27 row_shr:1 row_mask:0xf bank_mask:0xf
	v_mov_b32_dpp v31, v27 row_shr:2 row_mask:0xf bank_mask:0xf
	v_mov_b32_dpp v29, v27 row_shr:3 row_mask:0xf bank_mask:0xf
	s_and_saveexec_b64 s[22:23], s[2:3]
	s_cbranch_execz .LBB0_235
;     __device__ __forceinline__ void operator()(const f32x4 (&acc)[2][2][4][2], const Unit& u, int wr, int wc, int fr, int fq, LAS unsigned char* hb) const {
;     ...
;             for (int m = 0; m < 4; ++m) { asm volatile("" ::: "memory"); __builtin_amdgcn_sched_barrier(0);
;                 const int q = 8 * ai + 4 * wr + m, prev = q > 0 ? q - 1 : 0; const int lr = ai * HALF + wr * 64 + m * 16 + fr, R = R0 + lr;
;                 const int Rc = R < 0 ? 0 : R; const int b = Rc / LL, p = Rc - b * LL;
;                 const bool ok = (lr >= H && R < TT);
;                 const unsigned ooff = ((unsigned)Rc * (unsigned)LDP + (unsigned)(OFF_XBC + ch0)) * 2u;
; #pragma unroll
;                 for (int bn = 0; bn < 4; ++bn) { const int bj = bn >> 1, n = bn & 1; const int co = bj * HALF + 4 * n;
;                     const unsigned woff = (unsigned)(ch0 + co) * 4u;
;                     const f32x4 w0 = *(const f32x4*)((const char*)cw + woff), w1 = *(const f32x4*)((const char*)cw + woff + XBCW * 4), w2 = *(const f32x4*)((const char*)cw + woff + 2 * XBCW * 4), w3 = *(const f32x4*)((const char*)cw + woff + 3 * XBCW * 4), bs = *(const f32x4*)((const char*)cb + woff);
;                     const LAS unsigned char* hp = hb + (prev * H * NCH + chl + co) * 2;
;                     const u32x2 q1 = *(const LAS u32x2*)(hp + hr1 * NCH * 2), q2 = *(const LAS u32x2*)(hp + hr2 * NCH * 2), q3 = *(const LAS u32x2*)(hp + hr3 * NCH * 2);
;                     const float h1[4] = {__builtin_bit_cast(float, q1.x << 16), __builtin_bit_cast(float, q1.x & 0xffff0000u), __builtin_bit_cast(float, q1.y << 16), __builtin_bit_cast(float, q1.y & 0xffff0000u)};
;                     const float h2[4] = {__builtin_bit_cast(float, q2.x << 16), __builtin_bit_cast(float, q2.x & 0xffff0000u), __builtin_bit_cast(float, q2.y << 16), __builtin_bit_cast(float, q2.y & 0xffff0000u)};
;                     const float h3[4] = {__builtin_bit_cast(float, q3.x << 16), __builtin_bit_cast(float, q3.x & 0xffff0000u), __builtin_bit_cast(float, q3.y << 16), __builtin_bit_cast(float, q3.y & 0xffff0000u)};
;                     const f32x4 gv = acc[ai][bj][m][n];
;                     float o[4];
; #pragma unroll
;                     for (int j = 0; j < 4; ++j) { const float g = gv[j];
;                         float g1 = dpp_row_shr<1>(h1[j], g), g2 = dpp_row_shr<2>(h2[j], g), g3 = dpp_row_shr<3>(h3[j], g);
	ds_read_b128 v[46:49], v238 offset:4112
	ds_read_b128 v[50:53], v238 offset:3088
	ds_read_b128 v[54:57], v238 offset:2064
	v_cndmask_b32_e64 v45, v44, 0, s[8:9]
	ds_read_b128 v[58:61], v238 offset:1040
	s_nop 0
	ds_read_b128 v[62:65], v238 offset:16
	v_cndmask_b32_e64 v44, v43, 0, s[8:9]
	v_cndmask_b32_e64 v43, 0, v42, s[6:7]
	v_cndmask_b32_e64 v42, 0, v41, s[6:7]
	v_cndmask_b32_e64 v41, 0, v40, s[4:5]
	v_cndmask_b32_e64 v40, 0, v39, s[4:5]
	v_cndmask_b32_e64 v31, 0, v31, s[6:7]
	v_cndmask_b32_e64 v30, 0, v30, s[6:7]
	v_cndmask_b32_e64 v29, 0, v29, s[4:5]
	v_cndmask_b32_e64 v28, 0, v28, s[4:5]
	s_waitcnt lgkmcnt(0)
	v_pk_fma_f32 v[24:25], v[24:25], v[50:51], v[46:47]
	v_pk_fma_f32 v[26:27], v[26:27], v[52:53], v[48:49]
	v_pk_fma_f32 v[24:25], v[44:45], v[54:55], v[24:25]
	s_nop 0
	v_pk_fma_f32 v[24:25], v[42:43], v[58:59], v[24:25]
	s_nop 0
	v_pk_fma_f32 v[24:25], v[40:41], v[62:63], v[24:25]
	s_nop 0
	v_mul_f32_e32 v39, 0xbfb8aa3b, v25
	v_exp_f32_e32 v39, v39
	s_nop 0
	v_add_f32_e32 v39, 1.0, v39
	v_rcp_f32_e32 v41, v39
	v_mul_f32_e32 v39, 0xbfb8aa3b, v24
	v_exp_f32_e32 v39, v39
	s_nop 0
	v_add_f32_e32 v39, 1.0, v39
	v_rcp_f32_e32 v40, v39
	v_cndmask_b32_e64 v39, v38, 0, s[8:9]
	v_cndmask_b32_e64 v38, v37, 0, s[8:9]
	v_pk_fma_f32 v[26:27], v[38:39], v[56:57], v[26:27]
	v_pk_mul_f32 v[24:25], v[24:25], v[40:41]
	v_pk_fma_f32 v[26:27], v[30:31], v[60:61], v[26:27]
	v_cvt_pk_bf16_f32 v24, v24, v25
	v_pk_fma_f32 v[26:27], v[28:29], v[64:65], v[26:27]
	s_nop 0
	v_mul_f32_e32 v25, 0xbfb8aa3b, v27
	v_exp_f32_e32 v25, v25
	s_nop 0
	v_add_f32_e32 v25, 1.0, v25
	v_rcp_f32_e32 v29, v25
	v_mul_f32_e32 v25, 0xbfb8aa3b, v26
	v_exp_f32_e32 v25, v25
	s_nop 0
	v_add_f32_e32 v25, 1.0, v25
	v_rcp_f32_e32 v28, v25
	s_nop 0
	v_pk_mul_f32 v[26:27], v[26:27], v[28:29]
	s_nop 0
	v_cvt_pk_bf16_f32 v25, v26, v27
	global_store_dwordx2 v[32:33], v[24:25], off offset:8
.LBB0_235:
	s_or_b64 exec, exec, s[22:23]
	ds_read_b64 v[24:25], v34 offset:1280
	ds_read_b64 v[26:27], v35 offset:768
	ds_read_b64 v[42:43], v36 offset:256
	s_waitcnt lgkmcnt(0)
	v_lshlrev_b32_e32 v39, 16, v24
	v_and_b32_e32 v40, 0xffff0000, v24
	v_lshlrev_b32_e32 v28, 16, v25
	v_and_b32_e32 v29, 0xffff0000, v25
	v_lshlrev_b32_e32 v37, 16, v26
	v_and_b32_e32 v38, 0xffff0000, v26
	v_lshlrev_b32_e32 v26, 16, v27
	v_and_b32_e32 v27, 0xffff0000, v27
	v_lshlrev_b32_e32 v30, 16, v42
	v_and_b32_e32 v31, 0xffff0000, v42
	v_lshlrev_b32_e32 v24, 16, v43
	v_and_b32_e32 v25, 0xffff0000, v43
	v_mov_b32_dpp v39, v20 row_shr:1 row_mask:0xf bank_mask:0xf
	v_mov_b32_dpp v37, v20 row_shr:2 row_mask:0xf bank_mask:0xf
	v_mov_b32_dpp v30, v20 row_shr:3 row_mask:0xf bank_mask:0xf
	v_mov_b32_dpp v40, v21 row_shr:1 row_mask:0xf bank_mask:0xf
	v_mov_b32_dpp v38, v21 row_shr:2 row_mask:0xf bank_mask:0xf
	v_mov_b32_dpp v31, v21 row_shr:3 row_mask:0xf bank_mask:0xf
	v_mov_b32_dpp v28, v22 row_shr:1 row_mask:0xf bank_mask:0xf
	v_mov_b32_dpp v26, v22 row_shr:2 row_mask:0xf bank_mask:0xf
	v_mov_b32_dpp v24, v22 row_shr:3 row_mask:0xf bank_mask:0xf
	v_mov_b32_dpp v29, v23 row_shr:1 row_mask:0xf bank_mask:0xf
	v_mov_b32_dpp v27, v23 row_shr:2 row_mask:0xf bank_mask:0xf
	v_mov_b32_dpp v25, v23 row_shr:3 row_mask:0xf bank_mask:0xf
	s_and_saveexec_b64 s[22:23], s[2:3]
	s_cbranch_execz .LBB0_237
	ds_read_b128 v[42:45], v238 offset:4608
	ds_read_b128 v[46:49], v238 offset:3584
	ds_read_b128 v[50:53], v238 offset:2560
	v_cndmask_b32_e64 v41, v40, 0, s[8:9]
	ds_read_b128 v[54:57], v238 offset:1536
	s_nop 0
	ds_read_b128 v[58:61], v238 offset:512
	v_cndmask_b32_e64 v40, v39, 0, s[8:9]
	v_cndmask_b32_e64 v39, 0, v38, s[6:7]
	v_cndmask_b32_e64 v38, 0, v37, s[6:7]
	v_cndmask_b32_e64 v31, 0, v31, s[4:5]
	v_cndmask_b32_e64 v30, 0, v30, s[4:5]
	v_cndmask_b32_e64 v29, v29, 0, s[8:9]
	v_cndmask_b32_e64 v28, v28, 0, s[8:9]
	v_cndmask_b32_e64 v27, 0, v27, s[6:7]
	v_cndmask_b32_e64 v26, 0, v26, s[6:7]
	v_cndmask_b32_e64 v25, 0, v25, s[4:5]
	v_cndmask_b32_e64 v24, 0, v24, s[4:5]
	s_waitcnt lgkmcnt(0)
	v_pk_fma_f32 v[20:21], v[20:21], v[46:47], v[42:43]
	v_pk_fma_f32 v[22:23], v[22:23], v[48:49], v[44:45]
	v_pk_fma_f32 v[20:21], v[40:41], v[50:51], v[20:21]
	v_pk_fma_f32 v[22:23], v[28:29], v[52:53], v[22:23]
	v_pk_fma_f32 v[20:21], v[38:39], v[54:55], v[20:21]
	s_nop 0
	v_pk_fma_f32 v[20:21], v[30:31], v[58:59], v[20:21]
	v_pk_fma_f32 v[22:23], v[26:27], v[56:57], v[22:23]
	v_mul_f32_e32 v30, 0xbfb8aa3b, v21
	v_exp_f32_e32 v30, v30
	v_pk_fma_f32 v[22:23], v[24:25], v[60:61], v[22:23]
	v_add_f32_e32 v30, 1.0, v30
	v_rcp_f32_e32 v31, v30
	v_mul_f32_e32 v30, 0xbfb8aa3b, v20
	v_exp_f32_e32 v30, v30
	s_nop 0
	v_add_f32_e32 v30, 1.0, v30
	v_rcp_f32_e32 v30, v30
	s_nop 0
	v_pk_mul_f32 v[20:21], v[20:21], v[30:31]
	s_nop 0
	v_cvt_pk_bf16_f32 v20, v20, v21
	v_mul_f32_e32 v21, 0xbfb8aa3b, v23
	v_exp_f32_e32 v21, v21
	s_nop 0
	v_add_f32_e32 v21, 1.0, v21
	v_rcp_f32_e32 v25, v21
	v_mul_f32_e32 v21, 0xbfb8aa3b, v22
	v_exp_f32_e32 v21, v21
	s_nop 0
	v_add_f32_e32 v21, 1.0, v21
	v_rcp_f32_e32 v24, v21
	s_nop 0
	v_pk_mul_f32 v[22:23], v[22:23], v[24:25]
	s_nop 0
	v_cvt_pk_bf16_f32 v21, v22, v23
	global_store_dwordx2 v[32:33], v[20:21], off offset:256
;     __device__ __forceinline__ void operator()(const f32x4 (&acc)[2][2][4][2], const Unit& u, int wr, int wc, int fr, int fq, LAS unsigned char* hb) const {
;     ...
;             for (int m = 0; m < 4; ++m) { asm volatile("" ::: "memory"); __builtin_amdgcn_sched_barrier(0);
;                 const int q = 8 * ai + 4 * wr + m, prev = q > 0 ? q - 1 : 0; const int lr = ai * HALF + wr * 64 + m * 16 + fr, R = R0 + lr;
;                 const int Rc = R < 0 ? 0 : R; const int b = Rc / LL, p = Rc - b * LL;
;                 const bool ok = (lr >= H && R < TT);
;                 const unsigned ooff = ((unsigned)Rc * (unsigned)LDP + (unsigned)(OFF_XBC + ch0)) * 2u;
; #pragma unroll
;                 for (int bn = 0; bn < 4; ++bn) { const int bj = bn >> 1, n = bn & 1; const int co = bj * HALF + 4 * n;
;                     const unsigned woff = (unsigned)(ch0 + co) * 4u;
;                     const f32x4 w0 = *(const f32x4*)((const char*)cw + woff), w1 = *(const f32x4*)((const char*)cw + woff + XBCW * 4), w2 = *(const f32x4*)((const char*)cw + woff + 2 * XBCW * 4), w3 = *(const f32x4*)((const char*)cw + woff + 3 * XBCW * 4), bs = *(const f32x4*)((const char*)cb + woff);
;                     const LAS unsigned char* hp = hb + (prev * H * NCH + chl + co) * 2;
;                     const u32x2 q1 = *(const LAS u32x2*)(hp + hr1 * NCH * 2), q2 = *(const LAS u32x2*)(hp + hr2 * NCH * 2), q3 = *(const LAS u32x2*)(hp + hr3 * NCH * 2);
;                     const float h1[4] = {__builtin_bit_cast(float, q1.x << 16), __builtin_bit_cast(float, q1.x & 0xffff0000u), __builtin_bit_cast(float, q1.y << 16), __builtin_bit_cast(float, q1.y & 0xffff0000u)};
;                     const float h2[4] = {__builtin_bit_cast(float, q2.x << 16), __builtin_bit_cast(float, q2.x & 0xffff0000u), __builtin_bit_cast(float, q2.y << 16), __builtin_bit_cast(float, q2.y & 0xffff0000u)};
;                     const float h3[4] = {__builtin_bit_cast(float, q3.x << 16), __builtin_bit_cast(float, q3.x & 0xffff0000u), __builtin_bit_cast(float, q3.y << 16), __builtin_bit_cast(float, q3.y & 0xffff0000u)};
;                     const f32x4 gv = acc[ai][bj][m][n];
;                     float o[4];
; #pragma unroll
;                     for (int j = 0; j < 4; ++j) { const float g = gv[j];
;                         float g1 = dpp_row_shr<1>(h1[j], g), g2 = dpp_row_shr<2>(h2[j], g), g3 = dpp_row_shr<3>(h3[j], g);
.LBB0_237:
	s_or_b64 exec, exec, s[22:23]
	ds_read_b64 v[20:21], v34 offset:1288
	ds_read_b64 v[22:23], v35 offset:776
	ds_read_b64 v[34:35], v36 offset:264
	s_waitcnt lgkmcnt(0)
	v_lshlrev_b32_e32 v30, 16, v20
	v_and_b32_e32 v31, 0xffff0000, v20
	v_lshlrev_b32_e32 v24, 16, v21
	v_and_b32_e32 v25, 0xffff0000, v21
	v_lshlrev_b32_e32 v28, 16, v22
	v_and_b32_e32 v29, 0xffff0000, v22
	v_lshlrev_b32_e32 v22, 16, v23
	v_and_b32_e32 v23, 0xffff0000, v23
	v_lshlrev_b32_e32 v26, 16, v34
	v_and_b32_e32 v27, 0xffff0000, v34
	v_lshlrev_b32_e32 v20, 16, v35
	v_and_b32_e32 v21, 0xffff0000, v35
	v_mov_b32_dpp v30, v16 row_shr:1 row_mask:0xf bank_mask:0xf
	v_mov_b32_dpp v28, v16 row_shr:2 row_mask:0xf bank_mask:0xf
	v_mov_b32_dpp v26, v16 row_shr:3 row_mask:0xf bank_mask:0xf
	v_mov_b32_dpp v31, v17 row_shr:1 row_mask:0xf bank_mask:0xf
	v_mov_b32_dpp v29, v17 row_shr:2 row_mask:0xf bank_mask:0xf
	v_mov_b32_dpp v27, v17 row_shr:3 row_mask:0xf bank_mask:0xf
	v_mov_b32_dpp v24, v18 row_shr:1 row_mask:0xf bank_mask:0xf
	v_mov_b32_dpp v22, v18 row_shr:2 row_mask:0xf bank_mask:0xf
	v_mov_b32_dpp v20, v18 row_shr:3 row_mask:0xf bank_mask:0xf
	v_mov_b32_dpp v25, v19 row_shr:1 row_mask:0xf bank_mask:0xf
	v_mov_b32_dpp v23, v19 row_shr:2 row_mask:0xf bank_mask:0xf
	v_mov_b32_dpp v21, v19 row_shr:3 row_mask:0xf bank_mask:0xf
	s_and_saveexec_b64 s[22:23], s[2:3]
	s_cbranch_execz .LBB0_239
	ds_read_b128 v[34:37], v238 offset:4624
	ds_read_b128 v[38:41], v238 offset:3600
	ds_read_b128 v[42:45], v238 offset:2576
	v_cndmask_b32_e64 v31, v31, 0, s[8:9]
	ds_read_b128 v[46:49], v238 offset:1552
	s_nop 0
	ds_read_b128 v[50:53], v238 offset:528
	v_cndmask_b32_e64 v30, v30, 0, s[8:9]
	v_cndmask_b32_e64 v29, 0, v29, s[6:7]
	v_cndmask_b32_e64 v28, 0, v28, s[6:7]
	v_cndmask_b32_e64 v27, 0, v27, s[4:5]
	v_cndmask_b32_e64 v26, 0, v26, s[4:5]
	v_cndmask_b32_e64 v25, v25, 0, s[8:9]
	v_cndmask_b32_e64 v24, v24, 0, s[8:9]
	v_cndmask_b32_e64 v23, 0, v23, s[6:7]
	v_cndmask_b32_e64 v22, 0, v22, s[6:7]
	v_cndmask_b32_e64 v21, 0, v21, s[4:5]
	v_cndmask_b32_e64 v20, 0, v20, s[4:5]
	s_waitcnt lgkmcnt(0)
	v_pk_fma_f32 v[16:17], v[16:17], v[38:39], v[34:35]
	v_pk_fma_f32 v[18:19], v[18:19], v[40:41], v[36:37]
	v_pk_fma_f32 v[16:17], v[30:31], v[42:43], v[16:17]
	v_pk_fma_f32 v[18:19], v[24:25], v[44:45], v[18:19]
	v_pk_fma_f32 v[16:17], v[28:29], v[46:47], v[16:17]
	s_nop 0
	v_pk_fma_f32 v[16:17], v[26:27], v[50:51], v[16:17]
	v_pk_fma_f32 v[18:19], v[22:23], v[48:49], v[18:19]
	v_mul_f32_e32 v26, 0xbfb8aa3b, v17
	v_exp_f32_e32 v26, v26
	v_pk_fma_f32 v[18:19], v[20:21], v[52:53], v[18:19]
	v_add_f32_e32 v26, 1.0, v26
	v_rcp_f32_e32 v27, v26
	v_mul_f32_e32 v26, 0xbfb8aa3b, v16
	v_exp_f32_e32 v26, v26
	s_nop 0
	v_add_f32_e32 v26, 1.0, v26
	v_rcp_f32_e32 v26, v26
	s_nop 0
	v_pk_mul_f32 v[16:17], v[16:17], v[26:27]
	s_nop 0
	v_cvt_pk_bf16_f32 v16, v16, v17
	v_mul_f32_e32 v17, 0xbfb8aa3b, v19
	v_exp_f32_e32 v17, v17
	s_nop 0
	v_add_f32_e32 v17, 1.0, v17
	v_rcp_f32_e32 v21, v17
	v_mul_f32_e32 v17, 0xbfb8aa3b, v18
	v_exp_f32_e32 v17, v17
	s_nop 0
	v_add_f32_e32 v17, 1.0, v17
	v_rcp_f32_e32 v20, v17
	s_nop 0
	v_pk_mul_f32 v[18:19], v[18:19], v[20:21]
	s_nop 0
	v_cvt_pk_bf16_f32 v17, v18, v19
	global_store_dwordx2 v[32:33], v[16:17], off offset:264
.LBB0_239:
	s_or_b64 exec, exec, s[22:23]
	v_add_u32_e32 v16, 0xb0, v161
	v_add_u32_e32 v17, s17, v16
	v_max_i32_e32 v18, 0, v17
	v_mul_hi_u32 v19, v18, s56
	v_lshrrev_b32_e32 v19, 11, v19
	v_cmp_lt_i32_e32 vcc, 2, v16
	v_mul_lo_u32 v16, v18, s51
	v_mul_u32_u24_e32 v19, 0x1010, v19
	v_add_lshl_u32 v136, v16, v164, 1
	v_add_u32_e32 v16, s44, v165
	v_sub_u32_e32 v19, v18, v19
	v_cmp_gt_i32_e64 s[4:5], s50, v17
	v_lshl_add_u32 v18, v16, 1, s53
	s_and_b64 s[2:3], vcc, s[4:5]
	v_cmp_eq_u32_e64 s[8:9], 0, v19
	v_cmp_lt_u32_e64 s[6:7], 1, v19
	v_cmp_lt_u32_e64 s[4:5], 2, v19
	v_add_u32_e32 v19, v18, v163
	ds_read_b64 v[16:17], v18 offset:1024
	v_add_u32_e32 v20, v18, v162
	ds_read_b64 v[34:35], v19 offset:512
	ds_read_b64 v[36:37], v20
	v_readlane_b32 s22, v237, 58
	v_readlane_b32 s23, v237, 59
	s_waitcnt lgkmcnt(0)
	v_lshlrev_b32_e32 v31, 16, v16
	v_and_b32_e32 v32, 0xffff0000, v16
	v_lshlrev_b32_e32 v25, 16, v17
	v_and_b32_e32 v26, 0xffff0000, v17
	v_lshlrev_b32_e32 v29, 16, v34
	v_and_b32_e32 v30, 0xffff0000, v34
	v_lshlrev_b32_e32 v23, 16, v35
	v_and_b32_e32 v24, 0xffff0000, v35
	v_lshlrev_b32_e32 v27, 16, v36
	v_and_b32_e32 v28, 0xffff0000, v36
	v_lshlrev_b32_e32 v21, 16, v37
	v_and_b32_e32 v22, 0xffff0000, v37
	v_mov_b32_dpp v31, v12 row_shr:1 row_mask:0xf bank_mask:0xf
	v_mov_b32_dpp v29, v12 row_shr:2 row_mask:0xf bank_mask:0xf
	v_mov_b32_dpp v27, v12 row_shr:3 row_mask:0xf bank_mask:0xf
	v_mov_b32_dpp v32, v13 row_shr:1 row_mask:0xf bank_mask:0xf
	v_mov_b32_dpp v30, v13 row_shr:2 row_mask:0xf bank_mask:0xf
	v_mov_b32_dpp v28, v13 row_shr:3 row_mask:0xf bank_mask:0xf
	v_mov_b32_dpp v25, v14 row_shr:1 row_mask:0xf bank_mask:0xf
	v_mov_b32_dpp v23, v14 row_shr:2 row_mask:0xf bank_mask:0xf
	v_mov_b32_dpp v21, v14 row_shr:3 row_mask:0xf bank_mask:0xf
	v_mov_b32_dpp v26, v15 row_shr:1 row_mask:0xf bank_mask:0xf
	v_mov_b32_dpp v24, v15 row_shr:2 row_mask:0xf bank_mask:0xf
	v_mov_b32_dpp v22, v15 row_shr:3 row_mask:0xf bank_mask:0xf
	v_lshl_add_u64 v[16:17], s[22:23], 0, v[136:137]
	s_and_saveexec_b64 s[22:23], s[2:3]
	s_cbranch_execz .LBB0_241
;     __device__ __forceinline__ void operator()(const f32x4 (&acc)[2][2][4][2], const Unit& u, int wr, int wc, int fr, int fq, LAS unsigned char* hb) const {
;     ...
;             for (int m = 0; m < 4; ++m) { asm volatile("" ::: "memory"); __builtin_amdgcn_sched_barrier(0);
;                 const int q = 8 * ai + 4 * wr + m, prev = q > 0 ? q - 1 : 0; const int lr = ai * HALF + wr * 64 + m * 16 + fr, R = R0 + lr;
;                 const int Rc = R < 0 ? 0 : R; const int b = Rc / LL, p = Rc - b * LL;
;                 const bool ok = (lr >= H && R < TT);
;                 const unsigned ooff = ((unsigned)Rc * (unsigned)LDP + (unsigned)(OFF_XBC + ch0)) * 2u;
; #pragma unroll
;                 for (int bn = 0; bn < 4; ++bn) { const int bj = bn >> 1, n = bn & 1; const int co = bj * HALF + 4 * n;
;                     const unsigned woff = (unsigned)(ch0 + co) * 4u;
;                     const f32x4 w0 = *(const f32x4*)((const char*)cw + woff), w1 = *(const f32x4*)((const char*)cw + woff + XBCW * 4), w2 = *(const f32x4*)((const char*)cw + woff + 2 * XBCW * 4), w3 = *(const f32x4*)((const char*)cw + woff + 3 * XBCW * 4), bs = *(const f32x4*)((const char*)cb + woff);
;                     const LAS unsigned char* hp = hb + (prev * H * NCH + chl + co) * 2;
;                     const u32x2 q1 = *(const LAS u32x2*)(hp + hr1 * NCH * 2), q2 = *(const LAS u32x2*)(hp + hr2 * NCH * 2), q3 = *(const LAS u32x2*)(hp + hr3 * NCH * 2);
;                     const float h1[4] = {__builtin_bit_cast(float, q1.x << 16), __builtin_bit_cast(float, q1.x & 0xffff0000u), __builtin_bit_cast(float, q1.y << 16), __builtin_bit_cast(float, q1.y & 0xffff0000u)};
;                     const float h2[4] = {__builtin_bit_cast(float, q2.x << 16), __builtin_bit_cast(float, q2.x & 0xffff0000u), __builtin_bit_cast(float, q2.y << 16), __builtin_bit_cast(float, q2.y & 0xffff0000u)};
;                     const float h3[4] = {__builtin_bit_cast(float, q3.x << 16), __builtin_bit_cast(float, q3.x & 0xffff0000u), __builtin_bit_cast(float, q3.y << 16), __builtin_bit_cast(float, q3.y & 0xffff0000u)};
;                     const f32x4 gv = acc[ai][bj][m][n];
;                     float o[4];
; #pragma unroll
;                     for (int j = 0; j < 4; ++j) { const float g = gv[j];
;                         float g1 = dpp_row_shr<1>(h1[j], g), g2 = dpp_row_shr<2>(h2[j], g), g3 = dpp_row_shr<3>(h3[j], g);
	ds_read_b128 v[34:37], v238 offset:4096
	ds_read_b128 v[38:41], v238 offset:3072
	ds_read_b128 v[42:45], v238 offset:2048
	v_cndmask_b32_e64 v33, v32, 0, s[8:9]
	ds_read_b128 v[46:49], v238 offset:1024
	s_nop 0
	ds_read_b128 v[50:53], v238
	v_cndmask_b32_e64 v32, v31, 0, s[8:9]
	v_cndmask_b32_e64 v31, 0, v30, s[6:7]
	v_cndmask_b32_e64 v30, 0, v29, s[6:7]
	v_cndmask_b32_e64 v29, 0, v28, s[4:5]
	v_cndmask_b32_e64 v28, 0, v27, s[4:5]
	s_waitcnt lgkmcnt(0)
	v_pk_fma_f32 v[12:13], v[12:13], v[38:39], v[34:35]
	v_pk_fma_f32 v[14:15], v[14:15], v[40:41], v[36:37]
	v_pk_fma_f32 v[12:13], v[32:33], v[42:43], v[12:13]
	s_nop 0
	v_pk_fma_f32 v[12:13], v[30:31], v[46:47], v[12:13]
	s_nop 0
	v_pk_fma_f32 v[12:13], v[28:29], v[50:51], v[12:13]
	s_nop 0
	v_mul_f32_e32 v27, 0xbfb8aa3b, v13
	v_exp_f32_e32 v27, v27
	s_nop 0
	v_add_f32_e32 v27, 1.0, v27
	v_rcp_f32_e32 v29, v27
	v_mul_f32_e32 v27, 0xbfb8aa3b, v12
	v_exp_f32_e32 v27, v27
	s_nop 0
	v_add_f32_e32 v27, 1.0, v27
	v_rcp_f32_e32 v28, v27
	v_cndmask_b32_e64 v27, v26, 0, s[8:9]
	v_cndmask_b32_e64 v26, v25, 0, s[8:9]
	v_pk_fma_f32 v[14:15], v[26:27], v[44:45], v[14:15]
	v_cndmask_b32_e64 v25, 0, v24, s[6:7]
	v_cndmask_b32_e64 v24, 0, v23, s[6:7]
	v_pk_fma_f32 v[14:15], v[24:25], v[48:49], v[14:15]
	v_cndmask_b32_e64 v23, 0, v22, s[4:5]
	v_cndmask_b32_e64 v22, 0, v21, s[4:5]
	v_pk_mul_f32 v[12:13], v[12:13], v[28:29]
	v_pk_fma_f32 v[14:15], v[22:23], v[52:53], v[14:15]
	v_cvt_pk_bf16_f32 v12, v12, v13
	v_mul_f32_e32 v13, 0xbfb8aa3b, v15
	v_exp_f32_e32 v13, v13
	s_nop 0
	v_add_f32_e32 v13, 1.0, v13
	v_rcp_f32_e32 v23, v13
	v_mul_f32_e32 v13, 0xbfb8aa3b, v14
	v_exp_f32_e32 v13, v13
	s_nop 0
	v_add_f32_e32 v13, 1.0, v13
	v_rcp_f32_e32 v22, v13
	s_nop 0
	v_pk_mul_f32 v[14:15], v[14:15], v[22:23]
	s_nop 0
	v_cvt_pk_bf16_f32 v13, v14, v15
	global_store_dwordx2 v[16:17], v[12:13], off
.LBB0_241:
	s_or_b64 exec, exec, s[22:23]
	ds_read_b64 v[12:13], v18 offset:1032
	ds_read_b64 v[14:15], v19 offset:520
	ds_read_b64 v[30:31], v20 offset:8
	s_waitcnt lgkmcnt(0)
	v_lshlrev_b32_e32 v27, 16, v12
	v_and_b32_e32 v28, 0xffff0000, v12
	v_lshlrev_b32_e32 v21, 16, v13
	v_and_b32_e32 v22, 0xffff0000, v13
	v_lshlrev_b32_e32 v25, 16, v14
	v_and_b32_e32 v26, 0xffff0000, v14
	v_lshlrev_b32_e32 v14, 16, v15
	v_and_b32_e32 v15, 0xffff0000, v15
	v_lshlrev_b32_e32 v23, 16, v30
	v_and_b32_e32 v24, 0xffff0000, v30
	v_lshlrev_b32_e32 v12, 16, v31
	v_and_b32_e32 v13, 0xffff0000, v31
	v_mov_b32_dpp v27, v8 row_shr:1 row_mask:0xf bank_mask:0xf
	v_mov_b32_dpp v25, v8 row_shr:2 row_mask:0xf bank_mask:0xf
	v_mov_b32_dpp v23, v8 row_shr:3 row_mask:0xf bank_mask:0xf
	v_mov_b32_dpp v28, v9 row_shr:1 row_mask:0xf bank_mask:0xf
	v_mov_b32_dpp v26, v9 row_shr:2 row_mask:0xf bank_mask:0xf
	v_mov_b32_dpp v24, v9 row_shr:3 row_mask:0xf bank_mask:0xf
	v_mov_b32_dpp v21, v10 row_shr:1 row_mask:0xf bank_mask:0xf
	v_mov_b32_dpp v14, v10 row_shr:2 row_mask:0xf bank_mask:0xf
	v_mov_b32_dpp v12, v10 row_shr:3 row_mask:0xf bank_mask:0xf
	v_mov_b32_dpp v22, v11 row_shr:1 row_mask:0xf bank_mask:0xf
	v_mov_b32_dpp v15, v11 row_shr:2 row_mask:0xf bank_mask:0xf
	v_mov_b32_dpp v13, v11 row_shr:3 row_mask:0xf bank_mask:0xf
	s_and_saveexec_b64 s[22:23], s[2:3]
	s_cbranch_execz .LBB0_243
	ds_read_b128 v[30:33], v238 offset:4112
	ds_read_b128 v[34:37], v238 offset:3088
	ds_read_b128 v[38:41], v238 offset:2064
	v_cndmask_b32_e64 v29, v28, 0, s[8:9]
	ds_read_b128 v[42:45], v238 offset:1040
	s_nop 0
	ds_read_b128 v[46:49], v238 offset:16
	v_cndmask_b32_e64 v28, v27, 0, s[8:9]
	v_cndmask_b32_e64 v27, 0, v26, s[6:7]
	v_cndmask_b32_e64 v26, 0, v25, s[6:7]
	v_cndmask_b32_e64 v25, 0, v24, s[4:5]
	v_cndmask_b32_e64 v24, 0, v23, s[4:5]
	v_cndmask_b32_e64 v15, 0, v15, s[6:7]
	v_cndmask_b32_e64 v14, 0, v14, s[6:7]
	v_cndmask_b32_e64 v13, 0, v13, s[4:5]
	v_cndmask_b32_e64 v12, 0, v12, s[4:5]
	s_waitcnt lgkmcnt(0)
	v_pk_fma_f32 v[8:9], v[8:9], v[34:35], v[30:31]
	v_pk_fma_f32 v[10:11], v[10:11], v[36:37], v[32:33]
	v_pk_fma_f32 v[8:9], v[28:29], v[38:39], v[8:9]
	s_nop 0
	v_pk_fma_f32 v[8:9], v[26:27], v[42:43], v[8:9]
	s_nop 0
	v_pk_fma_f32 v[8:9], v[24:25], v[46:47], v[8:9]
	s_nop 0
	v_mul_f32_e32 v23, 0xbfb8aa3b, v9
	v_exp_f32_e32 v23, v23
	s_nop 0
	v_add_f32_e32 v23, 1.0, v23
	v_rcp_f32_e32 v25, v23
	v_mul_f32_e32 v23, 0xbfb8aa3b, v8
	v_exp_f32_e32 v23, v23
	s_nop 0
	v_add_f32_e32 v23, 1.0, v23
	v_rcp_f32_e32 v24, v23
	v_cndmask_b32_e64 v23, v22, 0, s[8:9]
	v_cndmask_b32_e64 v22, v21, 0, s[8:9]
	v_pk_fma_f32 v[10:11], v[22:23], v[40:41], v[10:11]
	v_pk_mul_f32 v[8:9], v[8:9], v[24:25]
	v_pk_fma_f32 v[10:11], v[14:15], v[44:45], v[10:11]
	v_cvt_pk_bf16_f32 v8, v8, v9
	v_pk_fma_f32 v[10:11], v[12:13], v[48:49], v[10:11]
	s_nop 0
	v_mul_f32_e32 v9, 0xbfb8aa3b, v11
	v_exp_f32_e32 v9, v9
	s_nop 0
	v_add_f32_e32 v9, 1.0, v9
	v_rcp_f32_e32 v13, v9
	v_mul_f32_e32 v9, 0xbfb8aa3b, v10
	v_exp_f32_e32 v9, v9
	s_nop 0
	v_add_f32_e32 v9, 1.0, v9
	v_rcp_f32_e32 v12, v9
	s_nop 0
	v_pk_mul_f32 v[10:11], v[10:11], v[12:13]
	s_nop 0
	v_cvt_pk_bf16_f32 v9, v10, v11
	global_store_dwordx2 v[16:17], v[8:9], off offset:8
;     __device__ __forceinline__ void operator()(const f32x4 (&acc)[2][2][4][2], const Unit& u, int wr, int wc, int fr, int fq, LAS unsigned char* hb) const {
;     ...
;             for (int m = 0; m < 4; ++m) { asm volatile("" ::: "memory"); __builtin_amdgcn_sched_barrier(0);
;                 const int q = 8 * ai + 4 * wr + m, prev = q > 0 ? q - 1 : 0; const int lr = ai * HALF + wr * 64 + m * 16 + fr, R = R0 + lr;
;                 const int Rc = R < 0 ? 0 : R; const int b = Rc / LL, p = Rc - b * LL;
;                 const bool ok = (lr >= H && R < TT);
;                 const unsigned ooff = ((unsigned)Rc * (unsigned)LDP + (unsigned)(OFF_XBC + ch0)) * 2u;
; #pragma unroll
;                 for (int bn = 0; bn < 4; ++bn) { const int bj = bn >> 1, n = bn & 1; const int co = bj * HALF + 4 * n;
;                     const unsigned woff = (unsigned)(ch0 + co) * 4u;
;                     const f32x4 w0 = *(const f32x4*)((const char*)cw + woff), w1 = *(const f32x4*)((const char*)cw + woff + XBCW * 4), w2 = *(const f32x4*)((const char*)cw + woff + 2 * XBCW * 4), w3 = *(const f32x4*)((const char*)cw + woff + 3 * XBCW * 4), bs = *(const f32x4*)((const char*)cb + woff);
;                     const LAS unsigned char* hp = hb + (prev * H * NCH + chl + co) * 2;
;                     const u32x2 q1 = *(const LAS u32x2*)(hp + hr1 * NCH * 2), q2 = *(const LAS u32x2*)(hp + hr2 * NCH * 2), q3 = *(const LAS u32x2*)(hp + hr3 * NCH * 2);
;                     const float h1[4] = {__builtin_bit_cast(float, q1.x << 16), __builtin_bit_cast(float, q1.x & 0xffff0000u), __builtin_bit_cast(float, q1.y << 16), __builtin_bit_cast(float, q1.y & 0xffff0000u)};
;                     const float h2[4] = {__builtin_bit_cast(float, q2.x << 16), __builtin_bit_cast(float, q2.x & 0xffff0000u), __builtin_bit_cast(float, q2.y << 16), __builtin_bit_cast(float, q2.y & 0xffff0000u)};
;                     const float h3[4] = {__builtin_bit_cast(float, q3.x << 16), __builtin_bit_cast(float, q3.x & 0xffff0000u), __builtin_bit_cast(float, q3.y << 16), __builtin_bit_cast(float, q3.y & 0xffff0000u)};
;                     const f32x4 gv = acc[ai][bj][m][n];
;                     float o[4];
; #pragma unroll
;                     for (int j = 0; j < 4; ++j) { const float g = gv[j];
;                         float g1 = dpp_row_shr<1>(h1[j], g), g2 = dpp_row_shr<2>(h2[j], g), g3 = dpp_row_shr<3>(h3[j], g);
.LBB0_243:
	s_or_b64 exec, exec, s[22:23]
	ds_read_b64 v[8:9], v18 offset:1280
	ds_read_b64 v[10:11], v19 offset:768
	ds_read_b64 v[26:27], v20 offset:256
	s_waitcnt lgkmcnt(0)
	v_lshlrev_b32_e32 v23, 16, v8
	v_and_b32_e32 v24, 0xffff0000, v8
	v_lshlrev_b32_e32 v12, 16, v9
	v_and_b32_e32 v13, 0xffff0000, v9
	v_lshlrev_b32_e32 v21, 16, v10
	v_and_b32_e32 v22, 0xffff0000, v10
	v_lshlrev_b32_e32 v10, 16, v11
	v_and_b32_e32 v11, 0xffff0000, v11
	v_lshlrev_b32_e32 v14, 16, v26
	v_and_b32_e32 v15, 0xffff0000, v26
	v_lshlrev_b32_e32 v8, 16, v27
	v_and_b32_e32 v9, 0xffff0000, v27
	v_mov_b32_dpp v23, v4 row_shr:1 row_mask:0xf bank_mask:0xf
	v_mov_b32_dpp v21, v4 row_shr:2 row_mask:0xf bank_mask:0xf
	v_mov_b32_dpp v14, v4 row_shr:3 row_mask:0xf bank_mask:0xf
	v_mov_b32_dpp v24, v5 row_shr:1 row_mask:0xf bank_mask:0xf
	v_mov_b32_dpp v22, v5 row_shr:2 row_mask:0xf bank_mask:0xf
	v_mov_b32_dpp v15, v5 row_shr:3 row_mask:0xf bank_mask:0xf
	v_mov_b32_dpp v12, v6 row_shr:1 row_mask:0xf bank_mask:0xf
	v_mov_b32_dpp v10, v6 row_shr:2 row_mask:0xf bank_mask:0xf
	v_mov_b32_dpp v8, v6 row_shr:3 row_mask:0xf bank_mask:0xf
	v_mov_b32_dpp v13, v7 row_shr:1 row_mask:0xf bank_mask:0xf
	v_mov_b32_dpp v11, v7 row_shr:2 row_mask:0xf bank_mask:0xf
	v_mov_b32_dpp v9, v7 row_shr:3 row_mask:0xf bank_mask:0xf
	s_and_saveexec_b64 s[22:23], s[2:3]
	s_cbranch_execz .LBB0_245
	ds_read_b128 v[26:29], v238 offset:4608
	ds_read_b128 v[30:33], v238 offset:3584
	ds_read_b128 v[34:37], v238 offset:2560
	v_cndmask_b32_e64 v25, v24, 0, s[8:9]
	ds_read_b128 v[38:41], v238 offset:1536
	s_nop 0
	ds_read_b128 v[42:45], v238 offset:512
	v_cndmask_b32_e64 v24, v23, 0, s[8:9]
	v_cndmask_b32_e64 v23, 0, v22, s[6:7]
	v_cndmask_b32_e64 v22, 0, v21, s[6:7]
	v_cndmask_b32_e64 v15, 0, v15, s[4:5]
	v_cndmask_b32_e64 v14, 0, v14, s[4:5]
	v_cndmask_b32_e64 v13, v13, 0, s[8:9]
	v_cndmask_b32_e64 v12, v12, 0, s[8:9]
	v_cndmask_b32_e64 v11, 0, v11, s[6:7]
	v_cndmask_b32_e64 v10, 0, v10, s[6:7]
	v_cndmask_b32_e64 v9, 0, v9, s[4:5]
	v_cndmask_b32_e64 v8, 0, v8, s[4:5]
	s_waitcnt lgkmcnt(0)
	v_pk_fma_f32 v[4:5], v[4:5], v[30:31], v[26:27]
	v_pk_fma_f32 v[6:7], v[6:7], v[32:33], v[28:29]
	v_pk_fma_f32 v[4:5], v[24:25], v[34:35], v[4:5]
	v_pk_fma_f32 v[6:7], v[12:13], v[36:37], v[6:7]
	v_pk_fma_f32 v[4:5], v[22:23], v[38:39], v[4:5]
	s_nop 0
	v_pk_fma_f32 v[4:5], v[14:15], v[42:43], v[4:5]
	v_pk_fma_f32 v[6:7], v[10:11], v[40:41], v[6:7]
	v_mul_f32_e32 v14, 0xbfb8aa3b, v5
	v_exp_f32_e32 v14, v14
	v_pk_fma_f32 v[6:7], v[8:9], v[44:45], v[6:7]
	v_add_f32_e32 v14, 1.0, v14
	v_rcp_f32_e32 v15, v14
	v_mul_f32_e32 v14, 0xbfb8aa3b, v4
	v_exp_f32_e32 v14, v14
	s_nop 0
	v_add_f32_e32 v14, 1.0, v14
	v_rcp_f32_e32 v14, v14
	s_nop 0
	v_pk_mul_f32 v[4:5], v[4:5], v[14:15]
	s_nop 0
	v_cvt_pk_bf16_f32 v4, v4, v5
	v_mul_f32_e32 v5, 0xbfb8aa3b, v7
	v_exp_f32_e32 v5, v5
	s_nop 0
	v_add_f32_e32 v5, 1.0, v5
	v_rcp_f32_e32 v9, v5
	v_mul_f32_e32 v5, 0xbfb8aa3b, v6
	v_exp_f32_e32 v5, v5
	s_nop 0
	v_add_f32_e32 v5, 1.0, v5
	v_rcp_f32_e32 v8, v5
	s_nop 0
	v_pk_mul_f32 v[6:7], v[6:7], v[8:9]
	s_nop 0
	v_cvt_pk_bf16_f32 v5, v6, v7
	global_store_dwordx2 v[16:17], v[4:5], off offset:256
.LBB0_245:
	s_or_b64 exec, exec, s[22:23]
	ds_read_b64 v[4:5], v18 offset:1288
	ds_read_b64 v[6:7], v19 offset:776
	ds_read_b64 v[18:19], v20 offset:264
	s_waitcnt lgkmcnt(0)
	v_lshlrev_b32_e32 v14, 16, v4
	v_and_b32_e32 v15, 0xffff0000, v4
	v_lshlrev_b32_e32 v8, 16, v5
	v_and_b32_e32 v9, 0xffff0000, v5
	v_lshlrev_b32_e32 v12, 16, v6
	v_and_b32_e32 v13, 0xffff0000, v6
	v_lshlrev_b32_e32 v6, 16, v7
	v_and_b32_e32 v7, 0xffff0000, v7
	v_lshlrev_b32_e32 v10, 16, v18
	v_and_b32_e32 v11, 0xffff0000, v18
	v_lshlrev_b32_e32 v4, 16, v19
	v_and_b32_e32 v5, 0xffff0000, v19
	v_mov_b32_dpp v14, v0 row_shr:1 row_mask:0xf bank_mask:0xf
	v_mov_b32_dpp v12, v0 row_shr:2 row_mask:0xf bank_mask:0xf
	v_mov_b32_dpp v10, v0 row_shr:3 row_mask:0xf bank_mask:0xf
	v_mov_b32_dpp v15, v1 row_shr:1 row_mask:0xf bank_mask:0xf
	v_mov_b32_dpp v13, v1 row_shr:2 row_mask:0xf bank_mask:0xf
	v_mov_b32_dpp v11, v1 row_shr:3 row_mask:0xf bank_mask:0xf
	v_mov_b32_dpp v8, v2 row_shr:1 row_mask:0xf bank_mask:0xf
	v_mov_b32_dpp v6, v2 row_shr:2 row_mask:0xf bank_mask:0xf
	v_mov_b32_dpp v4, v2 row_shr:3 row_mask:0xf bank_mask:0xf
	v_mov_b32_dpp v9, v3 row_shr:1 row_mask:0xf bank_mask:0xf
	v_mov_b32_dpp v7, v3 row_shr:2 row_mask:0xf bank_mask:0xf
	v_mov_b32_dpp v5, v3 row_shr:3 row_mask:0xf bank_mask:0xf
	s_and_saveexec_b64 s[22:23], s[2:3]
	s_cbranch_execz .LBB0_247
	ds_read_b128 v[18:21], v238 offset:4624
	ds_read_b128 v[22:25], v238 offset:3600
	ds_read_b128 v[26:29], v238 offset:2576
	v_cndmask_b32_e64 v15, v15, 0, s[8:9]
	ds_read_b128 v[30:33], v238 offset:1552
	s_nop 0
	ds_read_b128 v[34:37], v238 offset:528
	v_cndmask_b32_e64 v14, v14, 0, s[8:9]
	v_cndmask_b32_e64 v13, 0, v13, s[6:7]
	v_cndmask_b32_e64 v12, 0, v12, s[6:7]
	v_cndmask_b32_e64 v11, 0, v11, s[4:5]
	v_cndmask_b32_e64 v10, 0, v10, s[4:5]
	v_cndmask_b32_e64 v9, v9, 0, s[8:9]
	v_cndmask_b32_e64 v8, v8, 0, s[8:9]
	v_cndmask_b32_e64 v7, 0, v7, s[6:7]
	v_cndmask_b32_e64 v6, 0, v6, s[6:7]
	v_cndmask_b32_e64 v5, 0, v5, s[4:5]
	v_cndmask_b32_e64 v4, 0, v4, s[4:5]
	s_waitcnt lgkmcnt(0)
	v_pk_fma_f32 v[0:1], v[0:1], v[22:23], v[18:19]
	v_pk_fma_f32 v[2:3], v[2:3], v[24:25], v[20:21]
	v_pk_fma_f32 v[0:1], v[14:15], v[26:27], v[0:1]
	v_pk_fma_f32 v[2:3], v[8:9], v[28:29], v[2:3]
	v_pk_fma_f32 v[0:1], v[12:13], v[30:31], v[0:1]
	s_nop 0
	v_pk_fma_f32 v[0:1], v[10:11], v[34:35], v[0:1]
	v_pk_fma_f32 v[2:3], v[6:7], v[32:33], v[2:3]
	v_mul_f32_e32 v10, 0xbfb8aa3b, v1
	v_exp_f32_e32 v10, v10
	v_pk_fma_f32 v[2:3], v[4:5], v[36:37], v[2:3]
	v_add_f32_e32 v10, 1.0, v10
	v_rcp_f32_e32 v11, v10
	v_mul_f32_e32 v10, 0xbfb8aa3b, v0
	v_exp_f32_e32 v10, v10
	s_nop 0
	v_add_f32_e32 v10, 1.0, v10
	v_rcp_f32_e32 v10, v10
	s_nop 0
	v_pk_mul_f32 v[0:1], v[0:1], v[10:11]
	s_nop 0
	v_cvt_pk_bf16_f32 v0, v0, v1
	v_mul_f32_e32 v1, 0xbfb8aa3b, v3
	v_exp_f32_e32 v1, v1
	s_nop 0
	v_add_f32_e32 v1, 1.0, v1
	v_rcp_f32_e32 v5, v1
	v_mul_f32_e32 v1, 0xbfb8aa3b, v2
	v_exp_f32_e32 v1, v1
	s_nop 0
	v_add_f32_e32 v1, 1.0, v1
	v_rcp_f32_e32 v4, v1
	s_nop 0
	v_pk_mul_f32 v[2:3], v[2:3], v[4:5]
	s_nop 0
	v_cvt_pk_bf16_f32 v1, v2, v3
	global_store_dwordx2 v[16:17], v[0:1], off offset:264

; #define LAS __attribute__((address_space(3)))
; __device__ __forceinline__ unsigned f2bf(float f) { return pk2(f, 0.f) & 0xffffu; }
; __device__ __forceinline__ float fexp(float x) { return __builtin_amdgcn_exp2f(x * 1.4426950408889634f); }
; __device__ __forceinline__ void ssd_item(const Params& P, LAS unsigned char* lds, int item, int tid, int wave, int lane) {
;     ...
;         const int p0 = 128 * c, nvalid = (LL - p0) < 128 ? (LL - p0) : 128;
;         LAS float* ACS = (LAS float*)(lds + S_ACS) + (c & 1) * 128; LAS float* DTV = (LAS float*)(lds + S_DTV) + (c & 1) * 128;
; #pragma unroll
;         for (int k = 0; k < 8; ++k) { const int br = brow0 + 16 * k;
;             u32x4 v = pbc[k]; if (br >= nvalid) v = (u32x4){0u, 0u, 0u, 0u};
;             *(LAS u32x4*)(lds + (bsel ? S_CC : S_BC) + br * LP + boct * 16) = v; }
;         {
;             const float aend = ACS[127];
; #pragma unroll
;             for (int q = 0; q < 2; ++q) { const int s = xrow0 + 64 * q; const bool sv = s < nvalid;
;                 const float dtv = DTV[s], dd = fexp(aend - ACS[s]);
;                 const unsigned w4[4] = {pxv[q].x, pxv[q].y, pxv[q].z, pxv[q].w};
;                 const int sofs = (((s >> 3) ^ xoct) << 4) + (s & 7) * 2;
; #pragma unroll
;                 for (int j = 0; j < 8; ++j) { float x = (j & 1) ? bfhi(w4[j >> 1]) : bflo(w4[j >> 1]); x = sv ? x : 0.f; const int p = xoct * 8 + j;
;                     const float xd = x * dtv;
;                     *(LAS unsigned short*)(lds + S_XDTT + p * LP + sofs) = (unsigned short)f2bf(xd);
;                     *(LAS unsigned short*)(lds + S_XDDT + p * LP + sofs) = (unsigned short)f2bf(xd * dd); } }
;         }
.LBB0_318:
	s_lshl_b32 s6, s17, 7
	s_sub_i32 s7, 0x1010, s6
	s_min_u32 s19, s7, 0x80
	v_cmp_gt_u32_e32 vcc, s19, v104
	s_lshl_b32 s7, s17, 9
	s_and_b32 s7, s7, 0x200
	v_cndmask_b32_e32 v19, 0, v51, vcc
	v_cndmask_b32_e32 v18, 0, v50, vcc
	v_cndmask_b32_e32 v17, 0, v49, vcc
	v_cndmask_b32_e32 v16, 0, v48, vcc
	v_cmp_gt_u32_e32 vcc, s19, v108
	ds_write_b128 v188, v[16:19]
	s_add_i32 s21, s7, 0
	v_cndmask_b32_e32 v19, 0, v55, vcc
	v_cndmask_b32_e32 v18, 0, v54, vcc
	v_cndmask_b32_e32 v17, 0, v53, vcc
	v_cndmask_b32_e32 v16, 0, v52, vcc
	v_cmp_gt_u32_e32 vcc, s19, v110
	ds_write_b128 v188, v[16:19] offset:4352
	s_add_i32 s21, s21, 0x26400
	v_cndmask_b32_e32 v19, 0, v59, vcc
	v_cndmask_b32_e32 v18, 0, v58, vcc
	v_cndmask_b32_e32 v17, 0, v57, vcc
	v_cndmask_b32_e32 v16, 0, v56, vcc
	v_cmp_gt_u32_e32 vcc, s19, v112
	ds_write_b128 v188, v[16:19] offset:8704
	v_lshlrev_b32_e32 v21, 16, v80
	v_cndmask_b32_e32 v19, 0, v63, vcc
	v_cndmask_b32_e32 v18, 0, v62, vcc
	v_cndmask_b32_e32 v17, 0, v61, vcc
	v_cndmask_b32_e32 v16, 0, v60, vcc
	v_cmp_gt_u32_e32 vcc, s19, v114
	ds_write_b128 v188, v[16:19] offset:13056
	s_add_i32 s20, s16, s6
	v_cndmask_b32_e32 v19, 0, v67, vcc
	v_cndmask_b32_e32 v18, 0, v66, vcc
	v_cndmask_b32_e32 v17, 0, v65, vcc
	v_cndmask_b32_e32 v16, 0, v64, vcc
	v_cmp_gt_u32_e32 vcc, s19, v116
	ds_write_b128 v188, v[16:19] offset:17408
	s_mul_i32 s6, s20, 0x2c20
	v_cndmask_b32_e32 v19, 0, v71, vcc
	v_cndmask_b32_e32 v18, 0, v70, vcc
	v_cndmask_b32_e32 v17, 0, v69, vcc
	v_cndmask_b32_e32 v16, 0, v68, vcc
	v_cmp_gt_u32_e32 vcc, s19, v118
	ds_write_b128 v188, v[16:19] offset:21760
	s_add_i32 s18, s6, 0x5840
	v_cndmask_b32_e32 v19, 0, v75, vcc
	v_cndmask_b32_e32 v18, 0, v74, vcc
	v_cndmask_b32_e32 v17, 0, v73, vcc
	v_cndmask_b32_e32 v16, 0, v72, vcc
	v_cmp_gt_u32_e32 vcc, s19, v168
	ds_write_b128 v188, v[16:19] offset:26112
	s_add_i32 s74, s6, 0x8460
	v_cndmask_b32_e32 v19, 0, v79, vcc
	v_cndmask_b32_e32 v18, 0, v78, vcc
	v_cndmask_b32_e32 v17, 0, v77, vcc
	v_cndmask_b32_e32 v16, 0, v76, vcc
	ds_write_b128 v188, v[16:19] offset:30464
	v_mov_b32_e32 v16, s21
	ds_read_b32 v20, v16 offset:508
	v_lshl_add_u32 v16, v122, 2, s21
	ds_read2st64_b32 v[16:17], v16 offset1:1
	v_add_u32_e32 v18, s7, v179
	ds_read2st64_b32 v[18:19], v18 offset1:1
	v_cmp_gt_u32_e32 vcc, s19, v122
	s_add_i32 s7, s6, 0x2c20
	s_waitcnt lgkmcnt(1)
	v_sub_f32_e32 v16, v20, v16
	v_mul_f32_e32 v16, 0x3fb8aa3b, v16
	v_exp_f32_e32 v16, v16
	v_cndmask_b32_e32 v21, 0, v21, vcc
	s_waitcnt lgkmcnt(0)
	v_mul_f32_e32 v21, v21, v18
	v_cvt_pk_bf16_f32 v22, v21, s0
	v_mul_f32_e32 v21, v21, v16
	v_cvt_pk_bf16_f32 v21, v21, s0
	ds_write_b16 v190, v21
	v_and_b32_e32 v21, 0xffff0000, v80
	v_cndmask_b32_e32 v21, 0, v21, vcc
	v_mul_f32_e32 v21, v21, v18
	ds_write_b16 v189, v22
	v_cvt_pk_bf16_f32 v22, v21, s0
	v_mul_f32_e32 v21, v21, v16
	v_cvt_pk_bf16_f32 v21, v21, s0
	ds_write_b16 v190, v21 offset:272
	v_lshlrev_b32_e32 v21, 16, v81
	v_cndmask_b32_e32 v21, 0, v21, vcc
	v_mul_f32_e32 v21, v21, v18
	ds_write_b16 v189, v22 offset:272
	v_cvt_pk_bf16_f32 v22, v21, s0
	v_mul_f32_e32 v21, v21, v16
	v_cvt_pk_bf16_f32 v21, v21, s0
	ds_write_b16 v190, v21 offset:544
	v_and_b32_e32 v21, 0xffff0000, v81
	v_cndmask_b32_e32 v21, 0, v21, vcc
	v_mul_f32_e32 v21, v21, v18
	ds_write_b16 v189, v22 offset:544
	v_cvt_pk_bf16_f32 v22, v21, s0
	v_mul_f32_e32 v21, v21, v16
	v_cvt_pk_bf16_f32 v21, v21, s0
	ds_write_b16 v190, v21 offset:816
	v_lshlrev_b32_e32 v21, 16, v82
	v_cndmask_b32_e32 v21, 0, v21, vcc
	v_mul_f32_e32 v21, v21, v18
	ds_write_b16 v189, v22 offset:816
	v_cvt_pk_bf16_f32 v22, v21, s0
	v_mul_f32_e32 v21, v21, v16
	v_cvt_pk_bf16_f32 v21, v21, s0
	ds_write_b16 v190, v21 offset:1088
	v_and_b32_e32 v21, 0xffff0000, v82
	v_cndmask_b32_e32 v21, 0, v21, vcc
	v_mul_f32_e32 v21, v21, v18
	ds_write_b16 v189, v22 offset:1088
	v_cvt_pk_bf16_f32 v22, v21, s0
	v_mul_f32_e32 v21, v21, v16
	v_cvt_pk_bf16_f32 v21, v21, s0
	ds_write_b16 v190, v21 offset:1360
	v_lshlrev_b32_e32 v21, 16, v83
	v_cndmask_b32_e32 v21, 0, v21, vcc
	v_mul_f32_e32 v21, v21, v18
	ds_write_b16 v189, v22 offset:1360
	v_cvt_pk_bf16_f32 v22, v21, s0
	v_mul_f32_e32 v21, v21, v16
	v_cvt_pk_bf16_f32 v21, v21, s0
	ds_write_b16 v190, v21 offset:1632
	v_and_b32_e32 v21, 0xffff0000, v83
	v_cndmask_b32_e32 v21, 0, v21, vcc
	v_mul_f32_e32 v18, v21, v18
	v_mul_f32_e32 v16, v18, v16
	v_cvt_pk_bf16_f32 v16, v16, s0
	ds_write_b16 v190, v16 offset:1904
	v_sub_f32_e32 v16, v20, v17
	v_mul_f32_e32 v16, 0x3fb8aa3b, v16
	v_exp_f32_e32 v16, v16
	v_lshlrev_b32_e32 v17, 16, v84
	v_cmp_gt_u32_e32 vcc, s19, v169
	v_cvt_pk_bf16_f32 v21, v18, s0
	ds_write_b16 v189, v22 offset:1632
	v_cndmask_b32_e32 v17, 0, v17, vcc
	v_mul_f32_e32 v17, v17, v19
	v_cvt_pk_bf16_f32 v18, v17, s0
	v_mul_f32_e32 v17, v17, v16
	v_cvt_pk_bf16_f32 v17, v17, s0
	ds_write_b16 v192, v17
	v_and_b32_e32 v17, 0xffff0000, v84
	v_cndmask_b32_e32 v17, 0, v17, vcc
	v_mul_f32_e32 v17, v17, v19
	ds_write_b16 v189, v21 offset:1904
	ds_write_b16 v191, v18
	v_cvt_pk_bf16_f32 v18, v17, s0
	v_mul_f32_e32 v17, v17, v16
	v_cvt_pk_bf16_f32 v17, v17, s0
	ds_write_b16 v192, v17 offset:272
	v_lshlrev_b32_e32 v17, 16, v85
	v_cndmask_b32_e32 v17, 0, v17, vcc
	v_mul_f32_e32 v17, v17, v19
	ds_write_b16 v191, v18 offset:272
	v_cvt_pk_bf16_f32 v18, v17, s0
	v_mul_f32_e32 v17, v17, v16
	v_cvt_pk_bf16_f32 v17, v17, s0
	ds_write_b16 v192, v17 offset:544
	v_and_b32_e32 v17, 0xffff0000, v85
	v_cndmask_b32_e32 v17, 0, v17, vcc
	v_mul_f32_e32 v17, v17, v19
	ds_write_b16 v191, v18 offset:544
	v_cvt_pk_bf16_f32 v18, v17, s0
	v_mul_f32_e32 v17, v17, v16
	v_cvt_pk_bf16_f32 v17, v17, s0
	ds_write_b16 v192, v17 offset:816
	v_lshlrev_b32_e32 v17, 16, v86
	v_cndmask_b32_e32 v17, 0, v17, vcc
	v_mul_f32_e32 v17, v17, v19
	ds_write_b16 v191, v18 offset:816
	v_cvt_pk_bf16_f32 v18, v17, s0
	v_mul_f32_e32 v17, v17, v16
	v_cvt_pk_bf16_f32 v17, v17, s0
	ds_write_b16 v192, v17 offset:1088
	v_and_b32_e32 v17, 0xffff0000, v86
	v_cndmask_b32_e32 v17, 0, v17, vcc
	v_mul_f32_e32 v17, v17, v19
	ds_write_b16 v191, v18 offset:1088
	v_cvt_pk_bf16_f32 v18, v17, s0
	v_mul_f32_e32 v17, v17, v16
	v_cvt_pk_bf16_f32 v17, v17, s0
	ds_write_b16 v192, v17 offset:1360
	v_lshlrev_b32_e32 v17, 16, v87
	v_cndmask_b32_e32 v17, 0, v17, vcc
	v_mul_f32_e32 v17, v17, v19
	ds_write_b16 v191, v18 offset:1360
	v_cvt_pk_bf16_f32 v18, v17, s0
	v_mul_f32_e32 v17, v17, v16
	v_cvt_pk_bf16_f32 v17, v17, s0
	ds_write_b16 v192, v17 offset:1632
	v_and_b32_e32 v17, 0xffff0000, v87
	v_cndmask_b32_e32 v17, 0, v17, vcc
	v_mul_f32_e32 v17, v17, v19
	v_mul_f32_e32 v16, v17, v16
	ds_write_b16 v191, v18 offset:1632
	v_cvt_pk_bf16_f32 v18, v17, s0
	v_cvt_pk_bf16_f32 v16, v16, s0
	ds_write_b16 v191, v18 offset:1904
	ds_write_b16 v192, v16 offset:1904
	s_waitcnt lgkmcnt(0)
	s_barrier
; __device__ __forceinline__ void ssd_item(const Params& P, LAS unsigned char* lds, int item, int tid, int wave, int lane) {
;     ...
;         u32x2 zc[4], xc[4];
;         {
;             const int zb = __builtin_amdgcn_readfirstlane((int)(((unsigned)rowbase + p0 + wave * 16) * LDP * 2u));
; #pragma unroll
;             for (int i = 0; i < 4; ++i) { zc[i] = __builtin_bit_cast(u32x2, __builtin_amdgcn_raw_buffer_load_b64(prs, zvoff, zb + i * (LDP * 2), 2));
;                                           xc[i] = __builtin_bit_cast(u32x2, __builtin_amdgcn_raw_buffer_load_b64(prs, xvoff, zb + i * (LDP * 2), 2)); }
;         }
;         if (c + 1 < 33) SSD_LOAD(c + 1);
;         const int lb = wave >> 1, sb0 = 2 * (wave & 1);
;         f32x16 g0, g1; for (int i = 0; i < 16; ++i) { g0[i] = 0.f; g1[i] = 0.f; }
;         if (sb0 <= lb) g0 = mma_nt<4>(lds + S_CC + lb * 32 * LP + 128, lds + S_BC + sb0 * 32 * LP + 128, mma_nt<4>(lds + S_CC + lb * 32 * LP, lds + S_BC + sb0 * 32 * LP, g0, lane), lane);
;         if (sb0 + 1 <= lb) g1 = mma_nt<4>(lds + S_CC + lb * 32 * LP + 128, lds + S_BC + (sb0 + 1) * 32 * LP + 128, mma_nt<4>(lds + S_CC + lb * 32 * LP, lds + S_BC + (sb0 + 1) * 32 * LP, g1, lane), lane);
	buffer_load_dwordx2 v[160:161], v214, s[84:87], s6 offen nt
	buffer_load_dwordx2 v[156:157], v214, s[84:87], s7 offen nt
	buffer_load_dwordx2 v[150:151], v214, s[84:87], s18 offen nt
	buffer_load_dwordx2 v[144:145], v214, s[84:87], s74 offen nt
	buffer_load_dwordx2 v[158:159], v213, s[84:87], s6 offen nt
	buffer_load_dwordx2 v[154:155], v213, s[84:87], s7 offen nt
	buffer_load_dwordx2 v[148:149], v213, s[84:87], s18 offen nt
	buffer_load_dwordx2 v[146:147], v213, s[84:87], s74 offen nt
	s_add_i32 s18, s17, 1
	s_cmp_eq_u32 s17, 32
	s_cselect_b64 s[6:7], -1, 0
	s_and_b64 vcc, exec, s[6:7]
	s_cbranch_vccnz .LBB0_321
.LBB0_321:
	v_cndmask_b32_e64 v17, 0, 1, s[4:5]
	v_mov_b32_e32 v16, 0
	v_cmp_ne_u32_e64 s[76:77], 1, v17
	s_andn2_b64 vcc, exec, s[4:5]
	v_mov_b32_e32 v32, 0
	v_mov_b32_e32 v33, 0
	v_mov_b32_e32 v34, 0
	v_mov_b32_e32 v35, 0
	v_mov_b32_e32 v36, 0
	v_mov_b32_e32 v37, 0
	v_mov_b32_e32 v38, 0
	v_mov_b32_e32 v39, 0
	v_mov_b32_e32 v40, 0
	v_mov_b32_e32 v41, 0
	v_mov_b32_e32 v42, 0
	v_mov_b32_e32 v43, 0
	v_mov_b32_e32 v44, 0
	v_mov_b32_e32 v45, 0
	v_mov_b32_e32 v46, 0
	v_mov_b32_e32 v47, 0
	s_cbranch_vccnz .LBB0_323
	ds_read_b128 v[18:21], v207
	ds_read_b128 v[22:25], v207 offset:32
	ds_read_b128 v[26:29], v193 offset:34816
	ds_read_b128 v[88:91], v193 offset:34848
	ds_read_b128 v[92:95], v207 offset:64
	ds_read_b128 v[96:99], v207 offset:96
	ds_read_b128 v[100:103], v193 offset:34880
	ds_read_b128 v[216:219], v193 offset:34912
	s_waitcnt lgkmcnt(5)
	v_mfma_f32_32x32x16_bf16 v[32:47], v[18:21], v[26:29], 0
	s_waitcnt lgkmcnt(4)
	v_mfma_f32_32x32x16_bf16 v[32:47], v[22:25], v[88:91], v[32:47]
	s_waitcnt lgkmcnt(1)
	v_mfma_f32_32x32x16_bf16 v[32:47], v[92:95], v[100:103], v[32:47]
	s_waitcnt lgkmcnt(0)
	v_mfma_f32_32x32x16_bf16 v[32:47], v[96:99], v[216:219], v[32:47]
	ds_read_b128 v[18:21], v207 offset:128
	ds_read_b128 v[22:25], v207 offset:160
	ds_read_b128 v[26:29], v193 offset:34944
	ds_read_b128 v[88:91], v193 offset:34976
	ds_read_b128 v[92:95], v207 offset:192
	ds_read_b128 v[96:99], v193 offset:35008
	ds_read_b128 v[100:103], v207 offset:224
	ds_read_b128 v[216:219], v193 offset:35040
	s_waitcnt lgkmcnt(5)
	v_mfma_f32_32x32x16_bf16 v[32:47], v[18:21], v[26:29], v[32:47]
	s_waitcnt lgkmcnt(4)
	v_mfma_f32_32x32x16_bf16 v[32:47], v[22:25], v[88:91], v[32:47]
	s_waitcnt lgkmcnt(2)
	v_mfma_f32_32x32x16_bf16 v[32:47], v[92:95], v[96:99], v[32:47]
	s_waitcnt lgkmcnt(0)
	v_mfma_f32_32x32x16_bf16 v[32:47], v[100:103], v[216:219], v[32:47]

.LBB0_325:
	s_and_b64 vcc, exec, s[6:7]
	s_cbranch_vccnz .Lssd_pf_skip
	s_lshl_b32 s98, s18, 7
	s_add_i32 s98, s98, s82
	s_mul_i32 s98, s98, 0x2c20
	s_lshr_b32 s99, s80, 3
	s_lshl_b32 s99, s99, 8
	s_addk_i32 s99, 0x1000
	v_lshrrev_b32_e32 v238, 5, v181
	v_and_b32_e32 v239, 15, v181
	v_mul_u32_u24_e32 v238, 0x2c20, v238
	v_lshl_add_u32 v238, v239, 4, v238
	v_bfe_u32 v239, v181, 4, 1
	v_lshl_add_u32 v238, v239, 9, v238
	v_add_u32_e32 v238, s99, v238
	s_add_i32 s100, s98, 0x2c200
	s_add_i32 s101, s98, 0x58400
	buffer_load_dwordx4 v[48:51], v238, s[84:87], s98 offen
	buffer_load_dwordx4 v[52:55], v238, s[84:87], s100 offen
	s_add_i32 s100, s98, 0x84600
	buffer_load_dwordx4 v[56:59], v238, s[84:87], s101 offen
	s_add_i32 s101, s98, 0xb0800
	buffer_load_dwordx4 v[60:63], v238, s[84:87], s100 offen
	s_add_i32 s100, s98, 0xdca00
	buffer_load_dwordx4 v[64:67], v238, s[84:87], s101 offen
	s_add_i32 s99, s98, 0x108c00
	buffer_load_dwordx4 v[68:71], v238, s[84:87], s100 offen
	s_add_i32 s100, s98, 0x134e00
	buffer_load_dwordx4 v[72:75], v238, s[84:87], s99 offen
	v_lshrrev_b32_e32 v239, 3, v181
	buffer_load_dwordx4 v[76:79], v238, s[84:87], s100 offen
	v_and_b32_e32 v238, 7, v181
	v_mul_u32_u24_e32 v239, 0x2c20, v239
	s_lshl_b32 s99, s80, 7
	s_addk_i32 s99, 0x800
	v_lshl_add_u32 v239, v238, 4, v239
	v_add_u32_e32 v239, s99, v239
	s_nop 0
	buffer_load_dwordx4 v[80:83], v239, s[84:87], s98 offen nt
	buffer_load_dwordx4 v[84:87], v239, s[84:87], s101 offen nt
	s_and_b64 vcc, exec, s[72:73]
	s_cbranch_vccnz .Lssd_pf_skip
	v_and_b32_e32 v238, 63, v181
	v_mul_u32_u24_e32 v238, 0x5840, v238
	s_lshl_b32 s99, s80, 1
	s_addk_i32 s99, 0x1400
	s_add_i32 s100, s98, 0x2c20
	v_add_u32_e32 v238, s99, v238
	s_nop 0
	buffer_load_ushort v211, v238, s[84:87], s98 offen
	buffer_load_ushort v212, v238, s[84:87], s100 offen

; #define LAS __attribute__((address_space(3)))
; __device__ __forceinline__ float fexp(float x) { return __builtin_amdgcn_exp2f(x * 1.4426950408889634f); }
; __device__ __forceinline__ void ssd_item(const Params& P, LAS unsigned char* lds, int item, int tid, int wave, int lane) {
;     ...
;         {
;             const float cd = fexp(ACS[127]);
; #pragma unroll
;             for (int i = 0; i < 16; ++i) sacc[i] *= cd;
;             {
;                 const LAS unsigned char* ap = lds + S_XDDT + (pb * 32 + r) * LP; const int xsw = ((pb * 32 + r) >> 3) & 7;
;                 const LAS unsigned char* bp = lds + S_BC + (8 * hh) * LP + (yb * 32 + r) * 2;
; #pragma unroll
;                 for (int kh = 0; kh < 2; ++kh) {
;                     bf16x8 af[4], bfr[4];
; #pragma unroll
;                     for (int k4 = 0; k4 < 4; ++k4) { const int ks = kh * 4 + k4; af[k4] = *(const LAS bf16x8*)(ap + (((2 * ks + hh) ^ xsw) << 4));
; #pragma unroll
;                         for (int j = 0; j < 8; ++j) bfr[k4][j] = *(const LAS short*)(bp + (16 * ks + j) * LP); }
;                     __builtin_amdgcn_sched_barrier(0);
; #pragma unroll
;                     for (int k4 = 0; k4 < 4; ++k4) sacc = __builtin_amdgcn_mfma_f32_32x32x16_bf16(af[k4], bfr[k4], sacc, 0, 0, 0);
;                 }
.LBB0_335:
	v_mov_b32_e32 v16, s21
	ds_read_b32 v16, v16 offset:508
	s_waitcnt lgkmcnt(0)
	v_mul_f32_e32 v16, 0x3fb8aa3b, v16
	v_exp_f32_e32 v16, v16
	s_nop 0
	v_pk_mul_f32 v[14:15], v[14:15], v[16:17] op_sel_hi:[1,0]
	v_pk_mul_f32 v[12:13], v[12:13], v[16:17] op_sel_hi:[1,0]
	v_pk_mul_f32 v[10:11], v[10:11], v[16:17] op_sel_hi:[1,0]
	v_pk_mul_f32 v[8:9], v[8:9], v[16:17] op_sel_hi:[1,0]
	v_pk_mul_f32 v[6:7], v[6:7], v[16:17] op_sel_hi:[1,0]
	v_pk_mul_f32 v[4:5], v[4:5], v[16:17] op_sel_hi:[1,0]
	v_pk_mul_f32 v[2:3], v[2:3], v[16:17] op_sel_hi:[1,0]
	v_pk_mul_f32 v[0:1], v[0:1], v[16:17] op_sel_hi:[1,0]
	ds_read_b128 v[16:19], v195
	ds_read_u16 v32, v173 offset:34816
	ds_read_u16 v36, v173 offset:35088
	ds_read_u16 v33, v173 offset:35360
	ds_read_u16 v37, v173 offset:35632
	ds_read_u16 v34, v173 offset:35904
	ds_read_u16 v38, v173 offset:36176
	ds_read_u16 v35, v173 offset:36448
	ds_read_u16 v39, v173 offset:36720
	ds_read_b128 v[20:23], v196
	ds_read_u16 v40, v173 offset:39168
	ds_read_u16 v41, v173 offset:39440
	ds_read_u16 v42, v173 offset:39712
	ds_read_u16 v43, v173 offset:39984
	ds_read_u16 v44, v173 offset:40256
	ds_read_u16 v45, v173 offset:40528
	ds_read_u16 v46, v173 offset:40800
	ds_read_u16 v47, v173 offset:41072
	ds_read_b128 v[24:27], v197
	ds_read_u16 v88, v173 offset:43520
	ds_read_u16 v89, v173 offset:43792
	ds_read_u16 v90, v173 offset:44064
	ds_read_u16 v91, v173 offset:44336
	ds_read_u16 v92, v173 offset:44608
	ds_read_u16 v93, v173 offset:44880
	ds_read_u16 v94, v173 offset:45152
	ds_read_u16 v95, v173 offset:45424
	ds_read_b128 v[28:31], v198
	ds_read_u16 v96, v173 offset:47872
	ds_read_u16 v97, v173 offset:48144
	ds_read_u16 v98, v173 offset:48416
	ds_read_u16 v99, v173 offset:48688
	ds_read_u16 v100, v173 offset:48960
	ds_read_u16 v101, v173 offset:49232
	ds_read_u16 v102, v173 offset:49504
	ds_read_u16 v103, v173 offset:49776
	s_waitcnt lgkmcnt(14)
	v_perm_b32 v35, v39, v35, s13
	v_perm_b32 v34, v38, v34, s13
	v_perm_b32 v33, v37, v33, s13
	v_perm_b32 v32, v36, v32, s13
	s_nop 1
	v_mfma_f32_32x32x16_bf16 v[0:15], v[16:19], v[32:35], v[0:15]
	v_perm_b32 v19, v47, v46, s13
	v_perm_b32 v18, v45, v44, s13
	v_perm_b32 v17, v43, v42, s13
	v_perm_b32 v16, v41, v40, s13
	s_nop 1
	v_mfma_f32_32x32x16_bf16 v[0:15], v[20:23], v[16:19], v[0:15]
	s_waitcnt lgkmcnt(9)
	v_perm_b32 v19, v95, v94, s13
	v_perm_b32 v18, v93, v92, s13
	v_perm_b32 v17, v91, v90, s13
	v_perm_b32 v16, v89, v88, s13
	s_nop 1
	v_mfma_f32_32x32x16_bf16 v[0:15], v[24:27], v[16:19], v[0:15]
	s_waitcnt lgkmcnt(0)
	v_perm_b32 v19, v103, v102, s13
	v_perm_b32 v18, v101, v100, s13
	v_perm_b32 v17, v99, v98, s13
	v_perm_b32 v16, v97, v96, s13
	s_nop 1
	v_mfma_f32_32x32x16_bf16 v[0:15], v[28:31], v[16:19], v[0:15]
	ds_read_b128 v[16:19], v199
	ds_read_u16 v24, v173 offset:52224
	ds_read_u16 v28, v173 offset:52496
	ds_read_u16 v25, v173 offset:52768
	ds_read_u16 v29, v173 offset:53040
	ds_read_u16 v26, v173 offset:53312
	ds_read_u16 v30, v173 offset:53584
	ds_read_u16 v27, v173 offset:53856
	ds_read_u16 v31, v173 offset:54128
	ds_read_b128 v[20:23], v200
	ds_read_u16 v96, v173 offset:56576
	ds_read_u16 v97, v173 offset:56848
	ds_read_u16 v98, v173 offset:57120
	ds_read_u16 v99, v173 offset:57392
	ds_read_u16 v100, v173 offset:57664
	ds_read_u16 v101, v173 offset:57936
	ds_read_u16 v102, v173 offset:58208
	ds_read_u16 v103, v173 offset:58480
	ds_read_b128 v[36:39], v201
	ds_read_u16 v44, v173 offset:60928
	ds_read_u16 v45, v173 offset:61200
	ds_read_u16 v46, v173 offset:61472
	ds_read_u16 v47, v173 offset:61744
	ds_read_u16 v88, v173 offset:62016
	ds_read_u16 v89, v173 offset:62288
	ds_read_u16 v90, v173 offset:62560
	ds_read_u16 v92, v173 offset:62832
	ds_read_b128 v[32:35], v202
	ds_read_u16 v40, v173 offset:65280
	ds_read_u16 v41, v174 offset:30736
	ds_read_u16 v42, v174 offset:31008
	ds_read_u16 v43, v174 offset:31280
	ds_read_u16 v91, v174 offset:31552
	ds_read_u16 v93, v174 offset:31824
	ds_read_u16 v94, v174 offset:32096
	ds_read_u16 v95, v174 offset:32368
	s_waitcnt lgkmcnt(14)
	v_perm_b32 v27, v31, v27, s13
	v_perm_b32 v26, v30, v26, s13
	v_perm_b32 v25, v29, v25, s13
	v_perm_b32 v24, v28, v24, s13
	v_perm_b32 v31, v103, v102, s13
	v_perm_b32 v30, v101, v100, s13
	v_mfma_f32_32x32x16_bf16 v[0:15], v[16:19], v[24:27], v[0:15]
	v_perm_b32 v29, v99, v98, s13
	v_perm_b32 v28, v97, v96, s13
	s_waitcnt lgkmcnt(0)
	s_barrier
; #define LAS __attribute__((address_space(3)))
; __device__ __forceinline__ float fexp(float x) { return __builtin_amdgcn_exp2f(x * 1.4426950408889634f); }
; __device__ __forceinline__ void ssd_item(const Params& P, LAS unsigned char* lds, int item, int tid, int wave, int lane) {
;     ...
;             f32x4 ya[4];
; #pragma unroll
;             for (int q = 0; q < 4; ++q) ya[q] = (f32x4){0.f, 0.f, 0.f, 0.f};
;             const LAS unsigned char* cap = lds + S_CC + (wave * 16 + yc) * LP + yg * 16;
;             {
;                 bf16x8 af[4];
; #pragma unroll
;                 for (int ks = 0; ks < 4; ++ks) af[ks] = *(const LAS bf16x8*)(cap + ks * 64);
; #pragma unroll
;                 for (int q = 0; q < 4; ++q) { const LAS unsigned char* sbp = lds + S_SB + (4 * yc + q) * LP + yg * 16;
;                     bf16x8 bfr[4];
; #pragma unroll
;                     for (int ks = 0; ks < 4; ++ks) bfr[ks] = *(const LAS bf16x8*)(sbp + ks * 64);
; #pragma unroll
;                     for (int ks = 0; ks < 4; ++ks) ya[q] = __builtin_amdgcn_mfma_f32_16x16x32_bf16(af[ks], bfr[ks], ya[q], 0, 0, 0); }
;             }
;             float ay[4];
; #pragma unroll
;             for (int i = 0; i < 4; ++i) ay[i] = fexp(ACS[wave * 16 + 4 * yg + i]);
; #pragma unroll
;             for (int q = 0; q < 4; ++q) { ya[q][0] *= ay[0]; ya[q][1] *= ay[1]; ya[q][2] *= ay[2]; ya[q][3] *= ay[3]; }
	s_lshl_b32 s74, s81, 2
	v_mfma_f32_32x32x16_bf16 v[0:15], v[20:23], v[28:31], v[0:15]
	ds_read_b128 v[16:19], v203
	ds_read_b128 v[20:23], v203 offset:64
	ds_read_b128 v[24:27], v203 offset:128
	ds_read_b128 v[28:31], v203 offset:192
	ds_read_b128 v[96:99], v204
	ds_read_b128 v[100:103], v204 offset:64
	ds_read_b128 v[216:219], v204 offset:128
	ds_read_b128 v[220:223], v204 offset:192
	s_add_i32 s21, s21, s74
	s_waitcnt lgkmcnt(3)
	v_mfma_f32_16x16x32_bf16 v[96:99], v[16:19], v[96:99], 0
	s_waitcnt lgkmcnt(2)
	v_mfma_f32_16x16x32_bf16 v[96:99], v[20:23], v[100:103], v[96:99]
	s_waitcnt lgkmcnt(1)
	v_mfma_f32_16x16x32_bf16 v[96:99], v[24:27], v[216:219], v[96:99]
	s_waitcnt lgkmcnt(0)
	v_mfma_f32_16x16x32_bf16 v[96:99], v[28:31], v[220:223], v[96:99]
	ds_read_b128 v[100:103], v204 offset:272
	ds_read_b128 v[216:219], v204 offset:336
	ds_read_b128 v[220:223], v204 offset:400
	ds_read_b128 v[224:227], v204 offset:464
	s_waitcnt lgkmcnt(3)
	v_mfma_f32_16x16x32_bf16 v[100:103], v[16:19], v[100:103], 0
	s_waitcnt lgkmcnt(2)
	v_mfma_f32_16x16x32_bf16 v[100:103], v[20:23], v[216:219], v[100:103]
	s_waitcnt lgkmcnt(1)
	v_mfma_f32_16x16x32_bf16 v[100:103], v[24:27], v[220:223], v[100:103]
	s_waitcnt lgkmcnt(0)
	v_mfma_f32_16x16x32_bf16 v[100:103], v[28:31], v[224:227], v[100:103]
	ds_read_b128 v[216:219], v204 offset:544
	ds_read_b128 v[220:223], v204 offset:608
	ds_read_b128 v[224:227], v204 offset:672
	ds_read_b128 v[228:231], v204 offset:736
	s_waitcnt lgkmcnt(3)
	v_mfma_f32_16x16x32_bf16 v[216:219], v[16:19], v[216:219], 0
	s_waitcnt lgkmcnt(2)
	v_mfma_f32_16x16x32_bf16 v[216:219], v[20:23], v[220:223], v[216:219]
	s_waitcnt lgkmcnt(1)
	v_mfma_f32_16x16x32_bf16 v[216:219], v[24:27], v[224:227], v[216:219]
	s_waitcnt lgkmcnt(0)
	v_mfma_f32_16x16x32_bf16 v[216:219], v[28:31], v[228:231], v[216:219]
	ds_read_b128 v[220:223], v204 offset:816
	ds_read_b128 v[224:227], v204 offset:880
	ds_read_b128 v[228:231], v204 offset:944
	ds_read_b128 v[232:235], v204 offset:1008
	s_waitcnt lgkmcnt(3)
	v_mfma_f32_16x16x32_bf16 v[16:19], v[16:19], v[220:223], 0
	s_waitcnt lgkmcnt(2)
	v_mfma_f32_16x16x32_bf16 v[16:19], v[20:23], v[224:227], v[16:19]
	s_waitcnt lgkmcnt(1)
	v_mfma_f32_16x16x32_bf16 v[16:19], v[24:27], v[228:231], v[16:19]
	s_waitcnt lgkmcnt(0)
	v_mfma_f32_16x16x32_bf16 v[20:23], v[28:31], v[232:235], v[16:19]
	s_nop 5
	v_lshl_add_u32 v16, v167, 2, s21
	ds_read_b128 v[16:19], v16
	s_mov_b32 s21, s8
	s_waitcnt lgkmcnt(0)
	v_mul_f32_e32 v16, 0x3fb8aa3b, v16
	v_exp_f32_e32 v220, v16
	v_mul_f32_e32 v16, 0x3fb8aa3b, v17
	v_exp_f32_e32 v221, v16
	v_mul_f32_e32 v16, 0x3fb8aa3b, v18
	v_exp_f32_e32 v222, v16
	v_mul_f32_e32 v16, 0x3fb8aa3b, v19
	v_exp_f32_e32 v223, v16
	v_pk_mul_f32 v[24:25], v[96:97], v[220:221]
	v_pk_mul_f32 v[28:29], v[100:101], v[220:221]
	v_pk_mul_f32 v[16:17], v[216:217], v[220:221]
	v_pk_mul_f32 v[26:27], v[98:99], v[222:223]
	v_pk_mul_f32 v[30:31], v[102:103], v[222:223]
	v_pk_mul_f32 v[18:19], v[218:219], v[222:223]
	v_pk_mul_f32 v[22:23], v[22:23], v[222:223]
	v_pk_mul_f32 v[20:21], v[20:21], v[220:221]
	v_mov_b32_e32 v96, v187
	v_mov_b32_e32 v97, v162
; #define LAS __attribute__((address_space(3)))
; __device__ __forceinline__ float silu(float v) { return v * __builtin_amdgcn_rcpf(1.f + fexp(-v)); }
; __device__ __forceinline__ void ssd_item(const Params& P, LAS unsigned char* lds, int item, int tid, int wave, int lane) {
;     ...
;                 const LAS unsigned char* map = lds + S_MM + (wave * 16 + yc) * LP + yg * 16;
;                 const int nks = (wave >> 1) + 1;
;                 for (int ks = 0; ks < nks; ++ks) {
;                     const bf16x8 am = *(const LAS bf16x8*)(map + ks * 64);
; #pragma unroll
;                     for (int q = 0; q < 4; ++q) { const int p = 4 * yc + q; const int xsw = (p >> 3) & 7;
;                         const bf16x8 bx = *(const LAS bf16x8*)(lds + S_XDTT + p * LP + (((4 * ks + yg) ^ xsw) << 4));
;                         ya[q] = __builtin_amdgcn_mfma_f32_16x16x32_bf16(am, bx, ya[q], 0, 0, 0); }
;                 }
;             }
;             u32x2 yo[4];
; #pragma unroll
;             for (int i = 0; i < 4; ++i) {
;                 const float z0 = bflo(zc[i].x), z1 = bfhi(zc[i].x), z2 = bflo(zc[i].y), z3 = bfhi(zc[i].y);
;                 const float x0 = bflo(xc[i].x), x1 = bfhi(xc[i].x), x2 = bflo(xc[i].y), x3 = bfhi(xc[i].y);
;                 yo[i].x = pk2((ya[0][i] + Dh * x0) * silu(z0), (ya[1][i] + Dh * x1) * silu(z1));
;                 yo[i].y = pk2((ya[2][i] + Dh * x2) * silu(z2), (ya[3][i] + Dh * x3) * silu(z3)); }
;             __builtin_amdgcn_sched_barrier(0);
;             const int yb0 = __builtin_amdgcn_readfirstlane((int)(((unsigned)rowbase + p0 + wave * 16) * 1024u * 2u));
;             if (nvalid == 128) {
; #pragma unroll
;                 for (int i = 0; i < 4; ++i) __builtin_amdgcn_raw_buffer_store_b64(__builtin_bit_cast(__attribute__((__vector_size__(2 * sizeof(unsigned)))) unsigned, yo[i]), yrs, yvoff, yb0 + i * 2048, 0);
;             } else {
; #pragma unroll
;                 for (int i = 0; i < 4; ++i) if (wave * 16 + 4 * yg + i < nvalid) __builtin_amdgcn_raw_buffer_store_b64(__builtin_bit_cast(__attribute__((__vector_size__(2 * sizeof(unsigned)))) unsigned, yo[i]), yrs, yvoff, yb0 + i * 2048, 0);
.LBB0_336:
	ds_read_b128 v[98:101], v96
	v_xor_b32_e32 v102, v97, v177
	v_lshl_add_u32 v102, v102, 4, v186
	ds_read_b128 v[216:219], v102
	s_add_i32 s21, s21, -1
	v_add_u32_e32 v97, 4, v97
	v_add_u32_e32 v96, 64, v96
	s_cmp_eq_u32 s21, 0
	s_waitcnt lgkmcnt(0)
	v_mfma_f32_16x16x32_bf16 v[24:27], v[98:101], v[216:219], v[24:27]
	ds_read_b128 v[216:219], v102 offset:272
	s_waitcnt lgkmcnt(0)
	v_mfma_f32_16x16x32_bf16 v[28:31], v[98:101], v[216:219], v[28:31]
	ds_read_b128 v[216:219], v102 offset:544
	s_waitcnt lgkmcnt(0)
	v_mfma_f32_16x16x32_bf16 v[16:19], v[98:101], v[216:219], v[16:19]
	ds_read_b128 v[216:219], v102 offset:816
	s_waitcnt lgkmcnt(0)
	v_mfma_f32_16x16x32_bf16 v[20:23], v[98:101], v[216:219], v[20:23]
	s_cbranch_scc0 .LBB0_336
	s_waitcnt vmcnt(0)
	v_perm_b32 v99, v92, v90, s13
	v_perm_b32 v98, v89, v88, s13
	v_perm_b32 v97, v47, v46, s13
	v_perm_b32 v96, v45, v44, s13
	v_perm_b32 v45, v95, v94, s13
	v_perm_b32 v44, v93, v91, s13
	v_mfma_f32_32x32x16_bf16 v[0:15], v[36:39], v[96:99], v[0:15]
	v_perm_b32 v43, v43, v42, s13
	v_perm_b32 v42, v41, v40, s13
	v_lshlrev_b32_e32 v36, 16, v160
	v_and_b32_e32 v37, 0xffff0000, v160
	v_mul_f32_e32 v39, 0xbfb8aa3b, v36
	v_exp_f32_e32 v40, v39
	v_lshlrev_b32_e32 v38, 16, v158
	v_mfma_f32_32x32x16_bf16 v[0:15], v[32:35], v[42:45], v[0:15]
	v_mul_f32_e32 v32, 0xbfb8aa3b, v37
	v_exp_f32_e32 v33, v32
	v_add_f32_e32 v32, 1.0, v40
	v_rcp_f32_e32 v32, v32
	v_and_b32_e32 v39, 0xffff0000, v158
	v_add_f32_e32 v33, 1.0, v33
	v_rcp_f32_e32 v33, v33
	v_mov_b32_e32 v34, v24
	v_mov_b32_e32 v35, v28
	v_pk_fma_f32 v[34:35], v[140:141], v[38:39], v[34:35]
	v_pk_mul_f32 v[32:33], v[32:33], v[36:37]
	v_lshlrev_b32_e32 v36, 16, v159
	v_pk_mul_f32 v[32:33], v[32:33], v[34:35]
	v_lshlrev_b32_e32 v34, 16, v161
	v_and_b32_e32 v35, 0xffff0000, v161
	v_mul_f32_e32 v24, 0xbfb8aa3b, v34
	v_exp_f32_e32 v24, v24
	v_mul_f32_e32 v28, 0xbfb8aa3b, v35
	v_exp_f32_e32 v28, v28
	v_and_b32_e32 v37, 0xffff0000, v159
	v_add_f32_e32 v24, 1.0, v24
	v_rcp_f32_e32 v38, v24
	v_add_f32_e32 v24, 1.0, v28
	v_rcp_f32_e32 v39, v24
	v_mov_b32_e32 v40, v16
	v_mov_b32_e32 v41, v20
	v_pk_fma_f32 v[36:37], v[140:141], v[36:37], v[40:41]
	v_pk_mul_f32 v[34:35], v[38:39], v[34:35]
	v_cvt_pk_bf16_f32 v32, v32, v33
	v_pk_mul_f32 v[34:35], v[34:35], v[36:37]
	v_lshlrev_b32_e32 v36, 16, v154
	v_cvt_pk_bf16_f32 v33, v34, v35
	v_lshlrev_b32_e32 v34, 16, v156
	v_and_b32_e32 v35, 0xffff0000, v156
	v_mul_f32_e32 v16, 0xbfb8aa3b, v34
	v_exp_f32_e32 v16, v16
	v_mul_f32_e32 v20, 0xbfb8aa3b, v35
	v_exp_f32_e32 v20, v20
	v_and_b32_e32 v37, 0xffff0000, v154
	v_add_f32_e32 v16, 1.0, v16
	v_rcp_f32_e32 v38, v16
	v_add_f32_e32 v16, 1.0, v20
	v_rcp_f32_e32 v39, v16
	v_mov_b32_e32 v28, v25
	v_pk_fma_f32 v[24:25], v[140:141], v[36:37], v[28:29]
	v_mov_b32_e32 v36, v18
	v_pk_mul_f32 v[28:29], v[38:39], v[34:35]
	v_mov_b32_e32 v37, v22
	v_pk_mul_f32 v[24:25], v[28:29], v[24:25]
	s_nop 0
	v_cvt_pk_bf16_f32 v16, v24, v25
	v_lshlrev_b32_e32 v24, 16, v157
	v_and_b32_e32 v25, 0xffff0000, v157
	v_mul_f32_e32 v20, 0xbfb8aa3b, v24
	v_exp_f32_e32 v20, v20
	v_mul_f32_e32 v28, 0xbfb8aa3b, v25
	v_exp_f32_e32 v29, v28
	v_lshlrev_b32_e32 v28, 16, v155
	v_add_f32_e32 v20, 1.0, v20
	v_rcp_f32_e32 v34, v20
	v_add_f32_e32 v20, 1.0, v29
	v_rcp_f32_e32 v35, v20
	v_and_b32_e32 v29, 0xffff0000, v155
	v_mov_b32_e32 v20, v17
	v_pk_fma_f32 v[20:21], v[140:141], v[28:29], v[20:21]
	v_pk_mul_f32 v[24:25], v[34:35], v[24:25]
	v_mov_b32_e32 v34, v26
	v_pk_mul_f32 v[20:21], v[24:25], v[20:21]
	v_lshlrev_b32_e32 v24, 16, v148
	v_cvt_pk_bf16_f32 v17, v20, v21
	v_lshlrev_b32_e32 v20, 16, v150
	v_and_b32_e32 v21, 0xffff0000, v150
	v_mul_f32_e32 v25, 0xbfb8aa3b, v20
	v_exp_f32_e32 v28, v25
	v_mul_f32_e32 v25, 0xbfb8aa3b, v21
	v_exp_f32_e32 v29, v25
	v_and_b32_e32 v25, 0xffff0000, v148
	v_add_f32_e32 v28, 1.0, v28
	v_rcp_f32_e32 v28, v28
	v_add_f32_e32 v29, 1.0, v29
	v_rcp_f32_e32 v29, v29
	v_mov_b32_e32 v35, v30
	v_pk_fma_f32 v[24:25], v[140:141], v[24:25], v[34:35]
	v_pk_mul_f32 v[20:21], v[28:29], v[20:21]
	s_nop 0
	v_pk_mul_f32 v[20:21], v[20:21], v[24:25]
	v_lshlrev_b32_e32 v24, 16, v151
	v_cvt_pk_bf16_f32 v20, v20, v21
	v_and_b32_e32 v25, 0xffff0000, v151
	v_mul_f32_e32 v21, 0xbfb8aa3b, v24
	v_exp_f32_e32 v21, v21
	v_mul_f32_e32 v26, 0xbfb8aa3b, v25
	v_exp_f32_e32 v26, v26
	v_lshlrev_b32_e32 v28, 16, v149
	v_add_f32_e32 v21, 1.0, v21
	v_rcp_f32_e32 v34, v21
	v_add_f32_e32 v21, 1.0, v26
	v_rcp_f32_e32 v35, v21
	v_and_b32_e32 v29, 0xffff0000, v149
	v_pk_fma_f32 v[28:29], v[140:141], v[28:29], v[36:37]
	v_pk_mul_f32 v[24:25], v[34:35], v[24:25]
	s_nop 0
	v_pk_mul_f32 v[24:25], v[24:25], v[28:29]
	s_nop 0
	v_cvt_pk_bf16_f32 v21, v24, v25
	s_cmpk_lg_i32 s19, 0x80
	s_cbranch_scc0 .LBB0_345
	v_cmp_gt_i32_e32 vcc, s19, v178
	s_and_saveexec_b64 s[74:75], vcc
	s_cbranch_execz .LBB0_351
	s_lshl_b32 s21, s20, 11
	s_mov_b32 s90, s86
	s_mov_b32 s91, s87
	buffer_store_dwordx2 v[32:33], v215, s[88:91], s21 offen
	s_or_b64 exec, exec, s[74:75]
	v_cmp_gt_i32_e32 vcc, s19, v182
	s_and_saveexec_b64 s[74:75], vcc
	s_cbranch_execnz .LBB0_352

; #define LAS __attribute__((address_space(3)))
; __global__ void __launch_bounds__(NTHR, 2) hymba_fwd(Params P) {
;     extern __shared__ __attribute__((aligned(16))) unsigned char lds_raw[];
;     LAS unsigned char* lds = (LAS unsigned char*)lds_raw;
	.amdhsa_kernel _Z9hymba_fwd6Params
		.amdhsa_group_segment_fixed_size 0
		.amdhsa_private_segment_fixed_size 0
		.amdhsa_kernarg_size 424
		.amdhsa_user_sgpr_count 2
		.amdhsa_user_sgpr_dispatch_ptr 0
		.amdhsa_user_sgpr_queue_ptr 0
		.amdhsa_user_sgpr_kernarg_segment_ptr 1
		.amdhsa_user_sgpr_dispatch_id 0
		.amdhsa_user_sgpr_kernarg_preload_length 0
		.amdhsa_user_sgpr_kernarg_preload_offset 0
		.amdhsa_user_sgpr_private_segment_size 0
		.amdhsa_uses_dynamic_stack 0
		.amdhsa_enable_private_segment 0
		.amdhsa_system_sgpr_workgroup_id_x 1
		.amdhsa_system_sgpr_workgroup_id_y 0
		.amdhsa_system_sgpr_workgroup_id_z 0
		.amdhsa_system_sgpr_workgroup_info 0
		.amdhsa_system_vgpr_workitem_id 2
		.amdhsa_next_free_vgpr 240
		.amdhsa_next_free_sgpr 102
		.amdhsa_accum_offset 240
		.amdhsa_reserve_vcc 1
		.amdhsa_float_round_mode_32 0
		.amdhsa_float_round_mode_16_64 0
		.amdhsa_float_denorm_mode_32 3
		.amdhsa_float_denorm_mode_16_64 3
		.amdhsa_dx10_clamp 1
		.amdhsa_ieee_mode 1
		.amdhsa_fp16_overflow 0
		.amdhsa_tg_split 0
		.amdhsa_exception_fp_ieee_invalid_op 0
		.amdhsa_exception_fp_denorm_src 0
		.amdhsa_exception_fp_ieee_div_zero 0
		.amdhsa_exception_fp_ieee_overflow 0
		.amdhsa_exception_fp_ieee_underflow 0
		.amdhsa_exception_fp_ieee_inexact 0
		.amdhsa_exception_int_div_zero 0
	.end_amdhsa_kernel

; #define LAS __attribute__((address_space(3)))
; __global__ void __launch_bounds__(NTHR, 2) hymba_fwd(Params P) {
;     extern __shared__ __attribute__((aligned(16))) unsigned char lds_raw[];
;     LAS unsigned char* lds = (LAS unsigned char*)lds_raw;
amdhsa.kernels:
  - .agpr_count:     0
    .args:
      - .offset:         0
        .size:           168
        .value_kind:     by_value
      - .offset:         168
        .size:           4
        .value_kind:     hidden_block_count_x
      - .offset:         172
        .size:           4
        .value_kind:     hidden_block_count_y
      - .offset:         176
        .size:           4
        .value_kind:     hidden_block_count_z
      - .offset:         180
        .size:           2
        .value_kind:     hidden_group_size_x
      - .offset:         182
        .size:           2
        .value_kind:     hidden_group_size_y
      - .offset:         184
        .size:           2
        .value_kind:     hidden_group_size_z
      - .offset:         186
        .size:           2
        .value_kind:     hidden_remainder_x
      - .offset:         188
        .size:           2
        .value_kind:     hidden_remainder_y
      - .offset:         190
        .size:           2
        .value_kind:     hidden_remainder_z
      - .offset:         208
        .size:           8
        .value_kind:     hidden_global_offset_x
      - .offset:         216
        .size:           8
        .value_kind:     hidden_global_offset_y
      - .offset:         224
        .size:           8
        .value_kind:     hidden_global_offset_z
      - .offset:         232
        .size:           2
        .value_kind:     hidden_grid_dims
      - .offset:         256
        .size:           8
        .value_kind:     hidden_multigrid_sync_arg
      - .offset:         288
        .size:           4
        .value_kind:     hidden_dynamic_lds_size
    .group_segment_fixed_size: 0
    .kernarg_segment_align: 8
    .kernarg_segment_size: 424
    .language:       OpenCL C
    .language_version:
      - 2
      - 0
    .max_flat_workgroup_size: 512
    .name:           _Z9hymba_fwd6Params
    .private_segment_fixed_size: 0
    .sgpr_count:     108
    .sgpr_spill_count: 102
    .symbol:         _Z9hymba_fwd6Params.kd
    .uniform_work_group_size: 1
    .uses_dynamic_stack: false
    .vgpr_count:     240
    .vgpr_spill_count: 0
    .wavefront_size: 64
